# GEMM mainloops without the per-cluster s_setprio flips (age-based issue arbitration between the two waves of a SIMD)
# speedup vs baseline: 1.0072x; 1.0072x over previous
.LBB0_151:
	s_add_i32 s43, s8, 2
	s_add_u32 s9, s6, 0x4000
	s_addc_u32 s10, s7, 0
	s_cmp_eq_u32 s30, s8
	s_cselect_b32 s12, s0, s9
	s_cselect_b32 s13, s1, s10
	s_cselect_b32 s8, s2, s41
	s_cselect_b32 s9, s3, s42
	s_add_u32 s10, s12, 0x8000
	s_addc_u32 s11, s13, 0
	s_add_i32 s44, 0, 0x10000
	v_add_u32_e32 v154, s44, v174
	ds_read_b128 v[142:145], v154
	ds_read_b128 v[146:149], v154 offset:1024
	ds_read_b128 v[150:153], v154 offset:2048
	ds_read_b128 v[154:157], v154 offset:3072
	v_lshl_add_u64 v[168:169], s[6:7], 0, v[138:139]
	s_add_i32 m0, s19, 0xc000
	ds_read_b128 v[158:161], v175
	ds_read_b128 v[176:179], v175 offset:1024
	ds_read_b128 v[180:183], v175 offset:2048
	ds_read_b128 v[184:187], v175 offset:3072
	ds_read_b128 v[188:191], v175 offset:4096
	ds_read_b128 v[192:195], v175 offset:5120
	ds_read_b128 v[196:199], v175 offset:6144
	ds_read_b128 v[200:203], v175 offset:7168
	global_load_lds_dwordx4 v[168:169], off
	v_lshl_add_u64 v[168:169], s[6:7], 0, v[140:141]
	s_add_i32 m0, s19, 0xe000
	s_nop 0
	global_load_lds_dwordx4 v[168:169], off
	s_waitcnt lgkmcnt(8)
	s_barrier
	s_waitcnt lgkmcnt(0)
	s_waitcnt lgkmcnt(0)
	v_mfma_f32_16x16x32_bf16 v[126:129], v[142:145], v[158:161], v[126:129]
	v_mfma_f32_16x16x32_bf16 v[122:125], v[150:153], v[158:161], v[122:125]
	v_mfma_f32_16x16x32_bf16 v[110:113], v[142:145], v[180:183], v[110:113]
	v_mfma_f32_16x16x32_bf16 v[106:109], v[150:153], v[180:183], v[106:109]
	v_mfma_f32_16x16x32_bf16 v[94:97], v[142:145], v[188:191], v[94:97]
	v_mfma_f32_16x16x32_bf16 v[90:93], v[150:153], v[188:191], v[90:93]
	v_mfma_f32_16x16x32_bf16 v[78:81], v[142:145], v[196:199], v[78:81]
	v_mfma_f32_16x16x32_bf16 v[74:77], v[150:153], v[196:199], v[74:77]
	v_mfma_f32_16x16x32_bf16 v[126:129], v[146:149], v[176:179], v[126:129]
	v_mfma_f32_16x16x32_bf16 v[122:125], v[154:157], v[176:179], v[122:125]
	v_mfma_f32_16x16x32_bf16 v[110:113], v[146:149], v[184:187], v[110:113]
	v_mfma_f32_16x16x32_bf16 v[106:109], v[154:157], v[184:187], v[106:109]
	v_mfma_f32_16x16x32_bf16 v[94:97], v[146:149], v[192:195], v[94:97]
	v_mfma_f32_16x16x32_bf16 v[90:93], v[154:157], v[192:195], v[90:93]
	v_mfma_f32_16x16x32_bf16 v[78:81], v[146:149], v[200:203], v[78:81]
	v_mfma_f32_16x16x32_bf16 v[74:77], v[154:157], v[200:203], v[74:77]
	s_barrier
	s_add_i32 s46, 0, 0x14000
	v_add_u32_e32 v168, s46, v174
	s_add_i32 s44, s44, s18
	ds_read_b128 v[204:207], v168
	ds_read_b128 v[208:211], v168 offset:1024
	ds_read_b128 v[212:215], v168 offset:2048
	ds_read_b128 v[216:219], v168 offset:3072
	v_lshl_add_u64 v[168:169], s[8:9], 0, v[132:133]
	s_mov_b32 m0, s44
	v_lshl_add_u64 v[172:173], s[8:9], 0, v[136:137]
	global_load_lds_dwordx4 v[168:169], off
	s_add_i32 m0, s44, 0x2000
	s_nop 0
	global_load_lds_dwordx4 v[172:173], off
	s_barrier
	s_waitcnt lgkmcnt(0)
	s_waitcnt lgkmcnt(0)
	v_mfma_f32_16x16x32_bf16 v[118:121], v[204:207], v[158:161], v[118:121]
	v_mfma_f32_16x16x32_bf16 v[114:117], v[212:215], v[158:161], v[114:117]
	v_mfma_f32_16x16x32_bf16 v[102:105], v[204:207], v[180:183], v[102:105]
	v_mfma_f32_16x16x32_bf16 v[98:101], v[212:215], v[180:183], v[98:101]
	v_mfma_f32_16x16x32_bf16 v[86:89], v[204:207], v[188:191], v[86:89]
	v_mfma_f32_16x16x32_bf16 v[82:85], v[212:215], v[188:191], v[82:85]
	v_mfma_f32_16x16x32_bf16 v[70:73], v[204:207], v[196:199], v[70:73]
	v_mfma_f32_16x16x32_bf16 v[66:69], v[212:215], v[196:199], v[66:69]
	v_mfma_f32_16x16x32_bf16 v[118:121], v[208:211], v[176:179], v[118:121]
	v_mfma_f32_16x16x32_bf16 v[114:117], v[216:219], v[176:179], v[114:117]
	v_mfma_f32_16x16x32_bf16 v[102:105], v[208:211], v[184:187], v[102:105]
	v_mfma_f32_16x16x32_bf16 v[98:101], v[216:219], v[184:187], v[98:101]
	v_mfma_f32_16x16x32_bf16 v[86:89], v[208:211], v[192:195], v[86:89]
	v_mfma_f32_16x16x32_bf16 v[82:85], v[216:219], v[192:195], v[82:85]
	v_mfma_f32_16x16x32_bf16 v[70:73], v[208:211], v[200:203], v[70:73]
	v_mfma_f32_16x16x32_bf16 v[66:69], v[216:219], v[200:203], v[66:69]
	s_mov_b32 m0, s19
	v_lshl_add_u64 v[220:221], s[12:13], 0, v[130:131]
	s_barrier
	ds_read_b128 v[158:161], v175 offset:16384
	ds_read_b128 v[176:179], v175 offset:17408
	ds_read_b128 v[180:183], v175 offset:18432
	ds_read_b128 v[184:187], v175 offset:19456
	ds_read_b128 v[188:191], v175 offset:20480
	ds_read_b128 v[192:195], v175 offset:21504
	ds_read_b128 v[196:199], v175 offset:22528
	ds_read_b128 v[200:203], v175 offset:23552
	global_load_lds_dwordx4 v[220:221], off
	v_lshl_add_u64 v[220:221], s[12:13], 0, v[134:135]
	s_mov_b32 m0, s20
	s_nop 0
	global_load_lds_dwordx4 v[220:221], off
	s_barrier
	s_waitcnt lgkmcnt(0)
	s_waitcnt lgkmcnt(0)
	v_mfma_f32_16x16x32_bf16 v[62:65], v[142:145], v[158:161], v[62:65]
	v_mfma_f32_16x16x32_bf16 v[58:61], v[150:153], v[158:161], v[58:61]
	v_mfma_f32_16x16x32_bf16 v[46:49], v[142:145], v[180:183], v[46:49]
	v_mfma_f32_16x16x32_bf16 v[42:45], v[150:153], v[180:183], v[42:45]
	v_mfma_f32_16x16x32_bf16 v[30:33], v[142:145], v[188:191], v[30:33]
	v_mfma_f32_16x16x32_bf16 v[26:29], v[150:153], v[188:191], v[26:29]
	v_mfma_f32_16x16x32_bf16 v[14:17], v[142:145], v[196:199], v[14:17]
	v_mfma_f32_16x16x32_bf16 v[10:13], v[150:153], v[196:199], v[10:13]
	v_mfma_f32_16x16x32_bf16 v[62:65], v[146:149], v[176:179], v[62:65]
	v_mfma_f32_16x16x32_bf16 v[58:61], v[154:157], v[176:179], v[58:61]
	v_mfma_f32_16x16x32_bf16 v[46:49], v[146:149], v[184:187], v[46:49]
	v_mfma_f32_16x16x32_bf16 v[42:45], v[154:157], v[184:187], v[42:45]
	v_mfma_f32_16x16x32_bf16 v[30:33], v[146:149], v[192:195], v[30:33]
	v_mfma_f32_16x16x32_bf16 v[26:29], v[154:157], v[192:195], v[26:29]
	v_mfma_f32_16x16x32_bf16 v[14:17], v[146:149], v[200:203], v[14:17]
	v_mfma_f32_16x16x32_bf16 v[10:13], v[154:157], v[200:203], v[10:13]
	s_barrier
	s_add_u32 s44, s8, 0xb0000
	s_addc_u32 s45, s9, 0
	s_add_i32 s46, s46, s18
	v_lshl_add_u64 v[142:143], s[44:45], 0, v[132:133]
	s_mov_b32 m0, s46
	s_nop 0
	global_load_lds_dwordx4 v[142:143], off
	v_lshl_add_u64 v[142:143], s[44:45], 0, v[136:137]
	s_add_i32 m0, s46, 0x2000
	s_nop 0
	global_load_lds_dwordx4 v[142:143], off
	s_waitcnt vmcnt(6)
	s_barrier
	v_mfma_f32_16x16x32_bf16 v[54:57], v[204:207], v[158:161], v[54:57]
	v_mfma_f32_16x16x32_bf16 v[50:53], v[212:215], v[158:161], v[50:53]
	v_mfma_f32_16x16x32_bf16 v[38:41], v[204:207], v[180:183], v[38:41]
	v_mfma_f32_16x16x32_bf16 v[34:37], v[212:215], v[180:183], v[34:37]
	v_mfma_f32_16x16x32_bf16 v[22:25], v[204:207], v[188:191], v[22:25]
	v_mfma_f32_16x16x32_bf16 v[18:21], v[212:215], v[188:191], v[18:21]
	v_mfma_f32_16x16x32_bf16 v[6:9], v[204:207], v[196:199], v[6:9]
	v_mfma_f32_16x16x32_bf16 v[2:5], v[212:215], v[196:199], v[2:5]
	v_mfma_f32_16x16x32_bf16 v[54:57], v[208:211], v[176:179], v[54:57]
	v_mfma_f32_16x16x32_bf16 v[50:53], v[216:219], v[176:179], v[50:53]
	v_mfma_f32_16x16x32_bf16 v[38:41], v[208:211], v[184:187], v[38:41]
	v_mfma_f32_16x16x32_bf16 v[34:37], v[216:219], v[184:187], v[34:37]
	v_mfma_f32_16x16x32_bf16 v[22:25], v[208:211], v[192:195], v[22:25]
	v_mfma_f32_16x16x32_bf16 v[18:21], v[216:219], v[192:195], v[18:21]
	v_mfma_f32_16x16x32_bf16 v[6:9], v[208:211], v[200:203], v[6:9]
	v_mfma_f32_16x16x32_bf16 v[2:5], v[216:219], v[200:203], v[2:5]
	s_add_i32 s44, 0, 0x18000
	v_add_u32_e32 v154, s44, v174
	s_barrier
	ds_read_b128 v[142:145], v154
	ds_read_b128 v[146:149], v154 offset:1024
	ds_read_b128 v[150:153], v154 offset:2048
	ds_read_b128 v[154:157], v154 offset:3072
	s_add_u32 s12, s12, 0x4000
	s_addc_u32 s13, s13, 0
	s_mov_b32 m0, s21
	v_lshl_add_u64 v[204:205], s[12:13], 0, v[130:131]
	ds_read_b128 v[158:161], v175 offset:32768
	ds_read_b128 v[176:179], v175 offset:33792
	ds_read_b128 v[180:183], v175 offset:34816
	ds_read_b128 v[184:187], v175 offset:35840
	ds_read_b128 v[188:191], v175 offset:36864
	ds_read_b128 v[192:195], v175 offset:37888
	ds_read_b128 v[196:199], v175 offset:38912
	ds_read_b128 v[200:203], v175 offset:39936
	global_load_lds_dwordx4 v[204:205], off
	v_lshl_add_u64 v[204:205], s[12:13], 0, v[134:135]
	s_mov_b32 m0, s22
	s_nop 0
	global_load_lds_dwordx4 v[204:205], off
	s_waitcnt lgkmcnt(8)
	s_barrier
	s_waitcnt lgkmcnt(0)
	s_waitcnt lgkmcnt(0)
	v_mfma_f32_16x16x32_bf16 v[126:129], v[142:145], v[158:161], v[126:129]
	v_mfma_f32_16x16x32_bf16 v[122:125], v[150:153], v[158:161], v[122:125]
	v_mfma_f32_16x16x32_bf16 v[110:113], v[142:145], v[180:183], v[110:113]
	v_mfma_f32_16x16x32_bf16 v[106:109], v[150:153], v[180:183], v[106:109]
	v_mfma_f32_16x16x32_bf16 v[94:97], v[142:145], v[188:191], v[94:97]
	v_mfma_f32_16x16x32_bf16 v[90:93], v[150:153], v[188:191], v[90:93]
	v_mfma_f32_16x16x32_bf16 v[78:81], v[142:145], v[196:199], v[78:81]
	v_mfma_f32_16x16x32_bf16 v[74:77], v[150:153], v[196:199], v[74:77]
	v_mfma_f32_16x16x32_bf16 v[126:129], v[146:149], v[176:179], v[126:129]
	v_mfma_f32_16x16x32_bf16 v[122:125], v[154:157], v[176:179], v[122:125]
	v_mfma_f32_16x16x32_bf16 v[110:113], v[146:149], v[184:187], v[110:113]
	v_mfma_f32_16x16x32_bf16 v[106:109], v[154:157], v[184:187], v[106:109]
	v_mfma_f32_16x16x32_bf16 v[94:97], v[146:149], v[192:195], v[94:97]
	v_mfma_f32_16x16x32_bf16 v[90:93], v[154:157], v[192:195], v[90:93]
	v_mfma_f32_16x16x32_bf16 v[78:81], v[146:149], v[200:203], v[78:81]
	v_mfma_f32_16x16x32_bf16 v[74:77], v[154:157], v[200:203], v[74:77]
	s_barrier
	s_add_i32 s12, 0, 0x1c000
	s_add_i32 s13, s44, s18
	v_add_u32_e32 v216, s12, v174
	v_lshl_add_u64 v[168:169], v[168:169], 0, s[84:85]
	s_mov_b32 m0, s13
	ds_read_b128 v[204:207], v216
	ds_read_b128 v[208:211], v216 offset:1024
	ds_read_b128 v[212:215], v216 offset:2048
	ds_read_b128 v[216:219], v216 offset:3072
	global_load_lds_dwordx4 v[168:169], off
	v_lshl_add_u64 v[168:169], v[172:173], 0, s[84:85]
	s_add_i32 m0, s13, 0x2000
	s_nop 0
	global_load_lds_dwordx4 v[168:169], off
	s_barrier
	s_waitcnt lgkmcnt(0)
	s_waitcnt lgkmcnt(0)
	v_mfma_f32_16x16x32_bf16 v[118:121], v[204:207], v[158:161], v[118:121]
	v_mfma_f32_16x16x32_bf16 v[114:117], v[212:215], v[158:161], v[114:117]
	v_mfma_f32_16x16x32_bf16 v[102:105], v[204:207], v[180:183], v[102:105]
	v_mfma_f32_16x16x32_bf16 v[98:101], v[212:215], v[180:183], v[98:101]
	v_mfma_f32_16x16x32_bf16 v[86:89], v[204:207], v[188:191], v[86:89]
	v_mfma_f32_16x16x32_bf16 v[82:85], v[212:215], v[188:191], v[82:85]
	v_mfma_f32_16x16x32_bf16 v[70:73], v[204:207], v[196:199], v[70:73]
	v_mfma_f32_16x16x32_bf16 v[66:69], v[212:215], v[196:199], v[66:69]
	v_mfma_f32_16x16x32_bf16 v[118:121], v[208:211], v[176:179], v[118:121]
	v_mfma_f32_16x16x32_bf16 v[114:117], v[216:219], v[176:179], v[114:117]
	v_mfma_f32_16x16x32_bf16 v[102:105], v[208:211], v[184:187], v[102:105]
	v_mfma_f32_16x16x32_bf16 v[98:101], v[216:219], v[184:187], v[98:101]
	v_mfma_f32_16x16x32_bf16 v[86:89], v[208:211], v[192:195], v[86:89]
	v_mfma_f32_16x16x32_bf16 v[82:85], v[216:219], v[192:195], v[82:85]
	v_mfma_f32_16x16x32_bf16 v[70:73], v[208:211], v[200:203], v[70:73]
	v_mfma_f32_16x16x32_bf16 v[66:69], v[216:219], v[200:203], v[66:69]
	s_mov_b32 m0, s28
	v_lshl_add_u64 v[168:169], s[10:11], 0, v[130:131]
	s_barrier
	ds_read_b128 v[158:161], v175 offset:49152
	ds_read_b128 v[176:179], v175 offset:50176
	ds_read_b128 v[180:183], v175 offset:51200
	ds_read_b128 v[184:187], v175 offset:52224
	ds_read_b128 v[188:191], v175 offset:53248
	ds_read_b128 v[192:195], v175 offset:54272
	ds_read_b128 v[196:199], v175 offset:55296
	ds_read_b128 v[200:203], v175 offset:56320
	global_load_lds_dwordx4 v[168:169], off
	v_lshl_add_u64 v[168:169], s[10:11], 0, v[134:135]
	s_mov_b32 m0, s29
	s_nop 0
	global_load_lds_dwordx4 v[168:169], off
	s_barrier
	s_waitcnt lgkmcnt(0)
	s_waitcnt lgkmcnt(0)
	v_mfma_f32_16x16x32_bf16 v[62:65], v[142:145], v[158:161], v[62:65]
	v_mfma_f32_16x16x32_bf16 v[58:61], v[150:153], v[158:161], v[58:61]
	v_mfma_f32_16x16x32_bf16 v[46:49], v[142:145], v[180:183], v[46:49]
	v_mfma_f32_16x16x32_bf16 v[42:45], v[150:153], v[180:183], v[42:45]
	v_mfma_f32_16x16x32_bf16 v[30:33], v[142:145], v[188:191], v[30:33]
	v_mfma_f32_16x16x32_bf16 v[26:29], v[150:153], v[188:191], v[26:29]
	v_mfma_f32_16x16x32_bf16 v[14:17], v[142:145], v[196:199], v[14:17]
	v_mfma_f32_16x16x32_bf16 v[10:13], v[150:153], v[196:199], v[10:13]
	v_mfma_f32_16x16x32_bf16 v[62:65], v[146:149], v[176:179], v[62:65]
	v_mfma_f32_16x16x32_bf16 v[58:61], v[154:157], v[176:179], v[58:61]
	v_mfma_f32_16x16x32_bf16 v[46:49], v[146:149], v[184:187], v[46:49]
	v_mfma_f32_16x16x32_bf16 v[42:45], v[154:157], v[184:187], v[42:45]
	v_mfma_f32_16x16x32_bf16 v[30:33], v[146:149], v[192:195], v[30:33]
	v_mfma_f32_16x16x32_bf16 v[26:29], v[154:157], v[192:195], v[26:29]
	v_mfma_f32_16x16x32_bf16 v[14:17], v[146:149], v[200:203], v[14:17]
	v_mfma_f32_16x16x32_bf16 v[10:13], v[154:157], v[200:203], v[10:13]
	s_barrier
	s_add_u32 s8, s8, 0xb0080
	s_addc_u32 s9, s9, 0
	s_add_i32 s10, s12, s18
	v_lshl_add_u64 v[142:143], s[8:9], 0, v[132:133]
	s_mov_b32 m0, s10
	s_nop 0
	global_load_lds_dwordx4 v[142:143], off
	v_lshl_add_u64 v[142:143], s[8:9], 0, v[136:137]
	s_add_i32 m0, s10, 0x2000
	s_nop 0
	global_load_lds_dwordx4 v[142:143], off
	s_waitcnt vmcnt(6)
	s_barrier
	v_mfma_f32_16x16x32_bf16 v[54:57], v[204:207], v[158:161], v[54:57]
	v_mfma_f32_16x16x32_bf16 v[50:53], v[212:215], v[158:161], v[50:53]
	v_mfma_f32_16x16x32_bf16 v[38:41], v[204:207], v[180:183], v[38:41]
	v_mfma_f32_16x16x32_bf16 v[34:37], v[212:215], v[180:183], v[34:37]
	v_mfma_f32_16x16x32_bf16 v[22:25], v[204:207], v[188:191], v[22:25]
	v_mfma_f32_16x16x32_bf16 v[18:21], v[212:215], v[188:191], v[18:21]
	v_mfma_f32_16x16x32_bf16 v[6:9], v[204:207], v[196:199], v[6:9]
	v_mfma_f32_16x16x32_bf16 v[2:5], v[212:215], v[196:199], v[2:5]
	v_mfma_f32_16x16x32_bf16 v[54:57], v[208:211], v[176:179], v[54:57]
	v_mfma_f32_16x16x32_bf16 v[50:53], v[216:219], v[176:179], v[50:53]
	v_mfma_f32_16x16x32_bf16 v[38:41], v[208:211], v[184:187], v[38:41]
	v_mfma_f32_16x16x32_bf16 v[34:37], v[216:219], v[184:187], v[34:37]
	v_mfma_f32_16x16x32_bf16 v[22:25], v[208:211], v[192:195], v[22:25]
	v_mfma_f32_16x16x32_bf16 v[18:21], v[216:219], v[192:195], v[18:21]
	v_mfma_f32_16x16x32_bf16 v[6:9], v[208:211], v[200:203], v[6:9]
	v_mfma_f32_16x16x32_bf16 v[2:5], v[216:219], v[200:203], v[2:5]
	s_add_u32 s41, s41, 0x100
	s_addc_u32 s42, s42, 0
	s_add_u32 s6, s6, 0x10000
	s_addc_u32 s7, s7, 0
	s_cmp_ge_i32 s43, s25
	s_mov_b32 s8, s43
	s_barrier
	s_cbranch_scc0 .LBB0_151
	s_branch .LBB0_138

.LBB0_166:
	s_add_i32 s47, s16, 2
	s_add_u32 s17, s14, 0xfffc0080
	s_addc_u32 s18, s15, -1
	s_add_i32 s48, 0, 0x10000
	v_add_u32_e32 v102, s48, v171
	ds_read_b128 v[82:85], v102
	ds_read_b128 v[86:89], v102 offset:1024
	ds_read_b128 v[98:101], v102 offset:2048
	ds_read_b128 v[102:105], v102 offset:3072
	s_cmp_eq_u32 s39, s16
	s_cselect_b32 s16, s44, s45
	s_cselect_b32 s19, s5, s18
	s_cselect_b32 s18, s7, s17
	s_cselect_b32 s17, s43, s46
	v_lshl_add_u64 v[160:161], s[14:15], 0, v[154:155]
	s_add_i32 m0, s13, 0xc000
	ds_read_b128 v[174:177], v173
	ds_read_b128 v[178:181], v173 offset:1024
	ds_read_b128 v[182:185], v173 offset:2048
	ds_read_b128 v[186:189], v173 offset:3072
	ds_read_b128 v[190:193], v173 offset:4096
	ds_read_b128 v[194:197], v173 offset:5120
	ds_read_b128 v[198:201], v173 offset:6144
	ds_read_b128 v[202:205], v173 offset:7168
	global_load_lds_dwordx4 v[160:161], off
	v_lshl_add_u64 v[160:161], s[14:15], 0, v[156:157]
	s_add_i32 m0, s13, 0xe000
	s_nop 0
	global_load_lds_dwordx4 v[160:161], off
	s_waitcnt lgkmcnt(8)
	s_barrier
	s_waitcnt lgkmcnt(0)
	s_waitcnt lgkmcnt(0)
	v_mfma_f32_16x16x32_bf16 v[138:141], v[82:85], v[174:177], v[138:141]
	v_mfma_f32_16x16x32_bf16 v[134:137], v[98:101], v[174:177], v[134:137]
	v_mfma_f32_16x16x32_bf16 v[126:129], v[82:85], v[182:185], v[126:129]
	v_mfma_f32_16x16x32_bf16 v[118:121], v[98:101], v[182:185], v[118:121]
	v_mfma_f32_16x16x32_bf16 v[110:113], v[82:85], v[190:193], v[110:113]
	v_mfma_f32_16x16x32_bf16 v[94:97], v[98:101], v[190:193], v[94:97]
	v_mfma_f32_16x16x32_bf16 v[78:81], v[82:85], v[198:201], v[78:81]
	v_mfma_f32_16x16x32_bf16 v[70:73], v[98:101], v[198:201], v[70:73]
	v_mfma_f32_16x16x32_bf16 v[138:141], v[86:89], v[178:181], v[138:141]
	v_mfma_f32_16x16x32_bf16 v[134:137], v[102:105], v[178:181], v[134:137]
	v_mfma_f32_16x16x32_bf16 v[126:129], v[86:89], v[186:189], v[126:129]
	v_mfma_f32_16x16x32_bf16 v[118:121], v[102:105], v[186:189], v[118:121]
	v_mfma_f32_16x16x32_bf16 v[110:113], v[86:89], v[194:197], v[110:113]
	v_mfma_f32_16x16x32_bf16 v[94:97], v[102:105], v[194:197], v[94:97]
	v_mfma_f32_16x16x32_bf16 v[78:81], v[86:89], v[202:205], v[78:81]
	v_mfma_f32_16x16x32_bf16 v[70:73], v[102:105], v[202:205], v[70:73]
	s_barrier
	s_add_i32 s50, 0, 0x14000
	s_add_i32 s48, s48, s23
	v_add_u32_e32 v158, s50, v171
	v_lshl_add_u64 v[160:161], s[16:17], 0, v[150:151]
	s_mov_b32 m0, s48
	ds_read_b128 v[206:209], v158
	ds_read_b128 v[210:213], v158 offset:1024
	ds_read_b128 v[214:217], v158 offset:2048
	ds_read_b128 v[218:221], v158 offset:3072
	global_load_lds_dwordx4 v[160:161], off
	v_lshl_add_u64 v[168:169], s[16:17], 0, v[146:147]
	s_add_i32 m0, s48, 0x2000
	s_nop 0
	global_load_lds_dwordx4 v[168:169], off
	s_barrier
	s_waitcnt lgkmcnt(0)
	s_waitcnt lgkmcnt(0)
	v_mfma_f32_16x16x32_bf16 v[142:145], v[206:209], v[174:177], v[142:145]
	v_mfma_f32_16x16x32_bf16 v[130:133], v[214:217], v[174:177], v[130:133]
	v_mfma_f32_16x16x32_bf16 v[122:125], v[206:209], v[182:185], v[122:125]
	v_mfma_f32_16x16x32_bf16 v[114:117], v[214:217], v[182:185], v[114:117]
	v_mfma_f32_16x16x32_bf16 v[106:109], v[206:209], v[190:193], v[106:109]
	v_mfma_f32_16x16x32_bf16 v[90:93], v[214:217], v[190:193], v[90:93]
	v_mfma_f32_16x16x32_bf16 v[74:77], v[206:209], v[198:201], v[74:77]
	v_mfma_f32_16x16x32_bf16 v[66:69], v[214:217], v[198:201], v[66:69]
	v_mfma_f32_16x16x32_bf16 v[142:145], v[210:213], v[178:181], v[142:145]
	v_mfma_f32_16x16x32_bf16 v[130:133], v[218:221], v[178:181], v[130:133]
	v_mfma_f32_16x16x32_bf16 v[122:125], v[210:213], v[186:189], v[122:125]
	v_mfma_f32_16x16x32_bf16 v[114:117], v[218:221], v[186:189], v[114:117]
	v_mfma_f32_16x16x32_bf16 v[106:109], v[210:213], v[194:197], v[106:109]
	v_mfma_f32_16x16x32_bf16 v[90:93], v[218:221], v[194:197], v[90:93]
	v_mfma_f32_16x16x32_bf16 v[74:77], v[210:213], v[202:205], v[74:77]
	v_mfma_f32_16x16x32_bf16 v[66:69], v[218:221], v[202:205], v[66:69]
	s_mov_b32 m0, s13
	v_lshl_add_u64 v[236:237], s[18:19], 0, v[152:153]
	s_barrier
	ds_read_b128 v[174:177], v173 offset:16384
	ds_read_b128 v[178:181], v173 offset:17408
	ds_read_b128 v[182:185], v173 offset:18432
	ds_read_b128 v[186:189], v173 offset:19456
	ds_read_b128 v[190:193], v173 offset:20480
	ds_read_b128 v[194:197], v173 offset:21504
	ds_read_b128 v[198:201], v173 offset:22528
	ds_read_b128 v[202:205], v173 offset:23552
	global_load_lds_dwordx4 v[236:237], off
	v_lshl_add_u64 v[238:239], s[18:19], 0, v[148:149]
	s_mov_b32 m0, s25
	s_nop 0
	global_load_lds_dwordx4 v[238:239], off
	s_barrier
	s_waitcnt lgkmcnt(0)
	s_waitcnt lgkmcnt(0)
	v_mfma_f32_16x16x32_bf16 v[62:65], v[82:85], v[174:177], v[62:65]
	v_mfma_f32_16x16x32_bf16 v[54:57], v[98:101], v[174:177], v[54:57]
	v_mfma_f32_16x16x32_bf16 v[46:49], v[82:85], v[182:185], v[46:49]
	v_mfma_f32_16x16x32_bf16 v[38:41], v[98:101], v[182:185], v[38:41]
	v_mfma_f32_16x16x32_bf16 v[30:33], v[82:85], v[190:193], v[30:33]
	v_mfma_f32_16x16x32_bf16 v[22:25], v[98:101], v[190:193], v[22:25]
	v_mfma_f32_16x16x32_bf16 v[14:17], v[82:85], v[198:201], v[14:17]
	v_mfma_f32_16x16x32_bf16 v[6:9], v[98:101], v[198:201], v[6:9]
	v_mfma_f32_16x16x32_bf16 v[62:65], v[86:89], v[178:181], v[62:65]
	v_mfma_f32_16x16x32_bf16 v[54:57], v[102:105], v[178:181], v[54:57]
	v_mfma_f32_16x16x32_bf16 v[46:49], v[86:89], v[186:189], v[46:49]
	v_mfma_f32_16x16x32_bf16 v[38:41], v[102:105], v[186:189], v[38:41]
	v_mfma_f32_16x16x32_bf16 v[30:33], v[86:89], v[194:197], v[30:33]
	v_mfma_f32_16x16x32_bf16 v[22:25], v[102:105], v[194:197], v[22:25]
	v_mfma_f32_16x16x32_bf16 v[14:17], v[86:89], v[202:205], v[14:17]
	v_mfma_f32_16x16x32_bf16 v[6:9], v[102:105], v[202:205], v[6:9]
	s_barrier
	s_add_u32 s48, s16, 0x40000
	s_addc_u32 s49, s17, 0
	s_add_i32 s50, s50, s23
	v_lshl_add_u64 v[82:83], s[48:49], 0, v[150:151]
	s_mov_b32 m0, s50
	s_nop 0
	global_load_lds_dwordx4 v[82:83], off
	v_lshl_add_u64 v[82:83], s[48:49], 0, v[146:147]
	s_add_i32 m0, s50, 0x2000
	s_nop 0
	global_load_lds_dwordx4 v[82:83], off
	s_waitcnt vmcnt(6)
	s_barrier
	v_mfma_f32_16x16x32_bf16 v[58:61], v[206:209], v[174:177], v[58:61]
	v_mfma_f32_16x16x32_bf16 v[50:53], v[214:217], v[174:177], v[50:53]
	v_mfma_f32_16x16x32_bf16 v[42:45], v[206:209], v[182:185], v[42:45]
	v_mfma_f32_16x16x32_bf16 v[34:37], v[214:217], v[182:185], v[34:37]
	v_mfma_f32_16x16x32_bf16 v[26:29], v[206:209], v[190:193], v[26:29]
	v_mfma_f32_16x16x32_bf16 v[18:21], v[214:217], v[190:193], v[18:21]
	v_mfma_f32_16x16x32_bf16 v[10:13], v[206:209], v[198:201], v[10:13]
	v_mfma_f32_16x16x32_bf16 v[2:5], v[214:217], v[198:201], v[2:5]
	v_mfma_f32_16x16x32_bf16 v[58:61], v[210:213], v[178:181], v[58:61]
	v_mfma_f32_16x16x32_bf16 v[50:53], v[218:221], v[178:181], v[50:53]
	v_mfma_f32_16x16x32_bf16 v[42:45], v[210:213], v[186:189], v[42:45]
	v_mfma_f32_16x16x32_bf16 v[34:37], v[218:221], v[186:189], v[34:37]
	v_mfma_f32_16x16x32_bf16 v[26:29], v[210:213], v[194:197], v[26:29]
	v_mfma_f32_16x16x32_bf16 v[18:21], v[218:221], v[194:197], v[18:21]
	v_mfma_f32_16x16x32_bf16 v[10:13], v[210:213], v[202:205], v[10:13]
	v_mfma_f32_16x16x32_bf16 v[2:5], v[218:221], v[202:205], v[2:5]
	s_add_i32 s48, 0, 0x18000
	v_add_u32_e32 v102, s48, v171
	s_barrier
	ds_read_b128 v[82:85], v102
	ds_read_b128 v[86:89], v102 offset:1024
	ds_read_b128 v[98:101], v102 offset:2048
	ds_read_b128 v[102:105], v102 offset:3072
	s_add_u32 s18, s18, 0x40000
	s_addc_u32 s19, s19, 0
	s_mov_b32 m0, s26
	v_lshl_add_u64 v[206:207], s[18:19], 0, v[152:153]
	ds_read_b128 v[174:177], v173 offset:32768
	ds_read_b128 v[178:181], v173 offset:33792
	ds_read_b128 v[182:185], v173 offset:34816
	ds_read_b128 v[186:189], v173 offset:35840
	ds_read_b128 v[190:193], v173 offset:36864
	ds_read_b128 v[194:197], v173 offset:37888
	ds_read_b128 v[198:201], v173 offset:38912
	ds_read_b128 v[202:205], v173 offset:39936
	global_load_lds_dwordx4 v[206:207], off
	v_lshl_add_u64 v[206:207], s[18:19], 0, v[148:149]
	s_mov_b32 m0, s27
	s_nop 0
	global_load_lds_dwordx4 v[206:207], off
	s_waitcnt lgkmcnt(8)
	s_barrier
	s_waitcnt lgkmcnt(0)
	s_waitcnt lgkmcnt(0)
	v_mfma_f32_16x16x32_bf16 v[138:141], v[82:85], v[174:177], v[138:141]
	v_mfma_f32_16x16x32_bf16 v[134:137], v[98:101], v[174:177], v[134:137]
	v_mfma_f32_16x16x32_bf16 v[126:129], v[82:85], v[182:185], v[126:129]
	v_mfma_f32_16x16x32_bf16 v[118:121], v[98:101], v[182:185], v[118:121]
	v_mfma_f32_16x16x32_bf16 v[110:113], v[82:85], v[190:193], v[110:113]
	v_mfma_f32_16x16x32_bf16 v[94:97], v[98:101], v[190:193], v[94:97]
	v_mfma_f32_16x16x32_bf16 v[78:81], v[82:85], v[198:201], v[78:81]
	v_mfma_f32_16x16x32_bf16 v[70:73], v[98:101], v[198:201], v[70:73]
	v_mfma_f32_16x16x32_bf16 v[138:141], v[86:89], v[178:181], v[138:141]
	v_mfma_f32_16x16x32_bf16 v[134:137], v[102:105], v[178:181], v[134:137]
	v_mfma_f32_16x16x32_bf16 v[126:129], v[86:89], v[186:189], v[126:129]
	v_mfma_f32_16x16x32_bf16 v[118:121], v[102:105], v[186:189], v[118:121]
	v_mfma_f32_16x16x32_bf16 v[110:113], v[86:89], v[194:197], v[110:113]
	v_mfma_f32_16x16x32_bf16 v[94:97], v[102:105], v[194:197], v[94:97]
	v_mfma_f32_16x16x32_bf16 v[78:81], v[86:89], v[202:205], v[78:81]
	v_mfma_f32_16x16x32_bf16 v[70:73], v[102:105], v[202:205], v[70:73]
	s_barrier
	s_add_i32 s18, 0, 0x1c000
	s_add_i32 s19, s48, s23
	v_add_u32_e32 v158, s18, v171
	v_lshl_add_u64 v[160:161], v[160:161], 0, s[84:85]
	s_mov_b32 m0, s19
	ds_read_b128 v[206:209], v158
	ds_read_b128 v[210:213], v158 offset:1024
	ds_read_b128 v[214:217], v158 offset:2048
	ds_read_b128 v[218:221], v158 offset:3072
	global_load_lds_dwordx4 v[160:161], off
	v_lshl_add_u64 v[160:161], v[168:169], 0, s[84:85]
	s_add_i32 m0, s19, 0x2000
	s_nop 0
	global_load_lds_dwordx4 v[160:161], off
	s_barrier
	s_waitcnt lgkmcnt(0)
	s_waitcnt lgkmcnt(0)
	v_mfma_f32_16x16x32_bf16 v[142:145], v[206:209], v[174:177], v[142:145]
	v_mfma_f32_16x16x32_bf16 v[130:133], v[214:217], v[174:177], v[130:133]
	v_mfma_f32_16x16x32_bf16 v[122:125], v[206:209], v[182:185], v[122:125]
	v_mfma_f32_16x16x32_bf16 v[114:117], v[214:217], v[182:185], v[114:117]
	v_mfma_f32_16x16x32_bf16 v[106:109], v[206:209], v[190:193], v[106:109]
	v_mfma_f32_16x16x32_bf16 v[90:93], v[214:217], v[190:193], v[90:93]
	v_mfma_f32_16x16x32_bf16 v[74:77], v[206:209], v[198:201], v[74:77]
	v_mfma_f32_16x16x32_bf16 v[66:69], v[214:217], v[198:201], v[66:69]
	v_mfma_f32_16x16x32_bf16 v[142:145], v[210:213], v[178:181], v[142:145]
	v_mfma_f32_16x16x32_bf16 v[130:133], v[218:221], v[178:181], v[130:133]
	v_mfma_f32_16x16x32_bf16 v[122:125], v[210:213], v[186:189], v[122:125]
	v_mfma_f32_16x16x32_bf16 v[114:117], v[218:221], v[186:189], v[114:117]
	v_mfma_f32_16x16x32_bf16 v[106:109], v[210:213], v[194:197], v[106:109]
	v_mfma_f32_16x16x32_bf16 v[90:93], v[218:221], v[194:197], v[90:93]
	v_mfma_f32_16x16x32_bf16 v[74:77], v[210:213], v[202:205], v[74:77]
	v_mfma_f32_16x16x32_bf16 v[66:69], v[218:221], v[202:205], v[66:69]
	s_mov_b32 m0, s35
	v_lshl_add_u64 v[160:161], v[236:237], 0, s[84:85]
	s_barrier
	ds_read_b128 v[174:177], v173 offset:49152
	ds_read_b128 v[178:181], v173 offset:50176
	ds_read_b128 v[182:185], v173 offset:51200
	ds_read_b128 v[186:189], v173 offset:52224
	ds_read_b128 v[190:193], v173 offset:53248
	ds_read_b128 v[194:197], v173 offset:54272
	ds_read_b128 v[198:201], v173 offset:55296
	ds_read_b128 v[202:205], v173 offset:56320
	global_load_lds_dwordx4 v[160:161], off
	v_lshl_add_u64 v[160:161], v[238:239], 0, s[84:85]
	s_mov_b32 m0, s38
	s_nop 0
	global_load_lds_dwordx4 v[160:161], off
	s_barrier
	s_waitcnt lgkmcnt(0)
	s_waitcnt lgkmcnt(0)
	v_mfma_f32_16x16x32_bf16 v[62:65], v[82:85], v[174:177], v[62:65]
	v_mfma_f32_16x16x32_bf16 v[54:57], v[98:101], v[174:177], v[54:57]
	v_mfma_f32_16x16x32_bf16 v[46:49], v[82:85], v[182:185], v[46:49]
	v_mfma_f32_16x16x32_bf16 v[38:41], v[98:101], v[182:185], v[38:41]
	v_mfma_f32_16x16x32_bf16 v[30:33], v[82:85], v[190:193], v[30:33]
	v_mfma_f32_16x16x32_bf16 v[22:25], v[98:101], v[190:193], v[22:25]
	v_mfma_f32_16x16x32_bf16 v[14:17], v[82:85], v[198:201], v[14:17]
	v_mfma_f32_16x16x32_bf16 v[6:9], v[98:101], v[198:201], v[6:9]
	v_mfma_f32_16x16x32_bf16 v[62:65], v[86:89], v[178:181], v[62:65]
	v_mfma_f32_16x16x32_bf16 v[54:57], v[102:105], v[178:181], v[54:57]
	v_mfma_f32_16x16x32_bf16 v[46:49], v[86:89], v[186:189], v[46:49]
	v_mfma_f32_16x16x32_bf16 v[38:41], v[102:105], v[186:189], v[38:41]
	v_mfma_f32_16x16x32_bf16 v[30:33], v[86:89], v[194:197], v[30:33]
	v_mfma_f32_16x16x32_bf16 v[22:25], v[102:105], v[194:197], v[22:25]
	v_mfma_f32_16x16x32_bf16 v[14:17], v[86:89], v[202:205], v[14:17]
	v_mfma_f32_16x16x32_bf16 v[6:9], v[102:105], v[202:205], v[6:9]
	s_barrier
	s_add_u32 s16, s16, 0x40080
	s_addc_u32 s17, s17, 0
	s_add_i32 s18, s18, s23
	v_lshl_add_u64 v[82:83], s[16:17], 0, v[150:151]
	s_mov_b32 m0, s18
	s_nop 0
	global_load_lds_dwordx4 v[82:83], off
	v_lshl_add_u64 v[82:83], s[16:17], 0, v[146:147]
	s_add_i32 m0, s18, 0x2000
	s_nop 0
	global_load_lds_dwordx4 v[82:83], off
	s_waitcnt vmcnt(6)
	s_barrier
	v_mfma_f32_16x16x32_bf16 v[58:61], v[206:209], v[174:177], v[58:61]
	v_mfma_f32_16x16x32_bf16 v[50:53], v[214:217], v[174:177], v[50:53]
	v_mfma_f32_16x16x32_bf16 v[42:45], v[206:209], v[182:185], v[42:45]
	v_mfma_f32_16x16x32_bf16 v[34:37], v[214:217], v[182:185], v[34:37]
	v_mfma_f32_16x16x32_bf16 v[26:29], v[206:209], v[190:193], v[26:29]
	v_mfma_f32_16x16x32_bf16 v[18:21], v[214:217], v[190:193], v[18:21]
	v_mfma_f32_16x16x32_bf16 v[10:13], v[206:209], v[198:201], v[10:13]
	v_mfma_f32_16x16x32_bf16 v[2:5], v[214:217], v[198:201], v[2:5]
	v_mfma_f32_16x16x32_bf16 v[58:61], v[210:213], v[178:181], v[58:61]
	v_mfma_f32_16x16x32_bf16 v[50:53], v[218:221], v[178:181], v[50:53]
	v_mfma_f32_16x16x32_bf16 v[42:45], v[210:213], v[186:189], v[42:45]
	v_mfma_f32_16x16x32_bf16 v[34:37], v[218:221], v[186:189], v[34:37]
	v_mfma_f32_16x16x32_bf16 v[26:29], v[210:213], v[194:197], v[26:29]
	v_mfma_f32_16x16x32_bf16 v[18:21], v[218:221], v[194:197], v[18:21]
	v_mfma_f32_16x16x32_bf16 v[10:13], v[210:213], v[202:205], v[10:13]
	v_mfma_f32_16x16x32_bf16 v[2:5], v[218:221], v[202:205], v[2:5]
	s_add_u32 s14, s14, 0x100
	s_addc_u32 s15, s15, 0
	s_add_u32 s45, s45, 0x100
	s_addc_u32 s46, s46, 0
	s_cmp_ge_i32 s47, s30
	s_mov_b32 s16, s47
	s_barrier
	s_cbranch_scc0 .LBB0_166
	s_branch .LBB0_161

.LBB0_191:
	s_add_i32 s51, s18, 2
	s_add_u32 s19, s0, 0xfffc0080
	s_addc_u32 s20, s1, -1
	s_add_i32 s52, 0, 0x10000
	v_add_u32_e32 v122, s52, v206
	ds_read_b128 v[90:93], v122
	ds_read_b128 v[102:105], v122 offset:1024
	ds_read_b128 v[110:113], v122 offset:2048
	ds_read_b128 v[122:125], v122 offset:3072
	s_cmp_eq_u32 s43, s18
	s_cselect_b32 s18, s48, s49
	s_cselect_b32 s21, s7, s20
	s_cselect_b32 s20, s9, s19
	s_cselect_b32 s19, s47, s50
	v_lshl_add_u64 v[168:169], s[0:1], 0, v[172:173]
	s_add_i32 m0, s15, 0xc000
	ds_read_b128 v[146:149], v207
	ds_read_b128 v[150:153], v207 offset:1024
	ds_read_b128 v[176:179], v207 offset:2048
	ds_read_b128 v[180:183], v207 offset:3072
	ds_read_b128 v[184:187], v207 offset:4096
	ds_read_b128 v[188:191], v207 offset:5120
	ds_read_b128 v[192:195], v207 offset:6144
	ds_read_b128 v[196:199], v207 offset:7168
	global_load_lds_dwordx4 v[168:169], off
	v_lshl_add_u64 v[168:169], s[0:1], 0, v[174:175]
	s_add_i32 m0, s15, 0xe000
	s_nop 0
	global_load_lds_dwordx4 v[168:169], off
	s_waitcnt lgkmcnt(8)
	s_barrier
	s_waitcnt lgkmcnt(0)
	s_waitcnt lgkmcnt(0)
	v_mfma_f32_16x16x32_bf16 v[142:145], v[90:93], v[146:149], v[142:145]
	v_mfma_f32_16x16x32_bf16 v[138:141], v[110:113], v[146:149], v[138:141]
	v_mfma_f32_16x16x32_bf16 v[126:129], v[90:93], v[176:179], v[126:129]
	v_mfma_f32_16x16x32_bf16 v[118:121], v[110:113], v[176:179], v[118:121]
	v_mfma_f32_16x16x32_bf16 v[98:101], v[90:93], v[184:187], v[98:101]
	v_mfma_f32_16x16x32_bf16 v[94:97], v[110:113], v[184:187], v[94:97]
	v_mfma_f32_16x16x32_bf16 v[78:81], v[90:93], v[192:195], v[78:81]
	v_mfma_f32_16x16x32_bf16 v[74:77], v[110:113], v[192:195], v[74:77]
	v_mfma_f32_16x16x32_bf16 v[142:145], v[102:105], v[150:153], v[142:145]
	v_mfma_f32_16x16x32_bf16 v[138:141], v[122:125], v[150:153], v[138:141]
	v_mfma_f32_16x16x32_bf16 v[126:129], v[102:105], v[180:183], v[126:129]
	v_mfma_f32_16x16x32_bf16 v[118:121], v[122:125], v[180:183], v[118:121]
	v_mfma_f32_16x16x32_bf16 v[98:101], v[102:105], v[188:191], v[98:101]
	v_mfma_f32_16x16x32_bf16 v[94:97], v[122:125], v[188:191], v[94:97]
	v_mfma_f32_16x16x32_bf16 v[78:81], v[102:105], v[196:199], v[78:81]
	v_mfma_f32_16x16x32_bf16 v[74:77], v[122:125], v[196:199], v[74:77]
	s_barrier
	s_add_i32 s54, 0, 0x14000
	v_add_u32_e32 v168, s54, v206
	s_add_i32 s52, s52, s27
	ds_read_b128 v[200:203], v168
	ds_read_b128 v[208:211], v168 offset:1024
	ds_read_b128 v[212:215], v168 offset:2048
	ds_read_b128 v[216:219], v168 offset:3072
	v_lshl_add_u64 v[168:169], s[18:19], 0, v[156:157]
	s_mov_b32 m0, s52
	v_lshl_add_u64 v[204:205], s[18:19], 0, v[160:161]
	global_load_lds_dwordx4 v[168:169], off
	s_add_i32 m0, s52, 0x2000
	s_nop 0
	global_load_lds_dwordx4 v[204:205], off
	s_barrier
	s_waitcnt lgkmcnt(0)
	s_waitcnt lgkmcnt(0)
	v_mfma_f32_16x16x32_bf16 v[134:137], v[200:203], v[146:149], v[134:137]
	v_mfma_f32_16x16x32_bf16 v[130:133], v[212:215], v[146:149], v[130:133]
	v_mfma_f32_16x16x32_bf16 v[114:117], v[200:203], v[176:179], v[114:117]
	v_mfma_f32_16x16x32_bf16 v[106:109], v[212:215], v[176:179], v[106:109]
	v_mfma_f32_16x16x32_bf16 v[86:89], v[200:203], v[184:187], v[86:89]
	v_mfma_f32_16x16x32_bf16 v[82:85], v[212:215], v[184:187], v[82:85]
	v_mfma_f32_16x16x32_bf16 v[70:73], v[200:203], v[192:195], v[70:73]
	v_mfma_f32_16x16x32_bf16 v[66:69], v[212:215], v[192:195], v[66:69]
	v_mfma_f32_16x16x32_bf16 v[134:137], v[208:211], v[150:153], v[134:137]
	v_mfma_f32_16x16x32_bf16 v[130:133], v[216:219], v[150:153], v[130:133]
	v_mfma_f32_16x16x32_bf16 v[114:117], v[208:211], v[180:183], v[114:117]
	v_mfma_f32_16x16x32_bf16 v[106:109], v[216:219], v[180:183], v[106:109]
	v_mfma_f32_16x16x32_bf16 v[86:89], v[208:211], v[188:191], v[86:89]
	v_mfma_f32_16x16x32_bf16 v[82:85], v[216:219], v[188:191], v[82:85]
	v_mfma_f32_16x16x32_bf16 v[70:73], v[208:211], v[196:199], v[70:73]
	v_mfma_f32_16x16x32_bf16 v[66:69], v[216:219], v[196:199], v[66:69]
	s_mov_b32 m0, s15
	v_lshl_add_u64 v[220:221], s[20:21], 0, v[154:155]
	s_barrier
	ds_read_b128 v[146:149], v207 offset:16384
	ds_read_b128 v[150:153], v207 offset:17408
	ds_read_b128 v[176:179], v207 offset:18432
	ds_read_b128 v[180:183], v207 offset:19456
	ds_read_b128 v[184:187], v207 offset:20480
	ds_read_b128 v[188:191], v207 offset:21504
	ds_read_b128 v[192:195], v207 offset:22528
	ds_read_b128 v[196:199], v207 offset:23552
	global_load_lds_dwordx4 v[220:221], off
	v_lshl_add_u64 v[236:237], s[20:21], 0, v[158:159]
	s_mov_b32 m0, s17
	s_nop 0
	global_load_lds_dwordx4 v[236:237], off
	s_barrier
	s_waitcnt lgkmcnt(0)
	s_waitcnt lgkmcnt(0)
	v_mfma_f32_16x16x32_bf16 v[62:65], v[90:93], v[146:149], v[62:65]
	v_mfma_f32_16x16x32_bf16 v[58:61], v[110:113], v[146:149], v[58:61]
	v_mfma_f32_16x16x32_bf16 v[46:49], v[90:93], v[176:179], v[46:49]
	v_mfma_f32_16x16x32_bf16 v[42:45], v[110:113], v[176:179], v[42:45]
	v_mfma_f32_16x16x32_bf16 v[30:33], v[90:93], v[184:187], v[30:33]
	v_mfma_f32_16x16x32_bf16 v[26:29], v[110:113], v[184:187], v[26:29]
	v_mfma_f32_16x16x32_bf16 v[14:17], v[90:93], v[192:195], v[14:17]
	v_mfma_f32_16x16x32_bf16 v[10:13], v[110:113], v[192:195], v[10:13]
	v_mfma_f32_16x16x32_bf16 v[62:65], v[102:105], v[150:153], v[62:65]
	v_mfma_f32_16x16x32_bf16 v[58:61], v[122:125], v[150:153], v[58:61]
	v_mfma_f32_16x16x32_bf16 v[46:49], v[102:105], v[180:183], v[46:49]
	v_mfma_f32_16x16x32_bf16 v[42:45], v[122:125], v[180:183], v[42:45]
	v_mfma_f32_16x16x32_bf16 v[30:33], v[102:105], v[188:191], v[30:33]
	v_mfma_f32_16x16x32_bf16 v[26:29], v[122:125], v[188:191], v[26:29]
	v_mfma_f32_16x16x32_bf16 v[14:17], v[102:105], v[196:199], v[14:17]
	v_mfma_f32_16x16x32_bf16 v[10:13], v[122:125], v[196:199], v[10:13]
	s_barrier
	s_add_u32 s52, s18, 0x40000
	s_addc_u32 s53, s19, 0
	s_add_i32 s54, s54, s27
	v_lshl_add_u64 v[90:91], s[52:53], 0, v[156:157]
	s_mov_b32 m0, s54
	s_nop 0
	global_load_lds_dwordx4 v[90:91], off
	v_lshl_add_u64 v[90:91], s[52:53], 0, v[160:161]
	s_add_i32 m0, s54, 0x2000
	s_nop 0
	global_load_lds_dwordx4 v[90:91], off
	s_waitcnt vmcnt(6)
	s_barrier
	v_mfma_f32_16x16x32_bf16 v[54:57], v[200:203], v[146:149], v[54:57]
	v_mfma_f32_16x16x32_bf16 v[50:53], v[212:215], v[146:149], v[50:53]
	v_mfma_f32_16x16x32_bf16 v[38:41], v[200:203], v[176:179], v[38:41]
	v_mfma_f32_16x16x32_bf16 v[34:37], v[212:215], v[176:179], v[34:37]
	v_mfma_f32_16x16x32_bf16 v[22:25], v[200:203], v[184:187], v[22:25]
	v_mfma_f32_16x16x32_bf16 v[18:21], v[212:215], v[184:187], v[18:21]
	v_mfma_f32_16x16x32_bf16 v[6:9], v[200:203], v[192:195], v[6:9]
	v_mfma_f32_16x16x32_bf16 v[2:5], v[212:215], v[192:195], v[2:5]
	v_mfma_f32_16x16x32_bf16 v[54:57], v[208:211], v[150:153], v[54:57]
	v_mfma_f32_16x16x32_bf16 v[50:53], v[216:219], v[150:153], v[50:53]
	v_mfma_f32_16x16x32_bf16 v[38:41], v[208:211], v[180:183], v[38:41]
	v_mfma_f32_16x16x32_bf16 v[34:37], v[216:219], v[180:183], v[34:37]
	v_mfma_f32_16x16x32_bf16 v[22:25], v[208:211], v[188:191], v[22:25]
	v_mfma_f32_16x16x32_bf16 v[18:21], v[216:219], v[188:191], v[18:21]
	v_mfma_f32_16x16x32_bf16 v[6:9], v[208:211], v[196:199], v[6:9]
	v_mfma_f32_16x16x32_bf16 v[2:5], v[216:219], v[196:199], v[2:5]
	s_add_i32 s52, 0, 0x18000
	v_add_u32_e32 v122, s52, v206
	s_barrier
	ds_read_b128 v[90:93], v122
	ds_read_b128 v[102:105], v122 offset:1024
	ds_read_b128 v[110:113], v122 offset:2048
	ds_read_b128 v[122:125], v122 offset:3072
	s_add_u32 s20, s20, 0x40000
	s_addc_u32 s21, s21, 0
	s_mov_b32 m0, s28
	v_lshl_add_u64 v[200:201], s[20:21], 0, v[154:155]
	ds_read_b128 v[146:149], v207 offset:32768
	ds_read_b128 v[150:153], v207 offset:33792
	ds_read_b128 v[176:179], v207 offset:34816
	ds_read_b128 v[180:183], v207 offset:35840
	ds_read_b128 v[184:187], v207 offset:36864
	ds_read_b128 v[188:191], v207 offset:37888
	ds_read_b128 v[192:195], v207 offset:38912
	ds_read_b128 v[196:199], v207 offset:39936
	global_load_lds_dwordx4 v[200:201], off
	v_lshl_add_u64 v[200:201], s[20:21], 0, v[158:159]
	s_mov_b32 m0, s29
	s_nop 0
	global_load_lds_dwordx4 v[200:201], off
	s_waitcnt lgkmcnt(8)
	s_barrier
	s_waitcnt lgkmcnt(0)
	s_waitcnt lgkmcnt(0)
	v_mfma_f32_16x16x32_bf16 v[142:145], v[90:93], v[146:149], v[142:145]
	v_mfma_f32_16x16x32_bf16 v[138:141], v[110:113], v[146:149], v[138:141]
	v_mfma_f32_16x16x32_bf16 v[126:129], v[90:93], v[176:179], v[126:129]
	v_mfma_f32_16x16x32_bf16 v[118:121], v[110:113], v[176:179], v[118:121]
	v_mfma_f32_16x16x32_bf16 v[98:101], v[90:93], v[184:187], v[98:101]
	v_mfma_f32_16x16x32_bf16 v[94:97], v[110:113], v[184:187], v[94:97]
	v_mfma_f32_16x16x32_bf16 v[78:81], v[90:93], v[192:195], v[78:81]
	v_mfma_f32_16x16x32_bf16 v[74:77], v[110:113], v[192:195], v[74:77]
	v_mfma_f32_16x16x32_bf16 v[142:145], v[102:105], v[150:153], v[142:145]
	v_mfma_f32_16x16x32_bf16 v[138:141], v[122:125], v[150:153], v[138:141]
	v_mfma_f32_16x16x32_bf16 v[126:129], v[102:105], v[180:183], v[126:129]
	v_mfma_f32_16x16x32_bf16 v[118:121], v[122:125], v[180:183], v[118:121]
	v_mfma_f32_16x16x32_bf16 v[98:101], v[102:105], v[188:191], v[98:101]
	v_mfma_f32_16x16x32_bf16 v[94:97], v[122:125], v[188:191], v[94:97]
	v_mfma_f32_16x16x32_bf16 v[78:81], v[102:105], v[196:199], v[78:81]
	v_mfma_f32_16x16x32_bf16 v[74:77], v[122:125], v[196:199], v[74:77]
	s_barrier
	s_add_i32 s20, 0, 0x1c000
	s_add_i32 s21, s52, s27
	v_add_u32_e32 v216, s20, v206
	v_lshl_add_u64 v[168:169], v[168:169], 0, s[84:85]
	s_mov_b32 m0, s21
	ds_read_b128 v[200:203], v216
	ds_read_b128 v[208:211], v216 offset:1024
	ds_read_b128 v[212:215], v216 offset:2048
	ds_read_b128 v[216:219], v216 offset:3072
	global_load_lds_dwordx4 v[168:169], off
	v_lshl_add_u64 v[168:169], v[204:205], 0, s[84:85]
	s_add_i32 m0, s21, 0x2000
	s_nop 0
	global_load_lds_dwordx4 v[168:169], off
	s_barrier
	s_waitcnt lgkmcnt(0)
	s_waitcnt lgkmcnt(0)
	v_mfma_f32_16x16x32_bf16 v[134:137], v[200:203], v[146:149], v[134:137]
	v_mfma_f32_16x16x32_bf16 v[130:133], v[212:215], v[146:149], v[130:133]
	v_mfma_f32_16x16x32_bf16 v[114:117], v[200:203], v[176:179], v[114:117]
	v_mfma_f32_16x16x32_bf16 v[106:109], v[212:215], v[176:179], v[106:109]
	v_mfma_f32_16x16x32_bf16 v[86:89], v[200:203], v[184:187], v[86:89]
	v_mfma_f32_16x16x32_bf16 v[82:85], v[212:215], v[184:187], v[82:85]
	v_mfma_f32_16x16x32_bf16 v[70:73], v[200:203], v[192:195], v[70:73]
	v_mfma_f32_16x16x32_bf16 v[66:69], v[212:215], v[192:195], v[66:69]
	v_mfma_f32_16x16x32_bf16 v[134:137], v[208:211], v[150:153], v[134:137]
	v_mfma_f32_16x16x32_bf16 v[130:133], v[216:219], v[150:153], v[130:133]
	v_mfma_f32_16x16x32_bf16 v[114:117], v[208:211], v[180:183], v[114:117]
	v_mfma_f32_16x16x32_bf16 v[106:109], v[216:219], v[180:183], v[106:109]
	v_mfma_f32_16x16x32_bf16 v[86:89], v[208:211], v[188:191], v[86:89]
	v_mfma_f32_16x16x32_bf16 v[82:85], v[216:219], v[188:191], v[82:85]
	v_mfma_f32_16x16x32_bf16 v[70:73], v[208:211], v[196:199], v[70:73]
	v_mfma_f32_16x16x32_bf16 v[66:69], v[216:219], v[196:199], v[66:69]
	s_mov_b32 m0, s41
	v_lshl_add_u64 v[168:169], v[220:221], 0, s[84:85]
	s_barrier
	ds_read_b128 v[146:149], v207 offset:49152
	ds_read_b128 v[150:153], v207 offset:50176
	ds_read_b128 v[176:179], v207 offset:51200
	ds_read_b128 v[180:183], v207 offset:52224
	ds_read_b128 v[184:187], v207 offset:53248
	ds_read_b128 v[188:191], v207 offset:54272
	ds_read_b128 v[192:195], v207 offset:55296
	ds_read_b128 v[196:199], v207 offset:56320
	global_load_lds_dwordx4 v[168:169], off
	v_lshl_add_u64 v[168:169], v[236:237], 0, s[84:85]
	s_mov_b32 m0, s42
	s_nop 0
	global_load_lds_dwordx4 v[168:169], off
	s_barrier
	s_waitcnt lgkmcnt(0)
	s_waitcnt lgkmcnt(0)
	v_mfma_f32_16x16x32_bf16 v[62:65], v[90:93], v[146:149], v[62:65]
	v_mfma_f32_16x16x32_bf16 v[58:61], v[110:113], v[146:149], v[58:61]
	v_mfma_f32_16x16x32_bf16 v[46:49], v[90:93], v[176:179], v[46:49]
	v_mfma_f32_16x16x32_bf16 v[42:45], v[110:113], v[176:179], v[42:45]
	v_mfma_f32_16x16x32_bf16 v[30:33], v[90:93], v[184:187], v[30:33]
	v_mfma_f32_16x16x32_bf16 v[26:29], v[110:113], v[184:187], v[26:29]
	v_mfma_f32_16x16x32_bf16 v[14:17], v[90:93], v[192:195], v[14:17]
	v_mfma_f32_16x16x32_bf16 v[10:13], v[110:113], v[192:195], v[10:13]
	v_mfma_f32_16x16x32_bf16 v[62:65], v[102:105], v[150:153], v[62:65]
	v_mfma_f32_16x16x32_bf16 v[58:61], v[122:125], v[150:153], v[58:61]
	v_mfma_f32_16x16x32_bf16 v[46:49], v[102:105], v[180:183], v[46:49]
	v_mfma_f32_16x16x32_bf16 v[42:45], v[122:125], v[180:183], v[42:45]
	v_mfma_f32_16x16x32_bf16 v[30:33], v[102:105], v[188:191], v[30:33]
	v_mfma_f32_16x16x32_bf16 v[26:29], v[122:125], v[188:191], v[26:29]
	v_mfma_f32_16x16x32_bf16 v[14:17], v[102:105], v[196:199], v[14:17]
	v_mfma_f32_16x16x32_bf16 v[10:13], v[122:125], v[196:199], v[10:13]
	s_barrier
	s_add_u32 s18, s18, 0x40080
	s_addc_u32 s19, s19, 0
	s_add_i32 s20, s20, s27
	v_lshl_add_u64 v[90:91], s[18:19], 0, v[156:157]
	s_mov_b32 m0, s20
	s_nop 0
	global_load_lds_dwordx4 v[90:91], off
	v_lshl_add_u64 v[90:91], s[18:19], 0, v[160:161]
	s_add_i32 m0, s20, 0x2000
	s_nop 0
	global_load_lds_dwordx4 v[90:91], off
	s_waitcnt vmcnt(6)
	s_barrier
	v_mfma_f32_16x16x32_bf16 v[54:57], v[200:203], v[146:149], v[54:57]
	v_mfma_f32_16x16x32_bf16 v[50:53], v[212:215], v[146:149], v[50:53]
	v_mfma_f32_16x16x32_bf16 v[38:41], v[200:203], v[176:179], v[38:41]
	v_mfma_f32_16x16x32_bf16 v[34:37], v[212:215], v[176:179], v[34:37]
	v_mfma_f32_16x16x32_bf16 v[22:25], v[200:203], v[184:187], v[22:25]
	v_mfma_f32_16x16x32_bf16 v[18:21], v[212:215], v[184:187], v[18:21]
	v_mfma_f32_16x16x32_bf16 v[6:9], v[200:203], v[192:195], v[6:9]
	v_mfma_f32_16x16x32_bf16 v[2:5], v[212:215], v[192:195], v[2:5]
	v_mfma_f32_16x16x32_bf16 v[54:57], v[208:211], v[150:153], v[54:57]
	v_mfma_f32_16x16x32_bf16 v[50:53], v[216:219], v[150:153], v[50:53]
	v_mfma_f32_16x16x32_bf16 v[38:41], v[208:211], v[180:183], v[38:41]
	v_mfma_f32_16x16x32_bf16 v[34:37], v[216:219], v[180:183], v[34:37]
	v_mfma_f32_16x16x32_bf16 v[22:25], v[208:211], v[188:191], v[22:25]
	v_mfma_f32_16x16x32_bf16 v[18:21], v[216:219], v[188:191], v[18:21]
	v_mfma_f32_16x16x32_bf16 v[6:9], v[208:211], v[196:199], v[6:9]
	v_mfma_f32_16x16x32_bf16 v[2:5], v[216:219], v[196:199], v[2:5]
	s_add_u32 s49, s49, 0x100
	s_addc_u32 s50, s50, 0
	s_add_u32 s0, s0, 0x100
	s_addc_u32 s1, s1, 0
	s_cmp_ge_i32 s51, s38
	s_mov_b32 s18, s51
	s_barrier
	s_cbranch_scc0 .LBB0_191

.LBB0_427:
	s_add_i32 s23, s6, 2
	s_add_u32 s7, s4, 0xe2bf0080
	s_addc_u32 s8, s5, -1
	s_cmp_lg_u32 s22, s6
	s_cselect_b32 s6, s7, 0
	s_cselect_b32 s24, s8, 0
	s_add_u32 s8, s2, s6
	s_addc_u32 s9, s3, s24
	s_add_i32 s25, 0, 0x10000
	v_add_u32_e32 v144, s25, v142
	ds_read_b128 v[148:151], v144
	ds_read_b128 v[152:155], v144 offset:1024
	ds_read_b128 v[172:175], v144 offset:2048
	ds_read_b128 v[176:179], v144 offset:3072
	s_add_u32 s6, s0, s6
	s_addc_u32 s7, s1, s24
	v_lshl_add_u64 v[144:145], v[138:139], 0, s[4:5]
	s_add_i32 m0, s15, 0xc000
	ds_read_b128 v[180:183], v143
	ds_read_b128 v[184:187], v143 offset:1024
	ds_read_b128 v[188:191], v143 offset:2048
	ds_read_b128 v[192:195], v143 offset:3072
	ds_read_b128 v[196:199], v143 offset:4096
	ds_read_b128 v[200:203], v143 offset:5120
	ds_read_b128 v[204:207], v143 offset:6144
	ds_read_b128 v[208:211], v143 offset:7168
	global_load_lds_dwordx4 v[144:145], off
	v_lshl_add_u64 v[144:145], v[140:141], 0, s[4:5]
	s_add_i32 m0, s15, 0xe000
	s_nop 0
	global_load_lds_dwordx4 v[144:145], off
	s_waitcnt lgkmcnt(8)
	s_barrier
	s_waitcnt lgkmcnt(0)
	s_waitcnt lgkmcnt(0)
	v_mfma_f32_16x16x32_bf16 v[126:129], v[148:151], v[180:183], v[126:129]
	v_mfma_f32_16x16x32_bf16 v[122:125], v[172:175], v[180:183], v[122:125]
	v_mfma_f32_16x16x32_bf16 v[110:113], v[148:151], v[188:191], v[110:113]
	v_mfma_f32_16x16x32_bf16 v[106:109], v[172:175], v[188:191], v[106:109]
	v_mfma_f32_16x16x32_bf16 v[94:97], v[148:151], v[196:199], v[94:97]
	v_mfma_f32_16x16x32_bf16 v[90:93], v[172:175], v[196:199], v[90:93]
	v_mfma_f32_16x16x32_bf16 v[78:81], v[148:151], v[204:207], v[78:81]
	v_mfma_f32_16x16x32_bf16 v[74:77], v[172:175], v[204:207], v[74:77]
	v_mfma_f32_16x16x32_bf16 v[126:129], v[152:155], v[184:187], v[126:129]
	v_mfma_f32_16x16x32_bf16 v[122:125], v[176:179], v[184:187], v[122:125]
	v_mfma_f32_16x16x32_bf16 v[110:113], v[152:155], v[192:195], v[110:113]
	v_mfma_f32_16x16x32_bf16 v[106:109], v[176:179], v[192:195], v[106:109]
	v_mfma_f32_16x16x32_bf16 v[94:97], v[152:155], v[200:203], v[94:97]
	v_mfma_f32_16x16x32_bf16 v[90:93], v[176:179], v[200:203], v[90:93]
	v_mfma_f32_16x16x32_bf16 v[78:81], v[152:155], v[208:211], v[78:81]
	v_mfma_f32_16x16x32_bf16 v[74:77], v[176:179], v[208:211], v[74:77]
	s_barrier
	s_add_i32 s26, 0, 0x14000
	v_add_u32_e32 v144, s26, v142
	s_add_i32 s24, s25, s14
	ds_read_b128 v[212:215], v144
	ds_read_b128 v[216:219], v144 offset:1024
	ds_read_b128 v[236:239], v144 offset:2048
	ds_read_b128 v[240:243], v144 offset:3072
	v_lshl_add_u64 v[144:145], s[6:7], 0, v[132:133]
	s_mov_b32 m0, s24
	v_lshl_add_u64 v[156:157], s[6:7], 0, v[136:137]
	global_load_lds_dwordx4 v[144:145], off
	s_add_i32 m0, s24, 0x2000
	s_nop 0
	global_load_lds_dwordx4 v[156:157], off
	s_barrier
	s_waitcnt lgkmcnt(0)
	s_waitcnt lgkmcnt(0)
	v_mfma_f32_16x16x32_bf16 v[118:121], v[212:215], v[180:183], v[118:121]
	v_mfma_f32_16x16x32_bf16 v[114:117], v[236:239], v[180:183], v[114:117]
	v_mfma_f32_16x16x32_bf16 v[102:105], v[212:215], v[188:191], v[102:105]
	v_mfma_f32_16x16x32_bf16 v[98:101], v[236:239], v[188:191], v[98:101]
	v_mfma_f32_16x16x32_bf16 v[86:89], v[212:215], v[196:199], v[86:89]
	v_mfma_f32_16x16x32_bf16 v[82:85], v[236:239], v[196:199], v[82:85]
	v_mfma_f32_16x16x32_bf16 v[70:73], v[212:215], v[204:207], v[70:73]
	v_mfma_f32_16x16x32_bf16 v[66:69], v[236:239], v[204:207], v[66:69]
	v_mfma_f32_16x16x32_bf16 v[118:121], v[216:219], v[184:187], v[118:121]
	v_mfma_f32_16x16x32_bf16 v[114:117], v[240:243], v[184:187], v[114:117]
	v_mfma_f32_16x16x32_bf16 v[102:105], v[216:219], v[192:195], v[102:105]
	v_mfma_f32_16x16x32_bf16 v[98:101], v[240:243], v[192:195], v[98:101]
	v_mfma_f32_16x16x32_bf16 v[86:89], v[216:219], v[200:203], v[86:89]
	v_mfma_f32_16x16x32_bf16 v[82:85], v[240:243], v[200:203], v[82:85]
	v_mfma_f32_16x16x32_bf16 v[70:73], v[216:219], v[208:211], v[70:73]
	v_mfma_f32_16x16x32_bf16 v[66:69], v[240:243], v[208:211], v[66:69]
	s_mov_b32 m0, s15
	v_lshl_add_u64 v[160:161], s[8:9], 0, v[130:131]
	s_barrier
	ds_read_b128 v[180:183], v143 offset:16384
	ds_read_b128 v[184:187], v143 offset:17408
	ds_read_b128 v[188:191], v143 offset:18432
	ds_read_b128 v[192:195], v143 offset:19456
	ds_read_b128 v[196:199], v143 offset:20480
	ds_read_b128 v[200:203], v143 offset:21504
	ds_read_b128 v[204:207], v143 offset:22528
	ds_read_b128 v[208:211], v143 offset:23552
	global_load_lds_dwordx4 v[160:161], off
	v_lshl_add_u64 v[168:169], s[8:9], 0, v[134:135]
	s_mov_b32 m0, s16
	s_nop 0
	global_load_lds_dwordx4 v[168:169], off
	s_barrier
	s_waitcnt lgkmcnt(0)
	s_waitcnt lgkmcnt(0)
	v_mfma_f32_16x16x32_bf16 v[62:65], v[148:151], v[180:183], v[62:65]
	v_mfma_f32_16x16x32_bf16 v[58:61], v[172:175], v[180:183], v[58:61]
	v_mfma_f32_16x16x32_bf16 v[46:49], v[148:151], v[188:191], v[46:49]
	v_mfma_f32_16x16x32_bf16 v[42:45], v[172:175], v[188:191], v[42:45]
	v_mfma_f32_16x16x32_bf16 v[30:33], v[148:151], v[196:199], v[30:33]
	v_mfma_f32_16x16x32_bf16 v[26:29], v[172:175], v[196:199], v[26:29]
	v_mfma_f32_16x16x32_bf16 v[14:17], v[148:151], v[204:207], v[14:17]
	v_mfma_f32_16x16x32_bf16 v[10:13], v[172:175], v[204:207], v[10:13]
	v_mfma_f32_16x16x32_bf16 v[62:65], v[152:155], v[184:187], v[62:65]
	v_mfma_f32_16x16x32_bf16 v[58:61], v[176:179], v[184:187], v[58:61]
	v_mfma_f32_16x16x32_bf16 v[46:49], v[152:155], v[192:195], v[46:49]
	v_mfma_f32_16x16x32_bf16 v[42:45], v[176:179], v[192:195], v[42:45]
	v_mfma_f32_16x16x32_bf16 v[30:33], v[152:155], v[200:203], v[30:33]
	v_mfma_f32_16x16x32_bf16 v[26:29], v[176:179], v[200:203], v[26:29]
	v_mfma_f32_16x16x32_bf16 v[14:17], v[152:155], v[208:211], v[14:17]
	v_mfma_f32_16x16x32_bf16 v[10:13], v[176:179], v[208:211], v[10:13]
	s_barrier
	s_add_u32 s24, s6, 0x10000
	s_addc_u32 s25, s7, 0
	s_add_i32 s26, s26, s14
	v_lshl_add_u64 v[148:149], s[24:25], 0, v[132:133]
	s_mov_b32 m0, s26
	s_nop 0
	global_load_lds_dwordx4 v[148:149], off
	v_lshl_add_u64 v[148:149], s[24:25], 0, v[136:137]
	s_add_i32 m0, s26, 0x2000
	s_nop 0
	global_load_lds_dwordx4 v[148:149], off
	s_waitcnt vmcnt(6)
	s_barrier
	v_mfma_f32_16x16x32_bf16 v[54:57], v[212:215], v[180:183], v[54:57]
	v_mfma_f32_16x16x32_bf16 v[50:53], v[236:239], v[180:183], v[50:53]
	v_mfma_f32_16x16x32_bf16 v[38:41], v[212:215], v[188:191], v[38:41]
	v_mfma_f32_16x16x32_bf16 v[34:37], v[236:239], v[188:191], v[34:37]
	v_mfma_f32_16x16x32_bf16 v[22:25], v[212:215], v[196:199], v[22:25]
	v_mfma_f32_16x16x32_bf16 v[18:21], v[236:239], v[196:199], v[18:21]
	v_mfma_f32_16x16x32_bf16 v[6:9], v[212:215], v[204:207], v[6:9]
	v_mfma_f32_16x16x32_bf16 v[2:5], v[236:239], v[204:207], v[2:5]
	v_mfma_f32_16x16x32_bf16 v[54:57], v[216:219], v[184:187], v[54:57]
	v_mfma_f32_16x16x32_bf16 v[50:53], v[240:243], v[184:187], v[50:53]
	v_mfma_f32_16x16x32_bf16 v[38:41], v[216:219], v[192:195], v[38:41]
	v_mfma_f32_16x16x32_bf16 v[34:37], v[240:243], v[192:195], v[34:37]
	v_mfma_f32_16x16x32_bf16 v[22:25], v[216:219], v[200:203], v[22:25]
	v_mfma_f32_16x16x32_bf16 v[18:21], v[240:243], v[200:203], v[18:21]
	v_mfma_f32_16x16x32_bf16 v[6:9], v[216:219], v[208:211], v[6:9]
	v_mfma_f32_16x16x32_bf16 v[2:5], v[240:243], v[208:211], v[2:5]
	s_add_i32 s24, 0, 0x18000
	v_add_u32_e32 v159, s24, v142
	s_barrier
	ds_read_b128 v[148:151], v159
	ds_read_b128 v[152:155], v159 offset:1024
	ds_read_b128 v[172:175], v159 offset:2048
	ds_read_b128 v[176:179], v159 offset:3072
	s_add_u32 s8, s8, 0x10000
	s_addc_u32 s9, s9, 0
	s_mov_b32 m0, s17
	v_lshl_add_u64 v[212:213], s[8:9], 0, v[130:131]
	ds_read_b128 v[180:183], v143 offset:32768
	ds_read_b128 v[184:187], v143 offset:33792
	ds_read_b128 v[188:191], v143 offset:34816
	ds_read_b128 v[192:195], v143 offset:35840
	ds_read_b128 v[196:199], v143 offset:36864
	ds_read_b128 v[200:203], v143 offset:37888
	ds_read_b128 v[204:207], v143 offset:38912
	ds_read_b128 v[208:211], v143 offset:39936
	global_load_lds_dwordx4 v[212:213], off
	v_lshl_add_u64 v[212:213], s[8:9], 0, v[134:135]
	s_mov_b32 m0, s18
	s_nop 0
	global_load_lds_dwordx4 v[212:213], off
	s_waitcnt lgkmcnt(8)
	s_barrier
	s_waitcnt lgkmcnt(0)
	s_waitcnt lgkmcnt(0)
	v_mfma_f32_16x16x32_bf16 v[126:129], v[148:151], v[180:183], v[126:129]
	v_mfma_f32_16x16x32_bf16 v[122:125], v[172:175], v[180:183], v[122:125]
	v_mfma_f32_16x16x32_bf16 v[110:113], v[148:151], v[188:191], v[110:113]
	v_mfma_f32_16x16x32_bf16 v[106:109], v[172:175], v[188:191], v[106:109]
	v_mfma_f32_16x16x32_bf16 v[94:97], v[148:151], v[196:199], v[94:97]
	v_mfma_f32_16x16x32_bf16 v[90:93], v[172:175], v[196:199], v[90:93]
	v_mfma_f32_16x16x32_bf16 v[78:81], v[148:151], v[204:207], v[78:81]
	v_mfma_f32_16x16x32_bf16 v[74:77], v[172:175], v[204:207], v[74:77]
	v_mfma_f32_16x16x32_bf16 v[126:129], v[152:155], v[184:187], v[126:129]
	v_mfma_f32_16x16x32_bf16 v[122:125], v[176:179], v[184:187], v[122:125]
	v_mfma_f32_16x16x32_bf16 v[110:113], v[152:155], v[192:195], v[110:113]
	v_mfma_f32_16x16x32_bf16 v[106:109], v[176:179], v[192:195], v[106:109]
	v_mfma_f32_16x16x32_bf16 v[94:97], v[152:155], v[200:203], v[94:97]
	v_mfma_f32_16x16x32_bf16 v[90:93], v[176:179], v[200:203], v[90:93]
	v_mfma_f32_16x16x32_bf16 v[78:81], v[152:155], v[208:211], v[78:81]
	v_mfma_f32_16x16x32_bf16 v[74:77], v[176:179], v[208:211], v[74:77]
	s_barrier
	s_add_i32 s8, 0, 0x1c000
	s_add_i32 s9, s24, s14
	v_add_u32_e32 v159, s8, v142
	v_lshl_add_u64 v[144:145], v[144:145], 0, s[84:85]
	s_mov_b32 m0, s9
	ds_read_b128 v[212:215], v159
	ds_read_b128 v[216:219], v159 offset:1024
	ds_read_b128 v[236:239], v159 offset:2048
	ds_read_b128 v[240:243], v159 offset:3072
	global_load_lds_dwordx4 v[144:145], off
	v_lshl_add_u64 v[144:145], v[156:157], 0, s[84:85]
	s_add_i32 m0, s9, 0x2000
	s_nop 0
	global_load_lds_dwordx4 v[144:145], off
	s_barrier
	s_waitcnt lgkmcnt(0)
	s_waitcnt lgkmcnt(0)
	v_mfma_f32_16x16x32_bf16 v[118:121], v[212:215], v[180:183], v[118:121]
	v_mfma_f32_16x16x32_bf16 v[114:117], v[236:239], v[180:183], v[114:117]
	v_mfma_f32_16x16x32_bf16 v[102:105], v[212:215], v[188:191], v[102:105]
	v_mfma_f32_16x16x32_bf16 v[98:101], v[236:239], v[188:191], v[98:101]
	v_mfma_f32_16x16x32_bf16 v[86:89], v[212:215], v[196:199], v[86:89]
	v_mfma_f32_16x16x32_bf16 v[82:85], v[236:239], v[196:199], v[82:85]
	v_mfma_f32_16x16x32_bf16 v[70:73], v[212:215], v[204:207], v[70:73]
	v_mfma_f32_16x16x32_bf16 v[66:69], v[236:239], v[204:207], v[66:69]
	v_mfma_f32_16x16x32_bf16 v[118:121], v[216:219], v[184:187], v[118:121]
	v_mfma_f32_16x16x32_bf16 v[114:117], v[240:243], v[184:187], v[114:117]
	v_mfma_f32_16x16x32_bf16 v[102:105], v[216:219], v[192:195], v[102:105]
	v_mfma_f32_16x16x32_bf16 v[98:101], v[240:243], v[192:195], v[98:101]
	v_mfma_f32_16x16x32_bf16 v[86:89], v[216:219], v[200:203], v[86:89]
	v_mfma_f32_16x16x32_bf16 v[82:85], v[240:243], v[200:203], v[82:85]
	v_mfma_f32_16x16x32_bf16 v[70:73], v[216:219], v[208:211], v[70:73]
	v_mfma_f32_16x16x32_bf16 v[66:69], v[240:243], v[208:211], v[66:69]
	s_mov_b32 m0, s19
	v_lshl_add_u64 v[144:145], v[160:161], 0, s[84:85]
	s_barrier
	ds_read_b128 v[180:183], v143 offset:49152
	ds_read_b128 v[184:187], v143 offset:50176
	ds_read_b128 v[188:191], v143 offset:51200
	ds_read_b128 v[192:195], v143 offset:52224
	ds_read_b128 v[196:199], v143 offset:53248
	ds_read_b128 v[200:203], v143 offset:54272
	ds_read_b128 v[204:207], v143 offset:55296
	ds_read_b128 v[208:211], v143 offset:56320
	global_load_lds_dwordx4 v[144:145], off
	v_lshl_add_u64 v[144:145], v[168:169], 0, s[84:85]
	s_mov_b32 m0, s20
	s_nop 0
	global_load_lds_dwordx4 v[144:145], off
	s_barrier
	s_waitcnt lgkmcnt(0)
	s_waitcnt lgkmcnt(0)
	v_mfma_f32_16x16x32_bf16 v[62:65], v[148:151], v[180:183], v[62:65]
	v_mfma_f32_16x16x32_bf16 v[58:61], v[172:175], v[180:183], v[58:61]
	v_mfma_f32_16x16x32_bf16 v[46:49], v[148:151], v[188:191], v[46:49]
	v_mfma_f32_16x16x32_bf16 v[42:45], v[172:175], v[188:191], v[42:45]
	v_mfma_f32_16x16x32_bf16 v[30:33], v[148:151], v[196:199], v[30:33]
	v_mfma_f32_16x16x32_bf16 v[26:29], v[172:175], v[196:199], v[26:29]
	v_mfma_f32_16x16x32_bf16 v[14:17], v[148:151], v[204:207], v[14:17]
	v_mfma_f32_16x16x32_bf16 v[10:13], v[172:175], v[204:207], v[10:13]
	v_mfma_f32_16x16x32_bf16 v[62:65], v[152:155], v[184:187], v[62:65]
	v_mfma_f32_16x16x32_bf16 v[58:61], v[176:179], v[184:187], v[58:61]
	v_mfma_f32_16x16x32_bf16 v[46:49], v[152:155], v[192:195], v[46:49]
	v_mfma_f32_16x16x32_bf16 v[42:45], v[176:179], v[192:195], v[42:45]
	v_mfma_f32_16x16x32_bf16 v[30:33], v[152:155], v[200:203], v[30:33]
	v_mfma_f32_16x16x32_bf16 v[26:29], v[176:179], v[200:203], v[26:29]
	v_mfma_f32_16x16x32_bf16 v[14:17], v[152:155], v[208:211], v[14:17]
	v_mfma_f32_16x16x32_bf16 v[10:13], v[176:179], v[208:211], v[10:13]
	s_barrier
	s_add_u32 s6, s6, 0x10080
	s_addc_u32 s7, s7, 0
	s_add_i32 s8, s8, s14
	v_lshl_add_u64 v[144:145], s[6:7], 0, v[132:133]
	s_mov_b32 m0, s8
	s_nop 0
	global_load_lds_dwordx4 v[144:145], off
	v_lshl_add_u64 v[144:145], s[6:7], 0, v[136:137]
	s_add_i32 m0, s8, 0x2000
	s_nop 0
	global_load_lds_dwordx4 v[144:145], off
	s_waitcnt vmcnt(6)
	s_barrier
	v_mfma_f32_16x16x32_bf16 v[54:57], v[212:215], v[180:183], v[54:57]
	v_mfma_f32_16x16x32_bf16 v[50:53], v[236:239], v[180:183], v[50:53]
	v_mfma_f32_16x16x32_bf16 v[38:41], v[212:215], v[188:191], v[38:41]
	v_mfma_f32_16x16x32_bf16 v[34:37], v[236:239], v[188:191], v[34:37]
	v_mfma_f32_16x16x32_bf16 v[22:25], v[212:215], v[196:199], v[22:25]
	v_mfma_f32_16x16x32_bf16 v[18:21], v[236:239], v[196:199], v[18:21]
	v_mfma_f32_16x16x32_bf16 v[6:9], v[212:215], v[204:207], v[6:9]
	v_mfma_f32_16x16x32_bf16 v[2:5], v[236:239], v[204:207], v[2:5]
	v_mfma_f32_16x16x32_bf16 v[54:57], v[216:219], v[184:187], v[54:57]
	v_mfma_f32_16x16x32_bf16 v[50:53], v[240:243], v[184:187], v[50:53]
	v_mfma_f32_16x16x32_bf16 v[38:41], v[216:219], v[192:195], v[38:41]
	v_mfma_f32_16x16x32_bf16 v[34:37], v[240:243], v[192:195], v[34:37]
	v_mfma_f32_16x16x32_bf16 v[22:25], v[216:219], v[200:203], v[22:25]
	v_mfma_f32_16x16x32_bf16 v[18:21], v[240:243], v[200:203], v[18:21]
	v_mfma_f32_16x16x32_bf16 v[6:9], v[216:219], v[208:211], v[6:9]
	v_mfma_f32_16x16x32_bf16 v[2:5], v[240:243], v[208:211], v[2:5]
	s_add_u32 s4, s4, 0x100
	s_addc_u32 s5, s5, 0
	s_cmp_ge_i32 s23, s21
	s_mov_b32 s6, s23
	s_barrier
	s_cbranch_scc0 .LBB0_427

.LBB0_439:
	s_add_i32 s23, s6, 2
	s_add_u32 s7, s4, 0xe2df0080
	s_addc_u32 s8, s5, -1
	s_cmp_lg_u32 s22, s6
	s_cselect_b32 s6, s7, 0
	s_cselect_b32 s24, s8, 0
	s_add_u32 s8, s2, s6
	s_addc_u32 s9, s3, s24
	s_add_i32 s25, 0, 0x10000
	v_add_u32_e32 v144, s25, v142
	ds_read_b128 v[148:151], v144
	ds_read_b128 v[152:155], v144 offset:1024
	ds_read_b128 v[172:175], v144 offset:2048
	ds_read_b128 v[176:179], v144 offset:3072
	s_add_u32 s6, s0, s6
	s_addc_u32 s7, s1, s24
	v_lshl_add_u64 v[144:145], v[138:139], 0, s[4:5]
	s_add_i32 m0, s15, 0xc000
	ds_read_b128 v[180:183], v143
	ds_read_b128 v[184:187], v143 offset:1024
	ds_read_b128 v[188:191], v143 offset:2048
	ds_read_b128 v[192:195], v143 offset:3072
	ds_read_b128 v[196:199], v143 offset:4096
	ds_read_b128 v[200:203], v143 offset:5120
	ds_read_b128 v[204:207], v143 offset:6144
	ds_read_b128 v[208:211], v143 offset:7168
	global_load_lds_dwordx4 v[144:145], off
	v_lshl_add_u64 v[144:145], v[140:141], 0, s[4:5]
	s_add_i32 m0, s15, 0xe000
	s_nop 0
	global_load_lds_dwordx4 v[144:145], off
	s_waitcnt lgkmcnt(8)
	s_barrier
	s_waitcnt lgkmcnt(0)
	s_waitcnt lgkmcnt(0)
	v_mfma_f32_16x16x32_bf16 v[126:129], v[148:151], v[180:183], v[126:129]
	v_mfma_f32_16x16x32_bf16 v[122:125], v[172:175], v[180:183], v[122:125]
	v_mfma_f32_16x16x32_bf16 v[110:113], v[148:151], v[188:191], v[110:113]
	v_mfma_f32_16x16x32_bf16 v[106:109], v[172:175], v[188:191], v[106:109]
	v_mfma_f32_16x16x32_bf16 v[94:97], v[148:151], v[196:199], v[94:97]
	v_mfma_f32_16x16x32_bf16 v[90:93], v[172:175], v[196:199], v[90:93]
	v_mfma_f32_16x16x32_bf16 v[78:81], v[148:151], v[204:207], v[78:81]
	v_mfma_f32_16x16x32_bf16 v[74:77], v[172:175], v[204:207], v[74:77]
	v_mfma_f32_16x16x32_bf16 v[126:129], v[152:155], v[184:187], v[126:129]
	v_mfma_f32_16x16x32_bf16 v[122:125], v[176:179], v[184:187], v[122:125]
	v_mfma_f32_16x16x32_bf16 v[110:113], v[152:155], v[192:195], v[110:113]
	v_mfma_f32_16x16x32_bf16 v[106:109], v[176:179], v[192:195], v[106:109]
	v_mfma_f32_16x16x32_bf16 v[94:97], v[152:155], v[200:203], v[94:97]
	v_mfma_f32_16x16x32_bf16 v[90:93], v[176:179], v[200:203], v[90:93]
	v_mfma_f32_16x16x32_bf16 v[78:81], v[152:155], v[208:211], v[78:81]
	v_mfma_f32_16x16x32_bf16 v[74:77], v[176:179], v[208:211], v[74:77]
	s_barrier
	s_add_i32 s26, 0, 0x14000
	v_add_u32_e32 v144, s26, v142
	s_add_i32 s24, s25, s14
	ds_read_b128 v[212:215], v144
	ds_read_b128 v[216:219], v144 offset:1024
	ds_read_b128 v[236:239], v144 offset:2048
	ds_read_b128 v[240:243], v144 offset:3072
	v_lshl_add_u64 v[144:145], s[6:7], 0, v[132:133]
	s_mov_b32 m0, s24
	v_lshl_add_u64 v[156:157], s[6:7], 0, v[136:137]
	global_load_lds_dwordx4 v[144:145], off
	s_add_i32 m0, s24, 0x2000
	s_nop 0
	global_load_lds_dwordx4 v[156:157], off
	s_barrier
	s_waitcnt lgkmcnt(0)
	s_waitcnt lgkmcnt(0)
	v_mfma_f32_16x16x32_bf16 v[118:121], v[212:215], v[180:183], v[118:121]
	v_mfma_f32_16x16x32_bf16 v[114:117], v[236:239], v[180:183], v[114:117]
	v_mfma_f32_16x16x32_bf16 v[102:105], v[212:215], v[188:191], v[102:105]
	v_mfma_f32_16x16x32_bf16 v[98:101], v[236:239], v[188:191], v[98:101]
	v_mfma_f32_16x16x32_bf16 v[86:89], v[212:215], v[196:199], v[86:89]
	v_mfma_f32_16x16x32_bf16 v[82:85], v[236:239], v[196:199], v[82:85]
	v_mfma_f32_16x16x32_bf16 v[70:73], v[212:215], v[204:207], v[70:73]
	v_mfma_f32_16x16x32_bf16 v[66:69], v[236:239], v[204:207], v[66:69]
	v_mfma_f32_16x16x32_bf16 v[118:121], v[216:219], v[184:187], v[118:121]
	v_mfma_f32_16x16x32_bf16 v[114:117], v[240:243], v[184:187], v[114:117]
	v_mfma_f32_16x16x32_bf16 v[102:105], v[216:219], v[192:195], v[102:105]
	v_mfma_f32_16x16x32_bf16 v[98:101], v[240:243], v[192:195], v[98:101]
	v_mfma_f32_16x16x32_bf16 v[86:89], v[216:219], v[200:203], v[86:89]
	v_mfma_f32_16x16x32_bf16 v[82:85], v[240:243], v[200:203], v[82:85]
	v_mfma_f32_16x16x32_bf16 v[70:73], v[216:219], v[208:211], v[70:73]
	v_mfma_f32_16x16x32_bf16 v[66:69], v[240:243], v[208:211], v[66:69]
	s_mov_b32 m0, s15
	v_lshl_add_u64 v[160:161], s[8:9], 0, v[130:131]
	s_barrier
	ds_read_b128 v[180:183], v143 offset:16384
	ds_read_b128 v[184:187], v143 offset:17408
	ds_read_b128 v[188:191], v143 offset:18432
	ds_read_b128 v[192:195], v143 offset:19456
	ds_read_b128 v[196:199], v143 offset:20480
	ds_read_b128 v[200:203], v143 offset:21504
	ds_read_b128 v[204:207], v143 offset:22528
	ds_read_b128 v[208:211], v143 offset:23552
	global_load_lds_dwordx4 v[160:161], off
	v_lshl_add_u64 v[168:169], s[8:9], 0, v[134:135]
	s_mov_b32 m0, s16
	s_nop 0
	global_load_lds_dwordx4 v[168:169], off
	s_barrier
	s_waitcnt lgkmcnt(0)
	s_waitcnt lgkmcnt(0)
	v_mfma_f32_16x16x32_bf16 v[62:65], v[148:151], v[180:183], v[62:65]
	v_mfma_f32_16x16x32_bf16 v[58:61], v[172:175], v[180:183], v[58:61]
	v_mfma_f32_16x16x32_bf16 v[46:49], v[148:151], v[188:191], v[46:49]
	v_mfma_f32_16x16x32_bf16 v[42:45], v[172:175], v[188:191], v[42:45]
	v_mfma_f32_16x16x32_bf16 v[30:33], v[148:151], v[196:199], v[30:33]
	v_mfma_f32_16x16x32_bf16 v[26:29], v[172:175], v[196:199], v[26:29]
	v_mfma_f32_16x16x32_bf16 v[14:17], v[148:151], v[204:207], v[14:17]
	v_mfma_f32_16x16x32_bf16 v[10:13], v[172:175], v[204:207], v[10:13]
	v_mfma_f32_16x16x32_bf16 v[62:65], v[152:155], v[184:187], v[62:65]
	v_mfma_f32_16x16x32_bf16 v[58:61], v[176:179], v[184:187], v[58:61]
	v_mfma_f32_16x16x32_bf16 v[46:49], v[152:155], v[192:195], v[46:49]
	v_mfma_f32_16x16x32_bf16 v[42:45], v[176:179], v[192:195], v[42:45]
	v_mfma_f32_16x16x32_bf16 v[30:33], v[152:155], v[200:203], v[30:33]
	v_mfma_f32_16x16x32_bf16 v[26:29], v[176:179], v[200:203], v[26:29]
	v_mfma_f32_16x16x32_bf16 v[14:17], v[152:155], v[208:211], v[14:17]
	v_mfma_f32_16x16x32_bf16 v[10:13], v[176:179], v[208:211], v[10:13]
	s_barrier
	s_add_u32 s24, s6, 0x10000
	s_addc_u32 s25, s7, 0
	s_add_i32 s26, s26, s14
	v_lshl_add_u64 v[148:149], s[24:25], 0, v[132:133]
	s_mov_b32 m0, s26
	s_nop 0
	global_load_lds_dwordx4 v[148:149], off
	v_lshl_add_u64 v[148:149], s[24:25], 0, v[136:137]
	s_add_i32 m0, s26, 0x2000
	s_nop 0
	global_load_lds_dwordx4 v[148:149], off
	s_waitcnt vmcnt(6)
	s_barrier
	v_mfma_f32_16x16x32_bf16 v[54:57], v[212:215], v[180:183], v[54:57]
	v_mfma_f32_16x16x32_bf16 v[50:53], v[236:239], v[180:183], v[50:53]
	v_mfma_f32_16x16x32_bf16 v[38:41], v[212:215], v[188:191], v[38:41]
	v_mfma_f32_16x16x32_bf16 v[34:37], v[236:239], v[188:191], v[34:37]
	v_mfma_f32_16x16x32_bf16 v[22:25], v[212:215], v[196:199], v[22:25]
	v_mfma_f32_16x16x32_bf16 v[18:21], v[236:239], v[196:199], v[18:21]
	v_mfma_f32_16x16x32_bf16 v[6:9], v[212:215], v[204:207], v[6:9]
	v_mfma_f32_16x16x32_bf16 v[2:5], v[236:239], v[204:207], v[2:5]
	v_mfma_f32_16x16x32_bf16 v[54:57], v[216:219], v[184:187], v[54:57]
	v_mfma_f32_16x16x32_bf16 v[50:53], v[240:243], v[184:187], v[50:53]
	v_mfma_f32_16x16x32_bf16 v[38:41], v[216:219], v[192:195], v[38:41]
	v_mfma_f32_16x16x32_bf16 v[34:37], v[240:243], v[192:195], v[34:37]
	v_mfma_f32_16x16x32_bf16 v[22:25], v[216:219], v[200:203], v[22:25]
	v_mfma_f32_16x16x32_bf16 v[18:21], v[240:243], v[200:203], v[18:21]
	v_mfma_f32_16x16x32_bf16 v[6:9], v[216:219], v[208:211], v[6:9]
	v_mfma_f32_16x16x32_bf16 v[2:5], v[240:243], v[208:211], v[2:5]
	s_add_i32 s24, 0, 0x18000
	v_add_u32_e32 v159, s24, v142
	s_barrier
	ds_read_b128 v[148:151], v159
	ds_read_b128 v[152:155], v159 offset:1024
	ds_read_b128 v[172:175], v159 offset:2048
	ds_read_b128 v[176:179], v159 offset:3072
	s_add_u32 s8, s8, 0x10000
	s_addc_u32 s9, s9, 0
	s_mov_b32 m0, s17
	v_lshl_add_u64 v[212:213], s[8:9], 0, v[130:131]
	ds_read_b128 v[180:183], v143 offset:32768
	ds_read_b128 v[184:187], v143 offset:33792
	ds_read_b128 v[188:191], v143 offset:34816
	ds_read_b128 v[192:195], v143 offset:35840
	ds_read_b128 v[196:199], v143 offset:36864
	ds_read_b128 v[200:203], v143 offset:37888
	ds_read_b128 v[204:207], v143 offset:38912
	ds_read_b128 v[208:211], v143 offset:39936
	global_load_lds_dwordx4 v[212:213], off
	v_lshl_add_u64 v[212:213], s[8:9], 0, v[134:135]
	s_mov_b32 m0, s18
	s_nop 0
	global_load_lds_dwordx4 v[212:213], off
	s_waitcnt lgkmcnt(8)
	s_barrier
	s_waitcnt lgkmcnt(0)
	s_waitcnt lgkmcnt(0)
	v_mfma_f32_16x16x32_bf16 v[126:129], v[148:151], v[180:183], v[126:129]
	v_mfma_f32_16x16x32_bf16 v[122:125], v[172:175], v[180:183], v[122:125]
	v_mfma_f32_16x16x32_bf16 v[110:113], v[148:151], v[188:191], v[110:113]
	v_mfma_f32_16x16x32_bf16 v[106:109], v[172:175], v[188:191], v[106:109]
	v_mfma_f32_16x16x32_bf16 v[94:97], v[148:151], v[196:199], v[94:97]
	v_mfma_f32_16x16x32_bf16 v[90:93], v[172:175], v[196:199], v[90:93]
	v_mfma_f32_16x16x32_bf16 v[78:81], v[148:151], v[204:207], v[78:81]
	v_mfma_f32_16x16x32_bf16 v[74:77], v[172:175], v[204:207], v[74:77]
	v_mfma_f32_16x16x32_bf16 v[126:129], v[152:155], v[184:187], v[126:129]
	v_mfma_f32_16x16x32_bf16 v[122:125], v[176:179], v[184:187], v[122:125]
	v_mfma_f32_16x16x32_bf16 v[110:113], v[152:155], v[192:195], v[110:113]
	v_mfma_f32_16x16x32_bf16 v[106:109], v[176:179], v[192:195], v[106:109]
	v_mfma_f32_16x16x32_bf16 v[94:97], v[152:155], v[200:203], v[94:97]
	v_mfma_f32_16x16x32_bf16 v[90:93], v[176:179], v[200:203], v[90:93]
	v_mfma_f32_16x16x32_bf16 v[78:81], v[152:155], v[208:211], v[78:81]
	v_mfma_f32_16x16x32_bf16 v[74:77], v[176:179], v[208:211], v[74:77]
	s_barrier
	s_add_i32 s8, 0, 0x1c000
	s_add_i32 s9, s24, s14
	v_add_u32_e32 v159, s8, v142
	v_lshl_add_u64 v[144:145], v[144:145], 0, s[84:85]
	s_mov_b32 m0, s9
	ds_read_b128 v[212:215], v159
	ds_read_b128 v[216:219], v159 offset:1024
	ds_read_b128 v[236:239], v159 offset:2048
	ds_read_b128 v[240:243], v159 offset:3072
	global_load_lds_dwordx4 v[144:145], off
	v_lshl_add_u64 v[144:145], v[156:157], 0, s[84:85]
	s_add_i32 m0, s9, 0x2000
	s_nop 0
	global_load_lds_dwordx4 v[144:145], off
	s_barrier
	s_waitcnt lgkmcnt(0)
	s_waitcnt lgkmcnt(0)
	v_mfma_f32_16x16x32_bf16 v[118:121], v[212:215], v[180:183], v[118:121]
	v_mfma_f32_16x16x32_bf16 v[114:117], v[236:239], v[180:183], v[114:117]
	v_mfma_f32_16x16x32_bf16 v[102:105], v[212:215], v[188:191], v[102:105]
	v_mfma_f32_16x16x32_bf16 v[98:101], v[236:239], v[188:191], v[98:101]
	v_mfma_f32_16x16x32_bf16 v[86:89], v[212:215], v[196:199], v[86:89]
	v_mfma_f32_16x16x32_bf16 v[82:85], v[236:239], v[196:199], v[82:85]
	v_mfma_f32_16x16x32_bf16 v[70:73], v[212:215], v[204:207], v[70:73]
	v_mfma_f32_16x16x32_bf16 v[66:69], v[236:239], v[204:207], v[66:69]
	v_mfma_f32_16x16x32_bf16 v[118:121], v[216:219], v[184:187], v[118:121]
	v_mfma_f32_16x16x32_bf16 v[114:117], v[240:243], v[184:187], v[114:117]
	v_mfma_f32_16x16x32_bf16 v[102:105], v[216:219], v[192:195], v[102:105]
	v_mfma_f32_16x16x32_bf16 v[98:101], v[240:243], v[192:195], v[98:101]
	v_mfma_f32_16x16x32_bf16 v[86:89], v[216:219], v[200:203], v[86:89]
	v_mfma_f32_16x16x32_bf16 v[82:85], v[240:243], v[200:203], v[82:85]
	v_mfma_f32_16x16x32_bf16 v[70:73], v[216:219], v[208:211], v[70:73]
	v_mfma_f32_16x16x32_bf16 v[66:69], v[240:243], v[208:211], v[66:69]
	s_mov_b32 m0, s19
	v_lshl_add_u64 v[144:145], v[160:161], 0, s[84:85]
	s_barrier
	ds_read_b128 v[180:183], v143 offset:49152
	ds_read_b128 v[184:187], v143 offset:50176
	ds_read_b128 v[188:191], v143 offset:51200
	ds_read_b128 v[192:195], v143 offset:52224
	ds_read_b128 v[196:199], v143 offset:53248
	ds_read_b128 v[200:203], v143 offset:54272
	ds_read_b128 v[204:207], v143 offset:55296
	ds_read_b128 v[208:211], v143 offset:56320
	global_load_lds_dwordx4 v[144:145], off
	v_lshl_add_u64 v[144:145], v[168:169], 0, s[84:85]
	s_mov_b32 m0, s20
	s_nop 0
	global_load_lds_dwordx4 v[144:145], off
	s_barrier
	s_waitcnt lgkmcnt(0)
	s_waitcnt lgkmcnt(0)
	v_mfma_f32_16x16x32_bf16 v[62:65], v[148:151], v[180:183], v[62:65]
	v_mfma_f32_16x16x32_bf16 v[58:61], v[172:175], v[180:183], v[58:61]
	v_mfma_f32_16x16x32_bf16 v[46:49], v[148:151], v[188:191], v[46:49]
	v_mfma_f32_16x16x32_bf16 v[42:45], v[172:175], v[188:191], v[42:45]
	v_mfma_f32_16x16x32_bf16 v[30:33], v[148:151], v[196:199], v[30:33]
	v_mfma_f32_16x16x32_bf16 v[26:29], v[172:175], v[196:199], v[26:29]
	v_mfma_f32_16x16x32_bf16 v[14:17], v[148:151], v[204:207], v[14:17]
	v_mfma_f32_16x16x32_bf16 v[10:13], v[172:175], v[204:207], v[10:13]
	v_mfma_f32_16x16x32_bf16 v[62:65], v[152:155], v[184:187], v[62:65]
	v_mfma_f32_16x16x32_bf16 v[58:61], v[176:179], v[184:187], v[58:61]
	v_mfma_f32_16x16x32_bf16 v[46:49], v[152:155], v[192:195], v[46:49]
	v_mfma_f32_16x16x32_bf16 v[42:45], v[176:179], v[192:195], v[42:45]
	v_mfma_f32_16x16x32_bf16 v[30:33], v[152:155], v[200:203], v[30:33]
	v_mfma_f32_16x16x32_bf16 v[26:29], v[176:179], v[200:203], v[26:29]
	v_mfma_f32_16x16x32_bf16 v[14:17], v[152:155], v[208:211], v[14:17]
	v_mfma_f32_16x16x32_bf16 v[10:13], v[176:179], v[208:211], v[10:13]
	s_barrier
	s_add_u32 s6, s6, 0x10080
	s_addc_u32 s7, s7, 0
	s_add_i32 s8, s8, s14
	v_lshl_add_u64 v[144:145], s[6:7], 0, v[132:133]
	s_mov_b32 m0, s8
	s_nop 0
	global_load_lds_dwordx4 v[144:145], off
	v_lshl_add_u64 v[144:145], s[6:7], 0, v[136:137]
	s_add_i32 m0, s8, 0x2000
	s_nop 0
	global_load_lds_dwordx4 v[144:145], off
	s_waitcnt vmcnt(6)
	s_barrier
	v_mfma_f32_16x16x32_bf16 v[54:57], v[212:215], v[180:183], v[54:57]
	v_mfma_f32_16x16x32_bf16 v[50:53], v[236:239], v[180:183], v[50:53]
	v_mfma_f32_16x16x32_bf16 v[38:41], v[212:215], v[188:191], v[38:41]
	v_mfma_f32_16x16x32_bf16 v[34:37], v[236:239], v[188:191], v[34:37]
	v_mfma_f32_16x16x32_bf16 v[22:25], v[212:215], v[196:199], v[22:25]
	v_mfma_f32_16x16x32_bf16 v[18:21], v[236:239], v[196:199], v[18:21]
	v_mfma_f32_16x16x32_bf16 v[6:9], v[212:215], v[204:207], v[6:9]
	v_mfma_f32_16x16x32_bf16 v[2:5], v[236:239], v[204:207], v[2:5]
	v_mfma_f32_16x16x32_bf16 v[54:57], v[216:219], v[184:187], v[54:57]
	v_mfma_f32_16x16x32_bf16 v[50:53], v[240:243], v[184:187], v[50:53]
	v_mfma_f32_16x16x32_bf16 v[38:41], v[216:219], v[192:195], v[38:41]
	v_mfma_f32_16x16x32_bf16 v[34:37], v[240:243], v[192:195], v[34:37]
	v_mfma_f32_16x16x32_bf16 v[22:25], v[216:219], v[200:203], v[22:25]
	v_mfma_f32_16x16x32_bf16 v[18:21], v[240:243], v[200:203], v[18:21]
	v_mfma_f32_16x16x32_bf16 v[6:9], v[216:219], v[208:211], v[6:9]
	v_mfma_f32_16x16x32_bf16 v[2:5], v[240:243], v[208:211], v[2:5]
	s_add_u32 s4, s4, 0x100
	s_addc_u32 s5, s5, 0
	s_cmp_ge_i32 s23, s21
	s_mov_b32 s6, s23
	s_barrier
	s_cbranch_scc0 .LBB0_439

.LBB0_454:
	s_add_i32 s52, s20, 2
	s_add_u32 s21, s18, 0xfffc0080
	s_addc_u32 s22, s19, -1
	s_add_i32 s53, 0, 0x10000
	v_add_u32_e32 v154, s53, v159
	ds_read_b128 v[130:133], v154
	ds_read_b128 v[134:137], v154 offset:1024
	ds_read_b128 v[150:153], v154 offset:2048
	ds_read_b128 v[154:157], v154 offset:3072
	s_cmp_eq_u32 s44, s20
	s_cselect_b32 s20, s49, s50
	s_cselect_b32 s23, s9, s22
	s_cselect_b32 s22, s11, s21
	s_cselect_b32 s21, s48, s51
	v_lshl_add_u64 v[168:169], s[18:19], 0, v[146:147]
	s_add_i32 m0, s29, 0xc000
	ds_read_b128 v[172:175], v160
	ds_read_b128 v[176:179], v160 offset:1024
	ds_read_b128 v[180:183], v160 offset:2048
	ds_read_b128 v[184:187], v160 offset:3072
	ds_read_b128 v[188:191], v160 offset:4096
	ds_read_b128 v[192:195], v160 offset:5120
	ds_read_b128 v[196:199], v160 offset:6144
	ds_read_b128 v[200:203], v160 offset:7168
	global_load_lds_dwordx4 v[168:169], off
	v_lshl_add_u64 v[168:169], s[18:19], 0, v[148:149]
	s_add_i32 m0, s29, 0xe000
	s_nop 0
	global_load_lds_dwordx4 v[168:169], off
	s_waitcnt lgkmcnt(8)
	s_barrier
	s_waitcnt lgkmcnt(0)
	s_waitcnt lgkmcnt(0)
	v_mfma_f32_16x16x32_bf16 v[118:121], v[130:133], v[172:175], v[118:121]
	v_mfma_f32_16x16x32_bf16 v[122:125], v[150:153], v[172:175], v[122:125]
	v_mfma_f32_16x16x32_bf16 v[102:105], v[130:133], v[180:183], v[102:105]
	v_mfma_f32_16x16x32_bf16 v[106:109], v[150:153], v[180:183], v[106:109]
	v_mfma_f32_16x16x32_bf16 v[86:89], v[130:133], v[188:191], v[86:89]
	v_mfma_f32_16x16x32_bf16 v[90:93], v[150:153], v[188:191], v[90:93]
	v_mfma_f32_16x16x32_bf16 v[70:73], v[130:133], v[196:199], v[70:73]
	v_mfma_f32_16x16x32_bf16 v[74:77], v[150:153], v[196:199], v[74:77]
	v_mfma_f32_16x16x32_bf16 v[118:121], v[134:137], v[176:179], v[118:121]
	v_mfma_f32_16x16x32_bf16 v[122:125], v[154:157], v[176:179], v[122:125]
	v_mfma_f32_16x16x32_bf16 v[102:105], v[134:137], v[184:187], v[102:105]
	v_mfma_f32_16x16x32_bf16 v[106:109], v[154:157], v[184:187], v[106:109]
	v_mfma_f32_16x16x32_bf16 v[86:89], v[134:137], v[192:195], v[86:89]
	v_mfma_f32_16x16x32_bf16 v[90:93], v[154:157], v[192:195], v[90:93]
	v_mfma_f32_16x16x32_bf16 v[70:73], v[134:137], v[200:203], v[70:73]
	v_mfma_f32_16x16x32_bf16 v[74:77], v[154:157], v[200:203], v[74:77]
	s_barrier
	s_add_i32 s56, 0, 0x14000
	s_add_i32 s53, s53, s27
	v_add_u32_e32 v161, s56, v159
	v_lshl_add_u64 v[168:169], s[20:21], 0, v[142:143]
	s_mov_b32 m0, s53
	ds_read_b128 v[204:207], v161
	ds_read_b128 v[208:211], v161 offset:1024
	ds_read_b128 v[212:215], v161 offset:2048
	ds_read_b128 v[216:219], v161 offset:3072
	global_load_lds_dwordx4 v[168:169], off
	v_lshl_add_u64 v[220:221], s[20:21], 0, v[138:139]
	s_add_i32 m0, s53, 0x2000
	s_nop 0
	global_load_lds_dwordx4 v[220:221], off
	s_barrier
	s_waitcnt lgkmcnt(0)
	s_waitcnt lgkmcnt(0)
	v_mfma_f32_16x16x32_bf16 v[114:117], v[204:207], v[172:175], v[114:117]
	v_mfma_f32_16x16x32_bf16 v[126:129], v[212:215], v[172:175], v[126:129]
	v_mfma_f32_16x16x32_bf16 v[98:101], v[204:207], v[180:183], v[98:101]
	v_mfma_f32_16x16x32_bf16 v[110:113], v[212:215], v[180:183], v[110:113]
	v_mfma_f32_16x16x32_bf16 v[82:85], v[204:207], v[188:191], v[82:85]
	v_mfma_f32_16x16x32_bf16 v[94:97], v[212:215], v[188:191], v[94:97]
	v_mfma_f32_16x16x32_bf16 v[66:69], v[204:207], v[196:199], v[66:69]
	v_mfma_f32_16x16x32_bf16 v[78:81], v[212:215], v[196:199], v[78:81]
	v_mfma_f32_16x16x32_bf16 v[114:117], v[208:211], v[176:179], v[114:117]
	v_mfma_f32_16x16x32_bf16 v[126:129], v[216:219], v[176:179], v[126:129]
	v_mfma_f32_16x16x32_bf16 v[98:101], v[208:211], v[184:187], v[98:101]
	v_mfma_f32_16x16x32_bf16 v[110:113], v[216:219], v[184:187], v[110:113]
	v_mfma_f32_16x16x32_bf16 v[82:85], v[208:211], v[192:195], v[82:85]
	v_mfma_f32_16x16x32_bf16 v[94:97], v[216:219], v[192:195], v[94:97]
	v_mfma_f32_16x16x32_bf16 v[66:69], v[208:211], v[200:203], v[66:69]
	v_mfma_f32_16x16x32_bf16 v[78:81], v[216:219], v[200:203], v[78:81]
	s_mov_b32 m0, s29
	v_lshl_add_u64 v[236:237], s[22:23], 0, v[144:145]
	s_barrier
	ds_read_b128 v[172:175], v160 offset:16384
	ds_read_b128 v[176:179], v160 offset:17408
	ds_read_b128 v[180:183], v160 offset:18432
	ds_read_b128 v[184:187], v160 offset:19456
	ds_read_b128 v[188:191], v160 offset:20480
	ds_read_b128 v[192:195], v160 offset:21504
	ds_read_b128 v[196:199], v160 offset:22528
	ds_read_b128 v[200:203], v160 offset:23552
	global_load_lds_dwordx4 v[236:237], off
	v_lshl_add_u64 v[238:239], s[22:23], 0, v[140:141]
	s_mov_b32 m0, s30
	s_nop 0
	global_load_lds_dwordx4 v[238:239], off
	s_barrier
	s_waitcnt lgkmcnt(0)
	s_waitcnt lgkmcnt(0)
	v_mfma_f32_16x16x32_bf16 v[54:57], v[130:133], v[172:175], v[54:57]
	v_mfma_f32_16x16x32_bf16 v[58:61], v[150:153], v[172:175], v[58:61]
	v_mfma_f32_16x16x32_bf16 v[38:41], v[130:133], v[180:183], v[38:41]
	v_mfma_f32_16x16x32_bf16 v[42:45], v[150:153], v[180:183], v[42:45]
	v_mfma_f32_16x16x32_bf16 v[22:25], v[130:133], v[188:191], v[22:25]
	v_mfma_f32_16x16x32_bf16 v[26:29], v[150:153], v[188:191], v[26:29]
	v_mfma_f32_16x16x32_bf16 v[10:13], v[130:133], v[196:199], v[10:13]
	v_mfma_f32_16x16x32_bf16 v[14:17], v[150:153], v[196:199], v[14:17]
	v_mfma_f32_16x16x32_bf16 v[54:57], v[134:137], v[176:179], v[54:57]
	v_mfma_f32_16x16x32_bf16 v[58:61], v[154:157], v[176:179], v[58:61]
	v_mfma_f32_16x16x32_bf16 v[38:41], v[134:137], v[184:187], v[38:41]
	v_mfma_f32_16x16x32_bf16 v[42:45], v[154:157], v[184:187], v[42:45]
	v_mfma_f32_16x16x32_bf16 v[22:25], v[134:137], v[192:195], v[22:25]
	v_mfma_f32_16x16x32_bf16 v[26:29], v[154:157], v[192:195], v[26:29]
	v_mfma_f32_16x16x32_bf16 v[10:13], v[134:137], v[200:203], v[10:13]
	v_mfma_f32_16x16x32_bf16 v[14:17], v[154:157], v[200:203], v[14:17]
	s_barrier
	s_add_u32 s54, s20, 0x40000
	s_addc_u32 s55, s21, 0
	s_add_i32 s53, s56, s27
	v_lshl_add_u64 v[130:131], s[54:55], 0, v[142:143]
	s_mov_b32 m0, s53
	s_nop 0
	global_load_lds_dwordx4 v[130:131], off
	v_lshl_add_u64 v[130:131], s[54:55], 0, v[138:139]
	s_add_i32 m0, s53, 0x2000
	s_nop 0
	global_load_lds_dwordx4 v[130:131], off
	s_waitcnt vmcnt(6)
	s_barrier
	v_mfma_f32_16x16x32_bf16 v[50:53], v[204:207], v[172:175], v[50:53]
	v_mfma_f32_16x16x32_bf16 v[62:65], v[212:215], v[172:175], v[62:65]
	v_mfma_f32_16x16x32_bf16 v[34:37], v[204:207], v[180:183], v[34:37]
	v_mfma_f32_16x16x32_bf16 v[46:49], v[212:215], v[180:183], v[46:49]
	v_mfma_f32_16x16x32_bf16 v[18:21], v[204:207], v[188:191], v[18:21]
	v_mfma_f32_16x16x32_bf16 v[30:33], v[212:215], v[188:191], v[30:33]
	v_mfma_f32_16x16x32_bf16 v[2:5], v[204:207], v[196:199], v[2:5]
	v_mfma_f32_16x16x32_bf16 v[6:9], v[212:215], v[196:199], v[6:9]
	v_mfma_f32_16x16x32_bf16 v[50:53], v[208:211], v[176:179], v[50:53]
	v_mfma_f32_16x16x32_bf16 v[62:65], v[216:219], v[176:179], v[62:65]
	v_mfma_f32_16x16x32_bf16 v[34:37], v[208:211], v[184:187], v[34:37]
	v_mfma_f32_16x16x32_bf16 v[46:49], v[216:219], v[184:187], v[46:49]
	v_mfma_f32_16x16x32_bf16 v[18:21], v[208:211], v[192:195], v[18:21]
	v_mfma_f32_16x16x32_bf16 v[30:33], v[216:219], v[192:195], v[30:33]
	v_mfma_f32_16x16x32_bf16 v[2:5], v[208:211], v[200:203], v[2:5]
	v_mfma_f32_16x16x32_bf16 v[6:9], v[216:219], v[200:203], v[6:9]
	s_add_i32 s53, 0, 0x18000
	v_add_u32_e32 v154, s53, v159
	s_barrier
	ds_read_b128 v[130:133], v154
	ds_read_b128 v[134:137], v154 offset:1024
	ds_read_b128 v[150:153], v154 offset:2048
	ds_read_b128 v[154:157], v154 offset:3072
	s_add_u32 s22, s22, 0x40000
	s_addc_u32 s23, s23, 0
	s_mov_b32 m0, s31
	v_lshl_add_u64 v[204:205], s[22:23], 0, v[144:145]
	ds_read_b128 v[172:175], v160 offset:32768
	ds_read_b128 v[176:179], v160 offset:33792
	ds_read_b128 v[180:183], v160 offset:34816
	ds_read_b128 v[184:187], v160 offset:35840
	ds_read_b128 v[188:191], v160 offset:36864
	ds_read_b128 v[192:195], v160 offset:37888
	ds_read_b128 v[196:199], v160 offset:38912
	ds_read_b128 v[200:203], v160 offset:39936
	global_load_lds_dwordx4 v[204:205], off
	v_lshl_add_u64 v[204:205], s[22:23], 0, v[140:141]
	s_mov_b32 m0, s34
	s_nop 0
	global_load_lds_dwordx4 v[204:205], off
	s_waitcnt lgkmcnt(8)
	s_barrier
	s_waitcnt lgkmcnt(0)
	s_waitcnt lgkmcnt(0)
	v_mfma_f32_16x16x32_bf16 v[118:121], v[130:133], v[172:175], v[118:121]
	v_mfma_f32_16x16x32_bf16 v[122:125], v[150:153], v[172:175], v[122:125]
	v_mfma_f32_16x16x32_bf16 v[102:105], v[130:133], v[180:183], v[102:105]
	v_mfma_f32_16x16x32_bf16 v[106:109], v[150:153], v[180:183], v[106:109]
	v_mfma_f32_16x16x32_bf16 v[86:89], v[130:133], v[188:191], v[86:89]
	v_mfma_f32_16x16x32_bf16 v[90:93], v[150:153], v[188:191], v[90:93]
	v_mfma_f32_16x16x32_bf16 v[70:73], v[130:133], v[196:199], v[70:73]
	v_mfma_f32_16x16x32_bf16 v[74:77], v[150:153], v[196:199], v[74:77]
	v_mfma_f32_16x16x32_bf16 v[118:121], v[134:137], v[176:179], v[118:121]
	v_mfma_f32_16x16x32_bf16 v[122:125], v[154:157], v[176:179], v[122:125]
	v_mfma_f32_16x16x32_bf16 v[102:105], v[134:137], v[184:187], v[102:105]
	v_mfma_f32_16x16x32_bf16 v[106:109], v[154:157], v[184:187], v[106:109]
	v_mfma_f32_16x16x32_bf16 v[86:89], v[134:137], v[192:195], v[86:89]
	v_mfma_f32_16x16x32_bf16 v[90:93], v[154:157], v[192:195], v[90:93]
	v_mfma_f32_16x16x32_bf16 v[70:73], v[134:137], v[200:203], v[70:73]
	v_mfma_f32_16x16x32_bf16 v[74:77], v[154:157], v[200:203], v[74:77]
	s_barrier
	s_add_i32 s22, 0, 0x1c000
	s_add_i32 s23, s53, s27
	v_add_u32_e32 v161, s22, v159
	v_lshl_add_u64 v[168:169], v[168:169], 0, s[84:85]
	s_mov_b32 m0, s23
	ds_read_b128 v[204:207], v161
	ds_read_b128 v[208:211], v161 offset:1024
	ds_read_b128 v[212:215], v161 offset:2048
	ds_read_b128 v[216:219], v161 offset:3072
	global_load_lds_dwordx4 v[168:169], off
	v_lshl_add_u64 v[168:169], v[220:221], 0, s[84:85]
	s_add_i32 m0, s23, 0x2000
	s_nop 0
	global_load_lds_dwordx4 v[168:169], off
	s_barrier
	s_waitcnt lgkmcnt(0)
	s_waitcnt lgkmcnt(0)
	v_mfma_f32_16x16x32_bf16 v[114:117], v[204:207], v[172:175], v[114:117]
	v_mfma_f32_16x16x32_bf16 v[126:129], v[212:215], v[172:175], v[126:129]
	v_mfma_f32_16x16x32_bf16 v[98:101], v[204:207], v[180:183], v[98:101]
	v_mfma_f32_16x16x32_bf16 v[110:113], v[212:215], v[180:183], v[110:113]
	v_mfma_f32_16x16x32_bf16 v[82:85], v[204:207], v[188:191], v[82:85]
	v_mfma_f32_16x16x32_bf16 v[94:97], v[212:215], v[188:191], v[94:97]
	v_mfma_f32_16x16x32_bf16 v[66:69], v[204:207], v[196:199], v[66:69]
	v_mfma_f32_16x16x32_bf16 v[78:81], v[212:215], v[196:199], v[78:81]
	v_mfma_f32_16x16x32_bf16 v[114:117], v[208:211], v[176:179], v[114:117]
	v_mfma_f32_16x16x32_bf16 v[126:129], v[216:219], v[176:179], v[126:129]
	v_mfma_f32_16x16x32_bf16 v[98:101], v[208:211], v[184:187], v[98:101]
	v_mfma_f32_16x16x32_bf16 v[110:113], v[216:219], v[184:187], v[110:113]
	v_mfma_f32_16x16x32_bf16 v[82:85], v[208:211], v[192:195], v[82:85]
	v_mfma_f32_16x16x32_bf16 v[94:97], v[216:219], v[192:195], v[94:97]
	v_mfma_f32_16x16x32_bf16 v[66:69], v[208:211], v[200:203], v[66:69]
	v_mfma_f32_16x16x32_bf16 v[78:81], v[216:219], v[200:203], v[78:81]
	s_mov_b32 m0, s42
	v_lshl_add_u64 v[168:169], v[236:237], 0, s[84:85]
	s_barrier
	ds_read_b128 v[172:175], v160 offset:49152
	ds_read_b128 v[176:179], v160 offset:50176
	ds_read_b128 v[180:183], v160 offset:51200
	ds_read_b128 v[184:187], v160 offset:52224
	ds_read_b128 v[188:191], v160 offset:53248
	ds_read_b128 v[192:195], v160 offset:54272
	ds_read_b128 v[196:199], v160 offset:55296
	ds_read_b128 v[200:203], v160 offset:56320
	global_load_lds_dwordx4 v[168:169], off
	v_lshl_add_u64 v[168:169], v[238:239], 0, s[84:85]
	s_mov_b32 m0, s43
	s_nop 0
	global_load_lds_dwordx4 v[168:169], off
	s_barrier
	s_waitcnt lgkmcnt(0)
	s_waitcnt lgkmcnt(0)
	v_mfma_f32_16x16x32_bf16 v[54:57], v[130:133], v[172:175], v[54:57]
	v_mfma_f32_16x16x32_bf16 v[58:61], v[150:153], v[172:175], v[58:61]
	v_mfma_f32_16x16x32_bf16 v[38:41], v[130:133], v[180:183], v[38:41]
	v_mfma_f32_16x16x32_bf16 v[42:45], v[150:153], v[180:183], v[42:45]
	v_mfma_f32_16x16x32_bf16 v[22:25], v[130:133], v[188:191], v[22:25]
	v_mfma_f32_16x16x32_bf16 v[26:29], v[150:153], v[188:191], v[26:29]
	v_mfma_f32_16x16x32_bf16 v[10:13], v[130:133], v[196:199], v[10:13]
	v_mfma_f32_16x16x32_bf16 v[14:17], v[150:153], v[196:199], v[14:17]
	v_mfma_f32_16x16x32_bf16 v[54:57], v[134:137], v[176:179], v[54:57]
	v_mfma_f32_16x16x32_bf16 v[58:61], v[154:157], v[176:179], v[58:61]
	v_mfma_f32_16x16x32_bf16 v[38:41], v[134:137], v[184:187], v[38:41]
	v_mfma_f32_16x16x32_bf16 v[42:45], v[154:157], v[184:187], v[42:45]
	v_mfma_f32_16x16x32_bf16 v[22:25], v[134:137], v[192:195], v[22:25]
	v_mfma_f32_16x16x32_bf16 v[26:29], v[154:157], v[192:195], v[26:29]
	v_mfma_f32_16x16x32_bf16 v[10:13], v[134:137], v[200:203], v[10:13]
	v_mfma_f32_16x16x32_bf16 v[14:17], v[154:157], v[200:203], v[14:17]
	s_barrier
	s_add_u32 s20, s20, 0x40080
	s_addc_u32 s21, s21, 0
	s_add_i32 s22, s22, s27
	v_lshl_add_u64 v[130:131], s[20:21], 0, v[142:143]
	s_mov_b32 m0, s22
	s_nop 0
	global_load_lds_dwordx4 v[130:131], off
	v_lshl_add_u64 v[130:131], s[20:21], 0, v[138:139]
	s_add_i32 m0, s22, 0x2000
	s_nop 0
	global_load_lds_dwordx4 v[130:131], off
	s_waitcnt vmcnt(6)
	s_barrier
	v_mfma_f32_16x16x32_bf16 v[50:53], v[204:207], v[172:175], v[50:53]
	v_mfma_f32_16x16x32_bf16 v[62:65], v[212:215], v[172:175], v[62:65]
	v_mfma_f32_16x16x32_bf16 v[34:37], v[204:207], v[180:183], v[34:37]
	v_mfma_f32_16x16x32_bf16 v[46:49], v[212:215], v[180:183], v[46:49]
	v_mfma_f32_16x16x32_bf16 v[18:21], v[204:207], v[188:191], v[18:21]
	v_mfma_f32_16x16x32_bf16 v[30:33], v[212:215], v[188:191], v[30:33]
	v_mfma_f32_16x16x32_bf16 v[2:5], v[204:207], v[196:199], v[2:5]
	v_mfma_f32_16x16x32_bf16 v[6:9], v[212:215], v[196:199], v[6:9]
	v_mfma_f32_16x16x32_bf16 v[50:53], v[208:211], v[176:179], v[50:53]
	v_mfma_f32_16x16x32_bf16 v[62:65], v[216:219], v[176:179], v[62:65]
	v_mfma_f32_16x16x32_bf16 v[34:37], v[208:211], v[184:187], v[34:37]
	v_mfma_f32_16x16x32_bf16 v[46:49], v[216:219], v[184:187], v[46:49]
	v_mfma_f32_16x16x32_bf16 v[18:21], v[208:211], v[192:195], v[18:21]
	v_mfma_f32_16x16x32_bf16 v[30:33], v[216:219], v[192:195], v[30:33]
	v_mfma_f32_16x16x32_bf16 v[2:5], v[208:211], v[200:203], v[2:5]
	v_mfma_f32_16x16x32_bf16 v[6:9], v[216:219], v[200:203], v[6:9]
	s_add_u32 s18, s18, 0x100
	s_addc_u32 s19, s19, 0
	s_add_u32 s50, s50, 0x100
	s_addc_u32 s51, s51, 0
	s_cmp_ge_i32 s52, s39
	s_mov_b32 s20, s52
	s_barrier
	s_cbranch_scc0 .LBB0_454

.LBB0_473:
	s_add_i32 s31, s10, 2
	s_add_u32 s6, s8, 0x100
	s_addc_u32 s7, s9, 0
	s_cmp_lg_u32 s30, s10
	s_cselect_b32 s10, s6, 0
	s_cselect_b32 s11, s7, 0
	s_add_u32 s12, s4, s10
	s_addc_u32 s13, s5, s11
	s_add_i32 s34, 0, 0x10000
	v_add_u32_e32 v106, s34, v92
	ds_read_b128 v[94:97], v106
	ds_read_b128 v[98:101], v106 offset:1024
	ds_read_b128 v[102:105], v106 offset:2048
	ds_read_b128 v[106:109], v106 offset:3072
	s_add_u32 s10, s2, s10
	s_addc_u32 s11, s3, s11
	v_lshl_add_u64 v[142:143], v[74:75], 0, s[8:9]
	s_add_i32 m0, s19, 0xc000
	ds_read_b128 v[110:113], v93
	ds_read_b128 v[114:117], v93 offset:1024
	ds_read_b128 v[118:121], v93 offset:2048
	ds_read_b128 v[122:125], v93 offset:3072
	ds_read_b128 v[126:129], v93 offset:4096
	ds_read_b128 v[130:133], v93 offset:5120
	ds_read_b128 v[134:137], v93 offset:6144
	ds_read_b128 v[138:141], v93 offset:7168
	global_load_lds_dwordx4 v[142:143], off
	v_lshl_add_u64 v[142:143], v[76:77], 0, s[8:9]
	s_add_i32 m0, s19, 0xe000
	s_nop 0
	global_load_lds_dwordx4 v[142:143], off
	s_waitcnt lgkmcnt(8)
	s_barrier
	s_waitcnt lgkmcnt(0)
	s_waitcnt lgkmcnt(0)
	v_mfma_f32_16x16x32_bf16 v[70:73], v[94:97], v[110:113], v[70:73]
	v_mfma_f32_16x16x32_bf16 v[66:69], v[102:105], v[110:113], v[66:69]
	v_mfma_f32_16x16x32_bf16 v[62:65], v[94:97], v[118:121], v[62:65]
	v_mfma_f32_16x16x32_bf16 v[58:61], v[102:105], v[118:121], v[58:61]
	v_mfma_f32_16x16x32_bf16 v[54:57], v[94:97], v[126:129], v[54:57]
	v_mfma_f32_16x16x32_bf16 v[50:53], v[102:105], v[126:129], v[50:53]
	v_mfma_f32_16x16x32_bf16 v[46:49], v[94:97], v[134:137], v[46:49]
	v_mfma_f32_16x16x32_bf16 v[42:45], v[102:105], v[134:137], v[42:45]
	v_mfma_f32_16x16x32_bf16 v[70:73], v[98:101], v[114:117], v[70:73]
	v_mfma_f32_16x16x32_bf16 v[66:69], v[106:109], v[114:117], v[66:69]
	v_mfma_f32_16x16x32_bf16 v[62:65], v[98:101], v[122:125], v[62:65]
	v_mfma_f32_16x16x32_bf16 v[58:61], v[106:109], v[122:125], v[58:61]
	v_mfma_f32_16x16x32_bf16 v[54:57], v[98:101], v[130:133], v[54:57]
	v_mfma_f32_16x16x32_bf16 v[50:53], v[106:109], v[130:133], v[50:53]
	v_mfma_f32_16x16x32_bf16 v[46:49], v[98:101], v[138:141], v[46:49]
	v_mfma_f32_16x16x32_bf16 v[42:45], v[106:109], v[138:141], v[42:45]
	s_barrier
	s_add_i32 s8, s34, s18
	v_lshl_add_u64 v[142:143], s[10:11], 0, v[16:17]
	s_mov_b32 m0, s8
	v_lshl_add_u64 v[144:145], s[10:11], 0, v[24:25]
	global_load_lds_dwordx4 v[142:143], off
	s_add_i32 m0, s8, 0x2000
	s_nop 0
	global_load_lds_dwordx4 v[144:145], off
	s_barrier
	s_waitcnt lgkmcnt(0)
	s_mov_b32 m0, s19
	v_lshl_add_u64 v[146:147], s[12:13], 0, v[14:15]
	s_barrier
	ds_read_b128 v[110:113], v93 offset:16384
	ds_read_b128 v[114:117], v93 offset:17408
	ds_read_b128 v[118:121], v93 offset:18432
	ds_read_b128 v[122:125], v93 offset:19456
	ds_read_b128 v[126:129], v93 offset:20480
	ds_read_b128 v[130:133], v93 offset:21504
	ds_read_b128 v[134:137], v93 offset:22528
	ds_read_b128 v[138:141], v93 offset:23552
	global_load_lds_dwordx4 v[146:147], off
	v_lshl_add_u64 v[148:149], s[12:13], 0, v[22:23]
	s_mov_b32 m0, s20
	s_nop 0
	global_load_lds_dwordx4 v[148:149], off
	s_barrier
	s_waitcnt lgkmcnt(0)
	s_waitcnt lgkmcnt(0)
	v_mfma_f32_16x16x32_bf16 v[38:41], v[94:97], v[110:113], v[38:41]
	v_mfma_f32_16x16x32_bf16 v[34:37], v[102:105], v[110:113], v[34:37]
	v_mfma_f32_16x16x32_bf16 v[30:33], v[94:97], v[118:121], v[30:33]
	v_mfma_f32_16x16x32_bf16 v[26:29], v[102:105], v[118:121], v[26:29]
	v_mfma_f32_16x16x32_bf16 v[18:21], v[94:97], v[126:129], v[18:21]
	v_mfma_f32_16x16x32_bf16 v[10:13], v[102:105], v[126:129], v[10:13]
	v_mfma_f32_16x16x32_bf16 v[6:9], v[94:97], v[134:137], v[6:9]
	v_mfma_f32_16x16x32_bf16 v[2:5], v[102:105], v[134:137], v[2:5]
	v_mfma_f32_16x16x32_bf16 v[38:41], v[98:101], v[114:117], v[38:41]
	v_mfma_f32_16x16x32_bf16 v[34:37], v[106:109], v[114:117], v[34:37]
	v_mfma_f32_16x16x32_bf16 v[30:33], v[98:101], v[122:125], v[30:33]
	v_mfma_f32_16x16x32_bf16 v[26:29], v[106:109], v[122:125], v[26:29]
	v_mfma_f32_16x16x32_bf16 v[18:21], v[98:101], v[130:133], v[18:21]
	v_mfma_f32_16x16x32_bf16 v[10:13], v[106:109], v[130:133], v[10:13]
	v_mfma_f32_16x16x32_bf16 v[6:9], v[98:101], v[138:141], v[6:9]
	v_mfma_f32_16x16x32_bf16 v[2:5], v[106:109], v[138:141], v[2:5]
	s_barrier
	s_add_u32 s8, s10, 0x80000
	s_addc_u32 s9, s11, 0
	s_mov_b32 m0, s21
	v_lshl_add_u64 v[94:95], s[8:9], 0, v[16:17]
	global_load_lds_dwordx4 v[94:95], off
	v_lshl_add_u64 v[94:95], s[8:9], 0, v[24:25]
	s_mov_b32 m0, s22
	s_nop 0
	global_load_lds_dwordx4 v[94:95], off
	s_waitcnt vmcnt(6)
	s_barrier
	s_add_i32 s34, 0, 0x18000
	v_add_u32_e32 v106, s34, v92
	s_barrier
	ds_read_b128 v[94:97], v106
	ds_read_b128 v[98:101], v106 offset:1024
	ds_read_b128 v[102:105], v106 offset:2048
	ds_read_b128 v[106:109], v106 offset:3072
	s_add_u32 s8, s12, 0x40000
	s_addc_u32 s9, s13, 0
	s_mov_b32 m0, s23
	v_lshl_add_u64 v[150:151], s[8:9], 0, v[14:15]
	ds_read_b128 v[110:113], v93 offset:32768
	ds_read_b128 v[114:117], v93 offset:33792
	ds_read_b128 v[118:121], v93 offset:34816
	ds_read_b128 v[122:125], v93 offset:35840
	ds_read_b128 v[126:129], v93 offset:36864
	ds_read_b128 v[130:133], v93 offset:37888
	ds_read_b128 v[134:137], v93 offset:38912
	ds_read_b128 v[138:141], v93 offset:39936
	global_load_lds_dwordx4 v[150:151], off
	v_lshl_add_u64 v[150:151], s[8:9], 0, v[22:23]
	s_mov_b32 m0, s24
	s_nop 0
	global_load_lds_dwordx4 v[150:151], off
	s_waitcnt lgkmcnt(8)
	s_barrier
	s_waitcnt lgkmcnt(0)
	s_waitcnt lgkmcnt(0)
	v_mfma_f32_16x16x32_bf16 v[70:73], v[94:97], v[110:113], v[70:73]
	v_mfma_f32_16x16x32_bf16 v[66:69], v[102:105], v[110:113], v[66:69]
	v_mfma_f32_16x16x32_bf16 v[62:65], v[94:97], v[118:121], v[62:65]
	v_mfma_f32_16x16x32_bf16 v[58:61], v[102:105], v[118:121], v[58:61]
	v_mfma_f32_16x16x32_bf16 v[54:57], v[94:97], v[126:129], v[54:57]
	v_mfma_f32_16x16x32_bf16 v[50:53], v[102:105], v[126:129], v[50:53]
	v_mfma_f32_16x16x32_bf16 v[46:49], v[94:97], v[134:137], v[46:49]
	v_mfma_f32_16x16x32_bf16 v[42:45], v[102:105], v[134:137], v[42:45]
	v_mfma_f32_16x16x32_bf16 v[70:73], v[98:101], v[114:117], v[70:73]
	v_mfma_f32_16x16x32_bf16 v[66:69], v[106:109], v[114:117], v[66:69]
	v_mfma_f32_16x16x32_bf16 v[62:65], v[98:101], v[122:125], v[62:65]
	v_mfma_f32_16x16x32_bf16 v[58:61], v[106:109], v[122:125], v[58:61]
	v_mfma_f32_16x16x32_bf16 v[54:57], v[98:101], v[130:133], v[54:57]
	v_mfma_f32_16x16x32_bf16 v[50:53], v[106:109], v[130:133], v[50:53]
	v_mfma_f32_16x16x32_bf16 v[46:49], v[98:101], v[138:141], v[46:49]
	v_mfma_f32_16x16x32_bf16 v[42:45], v[106:109], v[138:141], v[42:45]
	s_barrier
	s_add_i32 s8, s34, s18
	v_lshl_add_u64 v[110:111], v[142:143], 0, s[84:85]
	s_mov_b32 m0, s8
	s_nop 0
	global_load_lds_dwordx4 v[110:111], off
	v_lshl_add_u64 v[110:111], v[144:145], 0, s[84:85]
	s_add_i32 m0, s8, 0x2000
	s_nop 0
	global_load_lds_dwordx4 v[110:111], off
	s_barrier
	s_waitcnt lgkmcnt(0)
	s_mov_b32 m0, s25
	v_lshl_add_u64 v[142:143], v[146:147], 0, s[84:85]
	s_barrier
	ds_read_b128 v[110:113], v93 offset:49152
	ds_read_b128 v[114:117], v93 offset:50176
	ds_read_b128 v[118:121], v93 offset:51200
	ds_read_b128 v[122:125], v93 offset:52224
	ds_read_b128 v[126:129], v93 offset:53248
	ds_read_b128 v[130:133], v93 offset:54272
	ds_read_b128 v[134:137], v93 offset:55296
	ds_read_b128 v[138:141], v93 offset:56320
	global_load_lds_dwordx4 v[142:143], off
	v_lshl_add_u64 v[142:143], v[148:149], 0, s[84:85]
	s_mov_b32 m0, s26
	s_nop 0
	global_load_lds_dwordx4 v[142:143], off
	s_barrier
	s_waitcnt lgkmcnt(0)
	s_waitcnt lgkmcnt(0)
	v_mfma_f32_16x16x32_bf16 v[38:41], v[94:97], v[110:113], v[38:41]
	v_mfma_f32_16x16x32_bf16 v[34:37], v[102:105], v[110:113], v[34:37]
	v_mfma_f32_16x16x32_bf16 v[30:33], v[94:97], v[118:121], v[30:33]
	v_mfma_f32_16x16x32_bf16 v[26:29], v[102:105], v[118:121], v[26:29]
	v_mfma_f32_16x16x32_bf16 v[18:21], v[94:97], v[126:129], v[18:21]
	v_mfma_f32_16x16x32_bf16 v[10:13], v[102:105], v[126:129], v[10:13]
	v_mfma_f32_16x16x32_bf16 v[6:9], v[94:97], v[134:137], v[6:9]
	v_mfma_f32_16x16x32_bf16 v[2:5], v[102:105], v[134:137], v[2:5]
	v_mfma_f32_16x16x32_bf16 v[38:41], v[98:101], v[114:117], v[38:41]
	v_mfma_f32_16x16x32_bf16 v[34:37], v[106:109], v[114:117], v[34:37]
	v_mfma_f32_16x16x32_bf16 v[30:33], v[98:101], v[122:125], v[30:33]
	v_mfma_f32_16x16x32_bf16 v[26:29], v[106:109], v[122:125], v[26:29]
	v_mfma_f32_16x16x32_bf16 v[18:21], v[98:101], v[130:133], v[18:21]
	v_mfma_f32_16x16x32_bf16 v[10:13], v[106:109], v[130:133], v[10:13]
	v_mfma_f32_16x16x32_bf16 v[6:9], v[98:101], v[138:141], v[6:9]
	v_mfma_f32_16x16x32_bf16 v[2:5], v[106:109], v[138:141], v[2:5]
	s_barrier
	s_add_u32 s8, s10, 0x80080
	s_addc_u32 s9, s11, 0
	s_mov_b32 m0, s27
	v_lshl_add_u64 v[94:95], s[8:9], 0, v[16:17]
	global_load_lds_dwordx4 v[94:95], off
	v_lshl_add_u64 v[94:95], s[8:9], 0, v[24:25]
	s_mov_b32 m0, s28
	s_nop 0
	global_load_lds_dwordx4 v[94:95], off
	s_waitcnt vmcnt(6)
	s_barrier
	s_cmp_ge_i32 s31, s29
	s_mov_b64 s[8:9], s[6:7]
	s_mov_b32 s10, s31
	s_barrier
	s_cbranch_scc0 .LBB0_473

.LBB0_500:
	s_add_i32 s47, s10, 2
	s_add_u32 s11, s8, 0x4000
	s_addc_u32 s12, s9, 0
	s_cmp_eq_u32 s35, s10
	s_cselect_b32 s14, s0, s11
	s_cselect_b32 s15, s1, s12
	s_cselect_b32 s10, s2, s45
	s_cselect_b32 s11, s3, s46
	s_add_u32 s12, s14, 0x8000
	s_addc_u32 s13, s15, 0
	s_add_i32 s48, 0, 0x10000
	v_add_u32_e32 v122, s48, v206
	ds_read_b128 v[98:101], v122
	ds_read_b128 v[106:109], v122 offset:1024
	ds_read_b128 v[114:117], v122 offset:2048
	ds_read_b128 v[122:125], v122 offset:3072
	v_lshl_add_u64 v[168:169], s[8:9], 0, v[158:159]
	s_add_i32 m0, s20, 0xc000
	ds_read_b128 v[146:149], v207
	ds_read_b128 v[150:153], v207 offset:1024
	ds_read_b128 v[154:157], v207 offset:2048
	ds_read_b128 v[176:179], v207 offset:3072
	ds_read_b128 v[180:183], v207 offset:4096
	ds_read_b128 v[184:187], v207 offset:5120
	ds_read_b128 v[188:191], v207 offset:6144
	ds_read_b128 v[192:195], v207 offset:7168
	global_load_lds_dwordx4 v[168:169], off
	v_lshl_add_u64 v[168:169], s[8:9], 0, v[172:173]
	s_add_i32 m0, s20, 0xe000
	s_nop 0
	global_load_lds_dwordx4 v[168:169], off
	s_waitcnt lgkmcnt(8)
	s_barrier
	s_waitcnt lgkmcnt(0)
	s_waitcnt lgkmcnt(0)
	v_mfma_f32_16x16x32_bf16 v[142:145], v[98:101], v[146:149], v[142:145]
	v_mfma_f32_16x16x32_bf16 v[138:141], v[114:117], v[146:149], v[138:141]
	v_mfma_f32_16x16x32_bf16 v[126:129], v[98:101], v[154:157], v[126:129]
	v_mfma_f32_16x16x32_bf16 v[118:121], v[114:117], v[154:157], v[118:121]
	v_mfma_f32_16x16x32_bf16 v[94:97], v[98:101], v[180:183], v[94:97]
	v_mfma_f32_16x16x32_bf16 v[90:93], v[114:117], v[180:183], v[90:93]
	v_mfma_f32_16x16x32_bf16 v[78:81], v[98:101], v[188:191], v[78:81]
	v_mfma_f32_16x16x32_bf16 v[74:77], v[114:117], v[188:191], v[74:77]
	v_mfma_f32_16x16x32_bf16 v[142:145], v[106:109], v[150:153], v[142:145]
	v_mfma_f32_16x16x32_bf16 v[138:141], v[122:125], v[150:153], v[138:141]
	v_mfma_f32_16x16x32_bf16 v[126:129], v[106:109], v[176:179], v[126:129]
	v_mfma_f32_16x16x32_bf16 v[118:121], v[122:125], v[176:179], v[118:121]
	v_mfma_f32_16x16x32_bf16 v[94:97], v[106:109], v[184:187], v[94:97]
	v_mfma_f32_16x16x32_bf16 v[90:93], v[122:125], v[184:187], v[90:93]
	v_mfma_f32_16x16x32_bf16 v[78:81], v[106:109], v[192:195], v[78:81]
	v_mfma_f32_16x16x32_bf16 v[74:77], v[122:125], v[192:195], v[74:77]
	s_barrier
	s_add_i32 s50, 0, 0x14000
	v_add_u32_e32 v168, s50, v206
	s_add_i32 s48, s48, s19
	ds_read_b128 v[196:199], v168
	ds_read_b128 v[200:203], v168 offset:1024
	ds_read_b128 v[208:211], v168 offset:2048
	ds_read_b128 v[212:215], v168 offset:3072
	v_lshl_add_u64 v[168:169], s[10:11], 0, v[160:161]
	s_mov_b32 m0, s48
	v_lshl_add_u64 v[204:205], s[10:11], 0, v[174:175]
	global_load_lds_dwordx4 v[168:169], off
	s_add_i32 m0, s48, 0x2000
	s_nop 0
	global_load_lds_dwordx4 v[204:205], off
	s_barrier
	s_waitcnt lgkmcnt(0)
	s_waitcnt lgkmcnt(0)
	v_mfma_f32_16x16x32_bf16 v[134:137], v[196:199], v[146:149], v[134:137]
	v_mfma_f32_16x16x32_bf16 v[130:133], v[208:211], v[146:149], v[130:133]
	v_mfma_f32_16x16x32_bf16 v[110:113], v[196:199], v[154:157], v[110:113]
	v_mfma_f32_16x16x32_bf16 v[102:105], v[208:211], v[154:157], v[102:105]
	v_mfma_f32_16x16x32_bf16 v[86:89], v[196:199], v[180:183], v[86:89]
	v_mfma_f32_16x16x32_bf16 v[82:85], v[208:211], v[180:183], v[82:85]
	v_mfma_f32_16x16x32_bf16 v[70:73], v[196:199], v[188:191], v[70:73]
	v_mfma_f32_16x16x32_bf16 v[66:69], v[208:211], v[188:191], v[66:69]
	v_mfma_f32_16x16x32_bf16 v[134:137], v[200:203], v[150:153], v[134:137]
	v_mfma_f32_16x16x32_bf16 v[130:133], v[212:215], v[150:153], v[130:133]
	v_mfma_f32_16x16x32_bf16 v[110:113], v[200:203], v[176:179], v[110:113]
	v_mfma_f32_16x16x32_bf16 v[102:105], v[212:215], v[176:179], v[102:105]
	v_mfma_f32_16x16x32_bf16 v[86:89], v[200:203], v[184:187], v[86:89]
	v_mfma_f32_16x16x32_bf16 v[82:85], v[212:215], v[184:187], v[82:85]
	v_mfma_f32_16x16x32_bf16 v[70:73], v[200:203], v[192:195], v[70:73]
	v_mfma_f32_16x16x32_bf16 v[66:69], v[212:215], v[192:195], v[66:69]
	s_mov_b32 m0, s20
	v_lshl_add_u64 v[216:217], s[14:15], 0, v[158:159]
	s_barrier
	ds_read_b128 v[146:149], v207 offset:16384
	ds_read_b128 v[150:153], v207 offset:17408
	ds_read_b128 v[154:157], v207 offset:18432
	ds_read_b128 v[176:179], v207 offset:19456
	ds_read_b128 v[180:183], v207 offset:20480
	ds_read_b128 v[184:187], v207 offset:21504
	ds_read_b128 v[188:191], v207 offset:22528
	ds_read_b128 v[192:195], v207 offset:23552
	global_load_lds_dwordx4 v[216:217], off
	v_lshl_add_u64 v[216:217], s[14:15], 0, v[172:173]
	s_mov_b32 m0, s21
	s_nop 0
	global_load_lds_dwordx4 v[216:217], off
	s_barrier
	s_waitcnt lgkmcnt(0)
	s_waitcnt lgkmcnt(0)
	v_mfma_f32_16x16x32_bf16 v[62:65], v[98:101], v[146:149], v[62:65]
	v_mfma_f32_16x16x32_bf16 v[58:61], v[114:117], v[146:149], v[58:61]
	v_mfma_f32_16x16x32_bf16 v[46:49], v[98:101], v[154:157], v[46:49]
	v_mfma_f32_16x16x32_bf16 v[42:45], v[114:117], v[154:157], v[42:45]
	v_mfma_f32_16x16x32_bf16 v[30:33], v[98:101], v[180:183], v[30:33]
	v_mfma_f32_16x16x32_bf16 v[26:29], v[114:117], v[180:183], v[26:29]
	v_mfma_f32_16x16x32_bf16 v[14:17], v[98:101], v[188:191], v[14:17]
	v_mfma_f32_16x16x32_bf16 v[10:13], v[114:117], v[188:191], v[10:13]
	v_mfma_f32_16x16x32_bf16 v[62:65], v[106:109], v[150:153], v[62:65]
	v_mfma_f32_16x16x32_bf16 v[58:61], v[122:125], v[150:153], v[58:61]
	v_mfma_f32_16x16x32_bf16 v[46:49], v[106:109], v[176:179], v[46:49]
	v_mfma_f32_16x16x32_bf16 v[42:45], v[122:125], v[176:179], v[42:45]
	v_mfma_f32_16x16x32_bf16 v[30:33], v[106:109], v[184:187], v[30:33]
	v_mfma_f32_16x16x32_bf16 v[26:29], v[122:125], v[184:187], v[26:29]
	v_mfma_f32_16x16x32_bf16 v[14:17], v[106:109], v[192:195], v[14:17]
	v_mfma_f32_16x16x32_bf16 v[10:13], v[122:125], v[192:195], v[10:13]
	s_barrier
	s_add_u32 s48, s10, 0xb0000
	s_addc_u32 s49, s11, 0
	s_add_i32 s50, s50, s19
	v_lshl_add_u64 v[98:99], s[48:49], 0, v[160:161]
	s_mov_b32 m0, s50
	s_nop 0
	global_load_lds_dwordx4 v[98:99], off
	v_lshl_add_u64 v[98:99], s[48:49], 0, v[174:175]
	s_add_i32 m0, s50, 0x2000
	s_nop 0
	global_load_lds_dwordx4 v[98:99], off
	s_waitcnt vmcnt(6)
	s_barrier
	v_mfma_f32_16x16x32_bf16 v[54:57], v[196:199], v[146:149], v[54:57]
	v_mfma_f32_16x16x32_bf16 v[50:53], v[208:211], v[146:149], v[50:53]
	v_mfma_f32_16x16x32_bf16 v[38:41], v[196:199], v[154:157], v[38:41]
	v_mfma_f32_16x16x32_bf16 v[34:37], v[208:211], v[154:157], v[34:37]
	v_mfma_f32_16x16x32_bf16 v[22:25], v[196:199], v[180:183], v[22:25]
	v_mfma_f32_16x16x32_bf16 v[18:21], v[208:211], v[180:183], v[18:21]
	v_mfma_f32_16x16x32_bf16 v[6:9], v[196:199], v[188:191], v[6:9]
	v_mfma_f32_16x16x32_bf16 v[2:5], v[208:211], v[188:191], v[2:5]
	v_mfma_f32_16x16x32_bf16 v[54:57], v[200:203], v[150:153], v[54:57]
	v_mfma_f32_16x16x32_bf16 v[50:53], v[212:215], v[150:153], v[50:53]
	v_mfma_f32_16x16x32_bf16 v[38:41], v[200:203], v[176:179], v[38:41]
	v_mfma_f32_16x16x32_bf16 v[34:37], v[212:215], v[176:179], v[34:37]
	v_mfma_f32_16x16x32_bf16 v[22:25], v[200:203], v[184:187], v[22:25]
	v_mfma_f32_16x16x32_bf16 v[18:21], v[212:215], v[184:187], v[18:21]
	v_mfma_f32_16x16x32_bf16 v[6:9], v[200:203], v[192:195], v[6:9]
	v_mfma_f32_16x16x32_bf16 v[2:5], v[212:215], v[192:195], v[2:5]
	s_add_i32 s48, 0, 0x18000
	v_add_u32_e32 v122, s48, v206
	s_barrier
	ds_read_b128 v[98:101], v122
	ds_read_b128 v[106:109], v122 offset:1024
	ds_read_b128 v[114:117], v122 offset:2048
	ds_read_b128 v[122:125], v122 offset:3072
	s_add_u32 s14, s14, 0x4000
	s_addc_u32 s15, s15, 0
	s_mov_b32 m0, s22
	v_lshl_add_u64 v[196:197], s[14:15], 0, v[158:159]
	ds_read_b128 v[146:149], v207 offset:32768
	ds_read_b128 v[150:153], v207 offset:33792
	ds_read_b128 v[154:157], v207 offset:34816
	ds_read_b128 v[176:179], v207 offset:35840
	ds_read_b128 v[180:183], v207 offset:36864
	ds_read_b128 v[184:187], v207 offset:37888
	ds_read_b128 v[188:191], v207 offset:38912
	ds_read_b128 v[192:195], v207 offset:39936
	global_load_lds_dwordx4 v[196:197], off
	v_lshl_add_u64 v[196:197], s[14:15], 0, v[172:173]
	s_mov_b32 m0, s23
	s_nop 0
	global_load_lds_dwordx4 v[196:197], off
	s_waitcnt lgkmcnt(8)
	s_barrier
	s_waitcnt lgkmcnt(0)
	s_waitcnt lgkmcnt(0)
	v_mfma_f32_16x16x32_bf16 v[142:145], v[98:101], v[146:149], v[142:145]
	v_mfma_f32_16x16x32_bf16 v[138:141], v[114:117], v[146:149], v[138:141]
	v_mfma_f32_16x16x32_bf16 v[126:129], v[98:101], v[154:157], v[126:129]
	v_mfma_f32_16x16x32_bf16 v[118:121], v[114:117], v[154:157], v[118:121]
	v_mfma_f32_16x16x32_bf16 v[94:97], v[98:101], v[180:183], v[94:97]
	v_mfma_f32_16x16x32_bf16 v[90:93], v[114:117], v[180:183], v[90:93]
	v_mfma_f32_16x16x32_bf16 v[78:81], v[98:101], v[188:191], v[78:81]
	v_mfma_f32_16x16x32_bf16 v[74:77], v[114:117], v[188:191], v[74:77]
	v_mfma_f32_16x16x32_bf16 v[142:145], v[106:109], v[150:153], v[142:145]
	v_mfma_f32_16x16x32_bf16 v[138:141], v[122:125], v[150:153], v[138:141]
	v_mfma_f32_16x16x32_bf16 v[126:129], v[106:109], v[176:179], v[126:129]
	v_mfma_f32_16x16x32_bf16 v[118:121], v[122:125], v[176:179], v[118:121]
	v_mfma_f32_16x16x32_bf16 v[94:97], v[106:109], v[184:187], v[94:97]
	v_mfma_f32_16x16x32_bf16 v[90:93], v[122:125], v[184:187], v[90:93]
	v_mfma_f32_16x16x32_bf16 v[78:81], v[106:109], v[192:195], v[78:81]
	v_mfma_f32_16x16x32_bf16 v[74:77], v[122:125], v[192:195], v[74:77]
	s_barrier
	s_add_i32 s14, 0, 0x1c000
	s_add_i32 s15, s48, s19
	v_add_u32_e32 v212, s14, v206
	v_lshl_add_u64 v[168:169], v[168:169], 0, s[84:85]
	s_mov_b32 m0, s15
	ds_read_b128 v[196:199], v212
	ds_read_b128 v[200:203], v212 offset:1024
	ds_read_b128 v[208:211], v212 offset:2048
	ds_read_b128 v[212:215], v212 offset:3072
	global_load_lds_dwordx4 v[168:169], off
	v_lshl_add_u64 v[168:169], v[204:205], 0, s[84:85]
	s_add_i32 m0, s15, 0x2000
	s_nop 0
	global_load_lds_dwordx4 v[168:169], off
	s_barrier
	s_waitcnt lgkmcnt(0)
	s_waitcnt lgkmcnt(0)
	v_mfma_f32_16x16x32_bf16 v[134:137], v[196:199], v[146:149], v[134:137]
	v_mfma_f32_16x16x32_bf16 v[130:133], v[208:211], v[146:149], v[130:133]
	v_mfma_f32_16x16x32_bf16 v[110:113], v[196:199], v[154:157], v[110:113]
	v_mfma_f32_16x16x32_bf16 v[102:105], v[208:211], v[154:157], v[102:105]
	v_mfma_f32_16x16x32_bf16 v[86:89], v[196:199], v[180:183], v[86:89]
	v_mfma_f32_16x16x32_bf16 v[82:85], v[208:211], v[180:183], v[82:85]
	v_mfma_f32_16x16x32_bf16 v[70:73], v[196:199], v[188:191], v[70:73]
	v_mfma_f32_16x16x32_bf16 v[66:69], v[208:211], v[188:191], v[66:69]
	v_mfma_f32_16x16x32_bf16 v[134:137], v[200:203], v[150:153], v[134:137]
	v_mfma_f32_16x16x32_bf16 v[130:133], v[212:215], v[150:153], v[130:133]
	v_mfma_f32_16x16x32_bf16 v[110:113], v[200:203], v[176:179], v[110:113]
	v_mfma_f32_16x16x32_bf16 v[102:105], v[212:215], v[176:179], v[102:105]
	v_mfma_f32_16x16x32_bf16 v[86:89], v[200:203], v[184:187], v[86:89]
	v_mfma_f32_16x16x32_bf16 v[82:85], v[212:215], v[184:187], v[82:85]
	v_mfma_f32_16x16x32_bf16 v[70:73], v[200:203], v[192:195], v[70:73]
	v_mfma_f32_16x16x32_bf16 v[66:69], v[212:215], v[192:195], v[66:69]
	s_mov_b32 m0, s31
	v_lshl_add_u64 v[168:169], s[12:13], 0, v[158:159]
	s_barrier
	ds_read_b128 v[146:149], v207 offset:49152
	ds_read_b128 v[150:153], v207 offset:50176
	ds_read_b128 v[154:157], v207 offset:51200
	ds_read_b128 v[176:179], v207 offset:52224
	ds_read_b128 v[180:183], v207 offset:53248
	ds_read_b128 v[184:187], v207 offset:54272
	ds_read_b128 v[188:191], v207 offset:55296
	ds_read_b128 v[192:195], v207 offset:56320
	global_load_lds_dwordx4 v[168:169], off
	v_lshl_add_u64 v[168:169], s[12:13], 0, v[172:173]
	s_mov_b32 m0, s34
	s_nop 0
	global_load_lds_dwordx4 v[168:169], off
	s_barrier
	s_waitcnt lgkmcnt(0)
	s_waitcnt lgkmcnt(0)
	v_mfma_f32_16x16x32_bf16 v[62:65], v[98:101], v[146:149], v[62:65]
	v_mfma_f32_16x16x32_bf16 v[58:61], v[114:117], v[146:149], v[58:61]
	v_mfma_f32_16x16x32_bf16 v[46:49], v[98:101], v[154:157], v[46:49]
	v_mfma_f32_16x16x32_bf16 v[42:45], v[114:117], v[154:157], v[42:45]
	v_mfma_f32_16x16x32_bf16 v[30:33], v[98:101], v[180:183], v[30:33]
	v_mfma_f32_16x16x32_bf16 v[26:29], v[114:117], v[180:183], v[26:29]
	v_mfma_f32_16x16x32_bf16 v[14:17], v[98:101], v[188:191], v[14:17]
	v_mfma_f32_16x16x32_bf16 v[10:13], v[114:117], v[188:191], v[10:13]
	v_mfma_f32_16x16x32_bf16 v[62:65], v[106:109], v[150:153], v[62:65]
	v_mfma_f32_16x16x32_bf16 v[58:61], v[122:125], v[150:153], v[58:61]
	v_mfma_f32_16x16x32_bf16 v[46:49], v[106:109], v[176:179], v[46:49]
	v_mfma_f32_16x16x32_bf16 v[42:45], v[122:125], v[176:179], v[42:45]
	v_mfma_f32_16x16x32_bf16 v[30:33], v[106:109], v[184:187], v[30:33]
	v_mfma_f32_16x16x32_bf16 v[26:29], v[122:125], v[184:187], v[26:29]
	v_mfma_f32_16x16x32_bf16 v[14:17], v[106:109], v[192:195], v[14:17]
	v_mfma_f32_16x16x32_bf16 v[10:13], v[122:125], v[192:195], v[10:13]
	s_barrier
	s_add_u32 s10, s10, 0xb0080
	s_addc_u32 s11, s11, 0
	s_add_i32 s12, s14, s19
	v_lshl_add_u64 v[98:99], s[10:11], 0, v[160:161]
	s_mov_b32 m0, s12
	s_nop 0
	global_load_lds_dwordx4 v[98:99], off
	v_lshl_add_u64 v[98:99], s[10:11], 0, v[174:175]
	s_add_i32 m0, s12, 0x2000
	s_nop 0
	global_load_lds_dwordx4 v[98:99], off
	s_waitcnt vmcnt(6)
	s_barrier
	v_mfma_f32_16x16x32_bf16 v[54:57], v[196:199], v[146:149], v[54:57]
	v_mfma_f32_16x16x32_bf16 v[50:53], v[208:211], v[146:149], v[50:53]
	v_mfma_f32_16x16x32_bf16 v[38:41], v[196:199], v[154:157], v[38:41]
	v_mfma_f32_16x16x32_bf16 v[34:37], v[208:211], v[154:157], v[34:37]
	v_mfma_f32_16x16x32_bf16 v[22:25], v[196:199], v[180:183], v[22:25]
	v_mfma_f32_16x16x32_bf16 v[18:21], v[208:211], v[180:183], v[18:21]
	v_mfma_f32_16x16x32_bf16 v[6:9], v[196:199], v[188:191], v[6:9]
	v_mfma_f32_16x16x32_bf16 v[2:5], v[208:211], v[188:191], v[2:5]
	v_mfma_f32_16x16x32_bf16 v[54:57], v[200:203], v[150:153], v[54:57]
	v_mfma_f32_16x16x32_bf16 v[50:53], v[212:215], v[150:153], v[50:53]
	v_mfma_f32_16x16x32_bf16 v[38:41], v[200:203], v[176:179], v[38:41]
	v_mfma_f32_16x16x32_bf16 v[34:37], v[212:215], v[176:179], v[34:37]
	v_mfma_f32_16x16x32_bf16 v[22:25], v[200:203], v[184:187], v[22:25]
	v_mfma_f32_16x16x32_bf16 v[18:21], v[212:215], v[184:187], v[18:21]
	v_mfma_f32_16x16x32_bf16 v[6:9], v[200:203], v[192:195], v[6:9]
	v_mfma_f32_16x16x32_bf16 v[2:5], v[212:215], v[192:195], v[2:5]
	s_add_u32 s45, s45, 0x100
	s_addc_u32 s46, s46, 0
	s_add_u32 s8, s8, 0x10000
	s_addc_u32 s9, s9, 0
	s_cmp_ge_i32 s47, s28
	s_mov_b32 s10, s47
	s_barrier
	s_cbranch_scc0 .LBB0_500

.LBB0_534:
	s_add_i32 s57, s22, 2
	s_add_u32 s23, s20, 0xfffc0080
	s_addc_u32 s24, s21, -1
	s_add_i32 s58, 0, 0x10000
	v_add_u32_e32 v62, s58, v214
	ds_read_b128 v[34:37], v62
	ds_read_b128 v[38:41], v62 offset:1024
	ds_read_b128 v[58:61], v62 offset:2048
	ds_read_b128 v[62:65], v62 offset:3072
	s_cmp_eq_u32 s49, s22
	s_cselect_b32 s22, s38, s39
	s_cselect_b32 s25, s11, s24
	s_cselect_b32 s24, s13, s23
	s_cselect_b32 s23, s19, s56
	v_lshl_add_u64 v[168:169], s[20:21], 0, v[180:181]
	s_add_i32 m0, s35, 0xc000
	ds_read_b128 v[146:149], v215
	ds_read_b128 v[150:153], v215 offset:1024
	ds_read_b128 v[154:157], v215 offset:2048
	ds_read_b128 v[158:161], v215 offset:3072
	ds_read_b128 v[184:187], v215 offset:4096
	ds_read_b128 v[188:191], v215 offset:5120
	ds_read_b128 v[192:195], v215 offset:6144
	ds_read_b128 v[196:199], v215 offset:7168
	global_load_lds_dwordx4 v[168:169], off
	v_lshl_add_u64 v[168:169], s[20:21], 0, v[182:183]
	s_add_i32 m0, s35, 0xe000
	s_nop 0
	global_load_lds_dwordx4 v[168:169], off
	s_waitcnt lgkmcnt(8)
	s_barrier
	s_waitcnt lgkmcnt(0)
	s_waitcnt lgkmcnt(0)
	v_mfma_f32_16x16x32_bf16 v[142:145], v[34:37], v[146:149], v[142:145]
	v_mfma_f32_16x16x32_bf16 v[134:137], v[58:61], v[146:149], v[134:137]
	v_mfma_f32_16x16x32_bf16 v[126:129], v[34:37], v[154:157], v[126:129]
	v_mfma_f32_16x16x32_bf16 v[118:121], v[58:61], v[154:157], v[118:121]
	v_mfma_f32_16x16x32_bf16 v[110:113], v[34:37], v[184:187], v[110:113]
	v_mfma_f32_16x16x32_bf16 v[102:105], v[58:61], v[184:187], v[102:105]
	v_mfma_f32_16x16x32_bf16 v[94:97], v[34:37], v[192:195], v[94:97]
	v_mfma_f32_16x16x32_bf16 v[86:89], v[58:61], v[192:195], v[86:89]
	v_mfma_f32_16x16x32_bf16 v[142:145], v[38:41], v[150:153], v[142:145]
	v_mfma_f32_16x16x32_bf16 v[134:137], v[62:65], v[150:153], v[134:137]
	v_mfma_f32_16x16x32_bf16 v[126:129], v[38:41], v[158:161], v[126:129]
	v_mfma_f32_16x16x32_bf16 v[118:121], v[62:65], v[158:161], v[118:121]
	v_mfma_f32_16x16x32_bf16 v[110:113], v[38:41], v[188:191], v[110:113]
	v_mfma_f32_16x16x32_bf16 v[102:105], v[62:65], v[188:191], v[102:105]
	v_mfma_f32_16x16x32_bf16 v[94:97], v[38:41], v[196:199], v[94:97]
	v_mfma_f32_16x16x32_bf16 v[86:89], v[62:65], v[196:199], v[86:89]
	s_barrier
	s_add_i32 s60, 0, 0x14000
	v_add_u32_e32 v168, s60, v214
	s_add_i32 s58, s58, s31
	ds_read_b128 v[200:203], v168
	ds_read_b128 v[204:207], v168 offset:1024
	ds_read_b128 v[208:211], v168 offset:2048
	ds_read_b128 v[216:219], v168 offset:3072
	v_lshl_add_u64 v[168:169], s[22:23], 0, v[176:177]
	s_mov_b32 m0, s58
	v_lshl_add_u64 v[220:221], s[22:23], 0, v[172:173]
	global_load_lds_dwordx4 v[168:169], off
	s_add_i32 m0, s58, 0x2000
	s_nop 0
	global_load_lds_dwordx4 v[220:221], off
	s_barrier
	s_waitcnt lgkmcnt(0)
	s_waitcnt lgkmcnt(0)
	v_mfma_f32_16x16x32_bf16 v[138:141], v[200:203], v[146:149], v[138:141]
	v_mfma_f32_16x16x32_bf16 v[130:133], v[208:211], v[146:149], v[130:133]
	v_mfma_f32_16x16x32_bf16 v[122:125], v[200:203], v[154:157], v[122:125]
	v_mfma_f32_16x16x32_bf16 v[114:117], v[208:211], v[154:157], v[114:117]
	v_mfma_f32_16x16x32_bf16 v[106:109], v[200:203], v[184:187], v[106:109]
	v_mfma_f32_16x16x32_bf16 v[98:101], v[208:211], v[184:187], v[98:101]
	v_mfma_f32_16x16x32_bf16 v[90:93], v[200:203], v[192:195], v[90:93]
	v_mfma_f32_16x16x32_bf16 v[82:85], v[208:211], v[192:195], v[82:85]
	v_mfma_f32_16x16x32_bf16 v[138:141], v[204:207], v[150:153], v[138:141]
	v_mfma_f32_16x16x32_bf16 v[130:133], v[216:219], v[150:153], v[130:133]
	v_mfma_f32_16x16x32_bf16 v[122:125], v[204:207], v[158:161], v[122:125]
	v_mfma_f32_16x16x32_bf16 v[114:117], v[216:219], v[158:161], v[114:117]
	v_mfma_f32_16x16x32_bf16 v[106:109], v[204:207], v[188:191], v[106:109]
	v_mfma_f32_16x16x32_bf16 v[98:101], v[216:219], v[188:191], v[98:101]
	v_mfma_f32_16x16x32_bf16 v[90:93], v[204:207], v[196:199], v[90:93]
	v_mfma_f32_16x16x32_bf16 v[82:85], v[216:219], v[196:199], v[82:85]
	s_mov_b32 m0, s35
	v_lshl_add_u64 v[236:237], s[24:25], 0, v[178:179]
	s_barrier
	ds_read_b128 v[146:149], v215 offset:16384
	ds_read_b128 v[150:153], v215 offset:17408
	ds_read_b128 v[154:157], v215 offset:18432
	ds_read_b128 v[158:161], v215 offset:19456
	ds_read_b128 v[184:187], v215 offset:20480
	ds_read_b128 v[188:191], v215 offset:21504
	ds_read_b128 v[192:195], v215 offset:22528
	ds_read_b128 v[196:199], v215 offset:23552
	global_load_lds_dwordx4 v[236:237], off
	v_lshl_add_u64 v[238:239], s[24:25], 0, v[174:175]
	s_mov_b32 m0, s40
	s_nop 0
	global_load_lds_dwordx4 v[238:239], off
	s_barrier
	s_waitcnt lgkmcnt(0)
	s_waitcnt lgkmcnt(0)
	v_mfma_f32_16x16x32_bf16 v[78:81], v[34:37], v[146:149], v[78:81]
	v_mfma_f32_16x16x32_bf16 v[70:73], v[58:61], v[146:149], v[70:73]
	v_mfma_f32_16x16x32_bf16 v[54:57], v[34:37], v[154:157], v[54:57]
	v_mfma_f32_16x16x32_bf16 v[46:49], v[58:61], v[154:157], v[46:49]
	v_mfma_f32_16x16x32_bf16 v[30:33], v[34:37], v[184:187], v[30:33]
	v_mfma_f32_16x16x32_bf16 v[22:25], v[58:61], v[184:187], v[22:25]
	v_mfma_f32_16x16x32_bf16 v[14:17], v[34:37], v[192:195], v[14:17]
	v_mfma_f32_16x16x32_bf16 v[6:9], v[58:61], v[192:195], v[6:9]
	v_mfma_f32_16x16x32_bf16 v[78:81], v[38:41], v[150:153], v[78:81]
	v_mfma_f32_16x16x32_bf16 v[70:73], v[62:65], v[150:153], v[70:73]
	v_mfma_f32_16x16x32_bf16 v[54:57], v[38:41], v[158:161], v[54:57]
	v_mfma_f32_16x16x32_bf16 v[46:49], v[62:65], v[158:161], v[46:49]
	v_mfma_f32_16x16x32_bf16 v[30:33], v[38:41], v[188:191], v[30:33]
	v_mfma_f32_16x16x32_bf16 v[22:25], v[62:65], v[188:191], v[22:25]
	v_mfma_f32_16x16x32_bf16 v[14:17], v[38:41], v[196:199], v[14:17]
	v_mfma_f32_16x16x32_bf16 v[6:9], v[62:65], v[196:199], v[6:9]
	s_barrier
	s_add_u32 s58, s22, 0x40000
	s_addc_u32 s59, s23, 0
	s_add_i32 s60, s60, s31
	v_lshl_add_u64 v[34:35], s[58:59], 0, v[176:177]
	s_mov_b32 m0, s60
	s_nop 0
	global_load_lds_dwordx4 v[34:35], off
	v_lshl_add_u64 v[34:35], s[58:59], 0, v[172:173]
	s_add_i32 m0, s60, 0x2000
	s_nop 0
	global_load_lds_dwordx4 v[34:35], off
	s_waitcnt vmcnt(6)
	s_barrier
	v_mfma_f32_16x16x32_bf16 v[50:53], v[200:203], v[154:157], v[50:53]
	v_mfma_f32_16x16x32_bf16 v[42:45], v[208:211], v[154:157], v[42:45]
	v_mfma_f32_16x16x32_bf16 v[26:29], v[200:203], v[184:187], v[26:29]
	v_mfma_f32_16x16x32_bf16 v[18:21], v[208:211], v[184:187], v[18:21]
	v_mfma_f32_16x16x32_bf16 v[10:13], v[200:203], v[192:195], v[10:13]
	v_mfma_f32_16x16x32_bf16 v[2:5], v[208:211], v[192:195], v[2:5]
	v_mfma_f32_16x16x32_bf16 v[34:37], v[200:203], v[146:149], v[74:77]
	v_mfma_f32_16x16x32_bf16 v[38:41], v[208:211], v[146:149], v[66:69]
	v_mfma_f32_16x16x32_bf16 v[50:53], v[204:207], v[158:161], v[50:53]
	v_mfma_f32_16x16x32_bf16 v[42:45], v[216:219], v[158:161], v[42:45]
	v_mfma_f32_16x16x32_bf16 v[26:29], v[204:207], v[188:191], v[26:29]
	v_mfma_f32_16x16x32_bf16 v[18:21], v[216:219], v[188:191], v[18:21]
	v_mfma_f32_16x16x32_bf16 v[10:13], v[204:207], v[196:199], v[10:13]
	v_mfma_f32_16x16x32_bf16 v[2:5], v[216:219], v[196:199], v[2:5]
	v_mfma_f32_16x16x32_bf16 v[34:37], v[204:207], v[150:153], v[34:37]
	v_mfma_f32_16x16x32_bf16 v[38:41], v[216:219], v[150:153], v[38:41]
	s_add_i32 s58, 0, 0x18000
	v_add_u32_e32 v74, s58, v214
	s_barrier
	ds_read_b128 v[58:61], v74
	ds_read_b128 v[62:65], v74 offset:1024
	ds_read_b128 v[66:69], v74 offset:2048
	ds_read_b128 v[74:77], v74 offset:3072
	s_add_u32 s24, s24, 0x40000
	s_addc_u32 s25, s25, 0
	s_mov_b32 m0, s41
	v_lshl_add_u64 v[200:201], s[24:25], 0, v[178:179]
	ds_read_b128 v[146:149], v215 offset:32768
	ds_read_b128 v[150:153], v215 offset:33792
	ds_read_b128 v[154:157], v215 offset:34816
	ds_read_b128 v[158:161], v215 offset:35840
	ds_read_b128 v[184:187], v215 offset:36864
	ds_read_b128 v[188:191], v215 offset:37888
	ds_read_b128 v[192:195], v215 offset:38912
	ds_read_b128 v[196:199], v215 offset:39936
	global_load_lds_dwordx4 v[200:201], off
	v_lshl_add_u64 v[200:201], s[24:25], 0, v[174:175]
	s_mov_b32 m0, s42
	s_nop 0
	global_load_lds_dwordx4 v[200:201], off
	s_waitcnt lgkmcnt(8)
	s_barrier
	s_waitcnt lgkmcnt(0)
	s_waitcnt lgkmcnt(0)
	v_mfma_f32_16x16x32_bf16 v[142:145], v[58:61], v[146:149], v[142:145]
	v_mfma_f32_16x16x32_bf16 v[134:137], v[66:69], v[146:149], v[134:137]
	v_mfma_f32_16x16x32_bf16 v[126:129], v[58:61], v[154:157], v[126:129]
	v_mfma_f32_16x16x32_bf16 v[118:121], v[66:69], v[154:157], v[118:121]
	v_mfma_f32_16x16x32_bf16 v[110:113], v[58:61], v[184:187], v[110:113]
	v_mfma_f32_16x16x32_bf16 v[102:105], v[66:69], v[184:187], v[102:105]
	v_mfma_f32_16x16x32_bf16 v[94:97], v[58:61], v[192:195], v[94:97]
	v_mfma_f32_16x16x32_bf16 v[86:89], v[66:69], v[192:195], v[86:89]
	v_mfma_f32_16x16x32_bf16 v[142:145], v[62:65], v[150:153], v[142:145]
	v_mfma_f32_16x16x32_bf16 v[134:137], v[74:77], v[150:153], v[134:137]
	v_mfma_f32_16x16x32_bf16 v[126:129], v[62:65], v[158:161], v[126:129]
	v_mfma_f32_16x16x32_bf16 v[118:121], v[74:77], v[158:161], v[118:121]
	v_mfma_f32_16x16x32_bf16 v[110:113], v[62:65], v[188:191], v[110:113]
	v_mfma_f32_16x16x32_bf16 v[102:105], v[74:77], v[188:191], v[102:105]
	v_mfma_f32_16x16x32_bf16 v[94:97], v[62:65], v[196:199], v[94:97]
	v_mfma_f32_16x16x32_bf16 v[86:89], v[74:77], v[196:199], v[86:89]
	s_barrier
	s_add_i32 s24, 0, 0x1c000
	s_add_i32 s25, s58, s31
	v_add_u32_e32 v216, s24, v214
	v_lshl_add_u64 v[168:169], v[168:169], 0, s[84:85]
	s_mov_b32 m0, s25
	ds_read_b128 v[200:203], v216
	ds_read_b128 v[204:207], v216 offset:1024
	ds_read_b128 v[208:211], v216 offset:2048
	ds_read_b128 v[216:219], v216 offset:3072
	global_load_lds_dwordx4 v[168:169], off
	v_lshl_add_u64 v[168:169], v[220:221], 0, s[84:85]
	s_add_i32 m0, s25, 0x2000
	s_nop 0
	global_load_lds_dwordx4 v[168:169], off
	s_barrier
	s_waitcnt lgkmcnt(0)
	s_waitcnt lgkmcnt(0)
	v_mfma_f32_16x16x32_bf16 v[138:141], v[200:203], v[146:149], v[138:141]
	v_mfma_f32_16x16x32_bf16 v[130:133], v[208:211], v[146:149], v[130:133]
	v_mfma_f32_16x16x32_bf16 v[122:125], v[200:203], v[154:157], v[122:125]
	v_mfma_f32_16x16x32_bf16 v[114:117], v[208:211], v[154:157], v[114:117]
	v_mfma_f32_16x16x32_bf16 v[106:109], v[200:203], v[184:187], v[106:109]
	v_mfma_f32_16x16x32_bf16 v[98:101], v[208:211], v[184:187], v[98:101]
	v_mfma_f32_16x16x32_bf16 v[90:93], v[200:203], v[192:195], v[90:93]
	v_mfma_f32_16x16x32_bf16 v[82:85], v[208:211], v[192:195], v[82:85]
	v_mfma_f32_16x16x32_bf16 v[138:141], v[204:207], v[150:153], v[138:141]
	v_mfma_f32_16x16x32_bf16 v[130:133], v[216:219], v[150:153], v[130:133]
	v_mfma_f32_16x16x32_bf16 v[122:125], v[204:207], v[158:161], v[122:125]
	v_mfma_f32_16x16x32_bf16 v[114:117], v[216:219], v[158:161], v[114:117]
	v_mfma_f32_16x16x32_bf16 v[106:109], v[204:207], v[188:191], v[106:109]
	v_mfma_f32_16x16x32_bf16 v[98:101], v[216:219], v[188:191], v[98:101]
	v_mfma_f32_16x16x32_bf16 v[90:93], v[204:207], v[196:199], v[90:93]
	v_mfma_f32_16x16x32_bf16 v[82:85], v[216:219], v[196:199], v[82:85]
	s_mov_b32 m0, s47
	v_lshl_add_u64 v[168:169], v[236:237], 0, s[84:85]
	s_barrier
	ds_read_b128 v[146:149], v215 offset:49152
	ds_read_b128 v[150:153], v215 offset:50176
	ds_read_b128 v[154:157], v215 offset:51200
	ds_read_b128 v[158:161], v215 offset:52224
	ds_read_b128 v[184:187], v215 offset:53248
	ds_read_b128 v[188:191], v215 offset:54272
	ds_read_b128 v[192:195], v215 offset:55296
	ds_read_b128 v[196:199], v215 offset:56320
	global_load_lds_dwordx4 v[168:169], off
	v_lshl_add_u64 v[168:169], v[238:239], 0, s[84:85]
	s_mov_b32 m0, s48
	s_nop 0
	global_load_lds_dwordx4 v[168:169], off
	s_barrier
	s_waitcnt lgkmcnt(0)
	s_waitcnt lgkmcnt(0)
	v_mfma_f32_16x16x32_bf16 v[78:81], v[58:61], v[146:149], v[78:81]
	v_mfma_f32_16x16x32_bf16 v[70:73], v[66:69], v[146:149], v[70:73]
	v_mfma_f32_16x16x32_bf16 v[54:57], v[58:61], v[154:157], v[54:57]
	v_mfma_f32_16x16x32_bf16 v[46:49], v[66:69], v[154:157], v[46:49]
	v_mfma_f32_16x16x32_bf16 v[30:33], v[58:61], v[184:187], v[30:33]
	v_mfma_f32_16x16x32_bf16 v[22:25], v[66:69], v[184:187], v[22:25]
	v_mfma_f32_16x16x32_bf16 v[14:17], v[58:61], v[192:195], v[14:17]
	v_mfma_f32_16x16x32_bf16 v[6:9], v[66:69], v[192:195], v[6:9]
	v_mfma_f32_16x16x32_bf16 v[78:81], v[62:65], v[150:153], v[78:81]
	v_mfma_f32_16x16x32_bf16 v[70:73], v[74:77], v[150:153], v[70:73]
	v_mfma_f32_16x16x32_bf16 v[54:57], v[62:65], v[158:161], v[54:57]
	v_mfma_f32_16x16x32_bf16 v[46:49], v[74:77], v[158:161], v[46:49]
	v_mfma_f32_16x16x32_bf16 v[30:33], v[62:65], v[188:191], v[30:33]
	v_mfma_f32_16x16x32_bf16 v[22:25], v[74:77], v[188:191], v[22:25]
	v_mfma_f32_16x16x32_bf16 v[14:17], v[62:65], v[196:199], v[14:17]
	v_mfma_f32_16x16x32_bf16 v[6:9], v[74:77], v[196:199], v[6:9]
	s_barrier
	s_add_u32 s22, s22, 0x40080
	s_addc_u32 s23, s23, 0
	s_add_i32 s24, s24, s31
	v_lshl_add_u64 v[58:59], s[22:23], 0, v[176:177]
	s_mov_b32 m0, s24
	s_nop 0
	global_load_lds_dwordx4 v[58:59], off
	v_lshl_add_u64 v[58:59], s[22:23], 0, v[172:173]
	s_add_i32 m0, s24, 0x2000
	s_nop 0
	global_load_lds_dwordx4 v[58:59], off
	s_waitcnt vmcnt(6)
	s_barrier
	v_mfma_f32_16x16x32_bf16 v[34:37], v[200:203], v[146:149], v[34:37]
	v_mfma_f32_16x16x32_bf16 v[74:77], v[204:207], v[150:153], v[34:37]
	v_mfma_f32_16x16x32_bf16 v[34:37], v[208:211], v[146:149], v[38:41]
	v_mfma_f32_16x16x32_bf16 v[66:69], v[216:219], v[150:153], v[34:37]
	v_mfma_f32_16x16x32_bf16 v[34:37], v[200:203], v[154:157], v[50:53]
	v_mfma_f32_16x16x32_bf16 v[50:53], v[204:207], v[158:161], v[34:37]
	v_mfma_f32_16x16x32_bf16 v[34:37], v[208:211], v[154:157], v[42:45]
	v_mfma_f32_16x16x32_bf16 v[26:29], v[200:203], v[184:187], v[26:29]
	v_mfma_f32_16x16x32_bf16 v[18:21], v[208:211], v[184:187], v[18:21]
	v_mfma_f32_16x16x32_bf16 v[10:13], v[200:203], v[192:195], v[10:13]
	v_mfma_f32_16x16x32_bf16 v[2:5], v[208:211], v[192:195], v[2:5]
	v_mfma_f32_16x16x32_bf16 v[42:45], v[216:219], v[158:161], v[34:37]
	v_mfma_f32_16x16x32_bf16 v[26:29], v[204:207], v[188:191], v[26:29]
	v_mfma_f32_16x16x32_bf16 v[18:21], v[216:219], v[188:191], v[18:21]
	v_mfma_f32_16x16x32_bf16 v[10:13], v[204:207], v[196:199], v[10:13]
	v_mfma_f32_16x16x32_bf16 v[2:5], v[216:219], v[196:199], v[2:5]
	s_add_u32 s20, s20, 0x100
	s_addc_u32 s21, s21, 0
	s_add_u32 s39, s39, 0x100
	s_addc_u32 s56, s56, 0
	s_cmp_ge_i32 s57, s45
	s_mov_b32 s22, s57
	s_barrier
	s_cbranch_scc0 .LBB0_534

.LBB0_563:
	s_add_i32 s47, s16, 2
	s_add_u32 s17, s14, 0xfffc0080
	s_addc_u32 s18, s15, -1
	s_add_i32 s48, 0, 0x10000
	v_add_u32_e32 v102, s48, v159
	ds_read_b128 v[82:85], v102
	ds_read_b128 v[86:89], v102 offset:1024
	ds_read_b128 v[98:101], v102 offset:2048
	ds_read_b128 v[102:105], v102 offset:3072
	s_cmp_eq_u32 s39, s16
	s_cselect_b32 s16, s44, s45
	s_cselect_b32 s19, s5, s18
	s_cselect_b32 s18, s7, s17
	s_cselect_b32 s17, s43, s46
	v_lshl_add_u64 v[160:161], s[14:15], 0, v[154:155]
	s_add_i32 m0, s13, 0xc000
	ds_read_b128 v[174:177], v173
	ds_read_b128 v[178:181], v173 offset:1024
	ds_read_b128 v[182:185], v173 offset:2048
	ds_read_b128 v[186:189], v173 offset:3072
	ds_read_b128 v[190:193], v173 offset:4096
	ds_read_b128 v[194:197], v173 offset:5120
	ds_read_b128 v[198:201], v173 offset:6144
	ds_read_b128 v[202:205], v173 offset:7168
	global_load_lds_dwordx4 v[160:161], off
	v_lshl_add_u64 v[160:161], s[14:15], 0, v[156:157]
	s_add_i32 m0, s13, 0xe000
	s_nop 0
	global_load_lds_dwordx4 v[160:161], off
	s_waitcnt lgkmcnt(8)
	s_barrier
	s_waitcnt lgkmcnt(0)
	s_waitcnt lgkmcnt(0)
	v_mfma_f32_16x16x32_bf16 v[138:141], v[82:85], v[174:177], v[138:141]
	v_mfma_f32_16x16x32_bf16 v[134:137], v[98:101], v[174:177], v[134:137]
	v_mfma_f32_16x16x32_bf16 v[126:129], v[82:85], v[182:185], v[126:129]
	v_mfma_f32_16x16x32_bf16 v[118:121], v[98:101], v[182:185], v[118:121]
	v_mfma_f32_16x16x32_bf16 v[110:113], v[82:85], v[190:193], v[110:113]
	v_mfma_f32_16x16x32_bf16 v[94:97], v[98:101], v[190:193], v[94:97]
	v_mfma_f32_16x16x32_bf16 v[78:81], v[82:85], v[198:201], v[78:81]
	v_mfma_f32_16x16x32_bf16 v[70:73], v[98:101], v[198:201], v[70:73]
	v_mfma_f32_16x16x32_bf16 v[138:141], v[86:89], v[178:181], v[138:141]
	v_mfma_f32_16x16x32_bf16 v[134:137], v[102:105], v[178:181], v[134:137]
	v_mfma_f32_16x16x32_bf16 v[126:129], v[86:89], v[186:189], v[126:129]
	v_mfma_f32_16x16x32_bf16 v[118:121], v[102:105], v[186:189], v[118:121]
	v_mfma_f32_16x16x32_bf16 v[110:113], v[86:89], v[194:197], v[110:113]
	v_mfma_f32_16x16x32_bf16 v[94:97], v[102:105], v[194:197], v[94:97]
	v_mfma_f32_16x16x32_bf16 v[78:81], v[86:89], v[202:205], v[78:81]
	v_mfma_f32_16x16x32_bf16 v[70:73], v[102:105], v[202:205], v[70:73]
	s_barrier
	s_add_i32 s50, 0, 0x14000
	s_add_i32 s48, s48, s23
	v_add_u32_e32 v158, s50, v159
	v_lshl_add_u64 v[160:161], s[16:17], 0, v[150:151]
	s_mov_b32 m0, s48
	ds_read_b128 v[206:209], v158
	ds_read_b128 v[210:213], v158 offset:1024
	ds_read_b128 v[214:217], v158 offset:2048
	ds_read_b128 v[218:221], v158 offset:3072
	global_load_lds_dwordx4 v[160:161], off
	v_lshl_add_u64 v[168:169], s[16:17], 0, v[146:147]
	s_add_i32 m0, s48, 0x2000
	s_nop 0
	global_load_lds_dwordx4 v[168:169], off
	s_barrier
	s_waitcnt lgkmcnt(0)
	s_waitcnt lgkmcnt(0)
	v_mfma_f32_16x16x32_bf16 v[142:145], v[206:209], v[174:177], v[142:145]
	v_mfma_f32_16x16x32_bf16 v[130:133], v[214:217], v[174:177], v[130:133]
	v_mfma_f32_16x16x32_bf16 v[122:125], v[206:209], v[182:185], v[122:125]
	v_mfma_f32_16x16x32_bf16 v[114:117], v[214:217], v[182:185], v[114:117]
	v_mfma_f32_16x16x32_bf16 v[106:109], v[206:209], v[190:193], v[106:109]
	v_mfma_f32_16x16x32_bf16 v[90:93], v[214:217], v[190:193], v[90:93]
	v_mfma_f32_16x16x32_bf16 v[74:77], v[206:209], v[198:201], v[74:77]
	v_mfma_f32_16x16x32_bf16 v[66:69], v[214:217], v[198:201], v[66:69]
	v_mfma_f32_16x16x32_bf16 v[142:145], v[210:213], v[178:181], v[142:145]
	v_mfma_f32_16x16x32_bf16 v[130:133], v[218:221], v[178:181], v[130:133]
	v_mfma_f32_16x16x32_bf16 v[122:125], v[210:213], v[186:189], v[122:125]
	v_mfma_f32_16x16x32_bf16 v[114:117], v[218:221], v[186:189], v[114:117]
	v_mfma_f32_16x16x32_bf16 v[106:109], v[210:213], v[194:197], v[106:109]
	v_mfma_f32_16x16x32_bf16 v[90:93], v[218:221], v[194:197], v[90:93]
	v_mfma_f32_16x16x32_bf16 v[74:77], v[210:213], v[202:205], v[74:77]
	v_mfma_f32_16x16x32_bf16 v[66:69], v[218:221], v[202:205], v[66:69]
	s_mov_b32 m0, s13
	v_lshl_add_u64 v[236:237], s[18:19], 0, v[152:153]
	s_barrier
	ds_read_b128 v[174:177], v173 offset:16384
	ds_read_b128 v[178:181], v173 offset:17408
	ds_read_b128 v[182:185], v173 offset:18432
	ds_read_b128 v[186:189], v173 offset:19456
	ds_read_b128 v[190:193], v173 offset:20480
	ds_read_b128 v[194:197], v173 offset:21504
	ds_read_b128 v[198:201], v173 offset:22528
	ds_read_b128 v[202:205], v173 offset:23552
	global_load_lds_dwordx4 v[236:237], off
	v_lshl_add_u64 v[238:239], s[18:19], 0, v[148:149]
	s_mov_b32 m0, s25
	s_nop 0
	global_load_lds_dwordx4 v[238:239], off
	s_barrier
	s_waitcnt lgkmcnt(0)
	s_waitcnt lgkmcnt(0)
	v_mfma_f32_16x16x32_bf16 v[62:65], v[82:85], v[174:177], v[62:65]
	v_mfma_f32_16x16x32_bf16 v[54:57], v[98:101], v[174:177], v[54:57]
	v_mfma_f32_16x16x32_bf16 v[46:49], v[82:85], v[182:185], v[46:49]
	v_mfma_f32_16x16x32_bf16 v[38:41], v[98:101], v[182:185], v[38:41]
	v_mfma_f32_16x16x32_bf16 v[30:33], v[82:85], v[190:193], v[30:33]
	v_mfma_f32_16x16x32_bf16 v[22:25], v[98:101], v[190:193], v[22:25]
	v_mfma_f32_16x16x32_bf16 v[14:17], v[82:85], v[198:201], v[14:17]
	v_mfma_f32_16x16x32_bf16 v[6:9], v[98:101], v[198:201], v[6:9]
	v_mfma_f32_16x16x32_bf16 v[62:65], v[86:89], v[178:181], v[62:65]
	v_mfma_f32_16x16x32_bf16 v[54:57], v[102:105], v[178:181], v[54:57]
	v_mfma_f32_16x16x32_bf16 v[46:49], v[86:89], v[186:189], v[46:49]
	v_mfma_f32_16x16x32_bf16 v[38:41], v[102:105], v[186:189], v[38:41]
	v_mfma_f32_16x16x32_bf16 v[30:33], v[86:89], v[194:197], v[30:33]
	v_mfma_f32_16x16x32_bf16 v[22:25], v[102:105], v[194:197], v[22:25]
	v_mfma_f32_16x16x32_bf16 v[14:17], v[86:89], v[202:205], v[14:17]
	v_mfma_f32_16x16x32_bf16 v[6:9], v[102:105], v[202:205], v[6:9]
	s_barrier
	s_add_u32 s48, s16, 0x40000
	s_addc_u32 s49, s17, 0
	s_add_i32 s50, s50, s23
	v_lshl_add_u64 v[82:83], s[48:49], 0, v[150:151]
	s_mov_b32 m0, s50
	s_nop 0
	global_load_lds_dwordx4 v[82:83], off
	v_lshl_add_u64 v[82:83], s[48:49], 0, v[146:147]
	s_add_i32 m0, s50, 0x2000
	s_nop 0
	global_load_lds_dwordx4 v[82:83], off
	s_waitcnt vmcnt(6)
	s_barrier
	v_mfma_f32_16x16x32_bf16 v[58:61], v[206:209], v[174:177], v[58:61]
	v_mfma_f32_16x16x32_bf16 v[50:53], v[214:217], v[174:177], v[50:53]
	v_mfma_f32_16x16x32_bf16 v[42:45], v[206:209], v[182:185], v[42:45]
	v_mfma_f32_16x16x32_bf16 v[34:37], v[214:217], v[182:185], v[34:37]
	v_mfma_f32_16x16x32_bf16 v[26:29], v[206:209], v[190:193], v[26:29]
	v_mfma_f32_16x16x32_bf16 v[18:21], v[214:217], v[190:193], v[18:21]
	v_mfma_f32_16x16x32_bf16 v[10:13], v[206:209], v[198:201], v[10:13]
	v_mfma_f32_16x16x32_bf16 v[2:5], v[214:217], v[198:201], v[2:5]
	v_mfma_f32_16x16x32_bf16 v[58:61], v[210:213], v[178:181], v[58:61]
	v_mfma_f32_16x16x32_bf16 v[50:53], v[218:221], v[178:181], v[50:53]
	v_mfma_f32_16x16x32_bf16 v[42:45], v[210:213], v[186:189], v[42:45]
	v_mfma_f32_16x16x32_bf16 v[34:37], v[218:221], v[186:189], v[34:37]
	v_mfma_f32_16x16x32_bf16 v[26:29], v[210:213], v[194:197], v[26:29]
	v_mfma_f32_16x16x32_bf16 v[18:21], v[218:221], v[194:197], v[18:21]
	v_mfma_f32_16x16x32_bf16 v[10:13], v[210:213], v[202:205], v[10:13]
	v_mfma_f32_16x16x32_bf16 v[2:5], v[218:221], v[202:205], v[2:5]
	s_add_i32 s48, 0, 0x18000
	v_add_u32_e32 v102, s48, v159
	s_barrier
	ds_read_b128 v[82:85], v102
	ds_read_b128 v[86:89], v102 offset:1024
	ds_read_b128 v[98:101], v102 offset:2048
	ds_read_b128 v[102:105], v102 offset:3072
	s_add_u32 s18, s18, 0x40000
	s_addc_u32 s19, s19, 0
	s_mov_b32 m0, s26
	v_lshl_add_u64 v[206:207], s[18:19], 0, v[152:153]
	ds_read_b128 v[174:177], v173 offset:32768
	ds_read_b128 v[178:181], v173 offset:33792
	ds_read_b128 v[182:185], v173 offset:34816
	ds_read_b128 v[186:189], v173 offset:35840
	ds_read_b128 v[190:193], v173 offset:36864
	ds_read_b128 v[194:197], v173 offset:37888
	ds_read_b128 v[198:201], v173 offset:38912
	ds_read_b128 v[202:205], v173 offset:39936
	global_load_lds_dwordx4 v[206:207], off
	v_lshl_add_u64 v[206:207], s[18:19], 0, v[148:149]
	s_mov_b32 m0, s27
	s_nop 0
	global_load_lds_dwordx4 v[206:207], off
	s_waitcnt lgkmcnt(8)
	s_barrier
	s_waitcnt lgkmcnt(0)
	s_waitcnt lgkmcnt(0)
	v_mfma_f32_16x16x32_bf16 v[138:141], v[82:85], v[174:177], v[138:141]
	v_mfma_f32_16x16x32_bf16 v[134:137], v[98:101], v[174:177], v[134:137]
	v_mfma_f32_16x16x32_bf16 v[126:129], v[82:85], v[182:185], v[126:129]
	v_mfma_f32_16x16x32_bf16 v[118:121], v[98:101], v[182:185], v[118:121]
	v_mfma_f32_16x16x32_bf16 v[110:113], v[82:85], v[190:193], v[110:113]
	v_mfma_f32_16x16x32_bf16 v[94:97], v[98:101], v[190:193], v[94:97]
	v_mfma_f32_16x16x32_bf16 v[78:81], v[82:85], v[198:201], v[78:81]
	v_mfma_f32_16x16x32_bf16 v[70:73], v[98:101], v[198:201], v[70:73]
	v_mfma_f32_16x16x32_bf16 v[138:141], v[86:89], v[178:181], v[138:141]
	v_mfma_f32_16x16x32_bf16 v[134:137], v[102:105], v[178:181], v[134:137]
	v_mfma_f32_16x16x32_bf16 v[126:129], v[86:89], v[186:189], v[126:129]
	v_mfma_f32_16x16x32_bf16 v[118:121], v[102:105], v[186:189], v[118:121]
	v_mfma_f32_16x16x32_bf16 v[110:113], v[86:89], v[194:197], v[110:113]
	v_mfma_f32_16x16x32_bf16 v[94:97], v[102:105], v[194:197], v[94:97]
	v_mfma_f32_16x16x32_bf16 v[78:81], v[86:89], v[202:205], v[78:81]
	v_mfma_f32_16x16x32_bf16 v[70:73], v[102:105], v[202:205], v[70:73]
	s_barrier
	s_add_i32 s18, 0, 0x1c000
	s_add_i32 s19, s48, s23
	v_add_u32_e32 v158, s18, v159
	v_lshl_add_u64 v[160:161], v[160:161], 0, s[84:85]
	s_mov_b32 m0, s19
	ds_read_b128 v[206:209], v158
	ds_read_b128 v[210:213], v158 offset:1024
	ds_read_b128 v[214:217], v158 offset:2048
	ds_read_b128 v[218:221], v158 offset:3072
	global_load_lds_dwordx4 v[160:161], off
	v_lshl_add_u64 v[160:161], v[168:169], 0, s[84:85]
	s_add_i32 m0, s19, 0x2000
	s_nop 0
	global_load_lds_dwordx4 v[160:161], off
	s_barrier
	s_waitcnt lgkmcnt(0)
	s_waitcnt lgkmcnt(0)
	v_mfma_f32_16x16x32_bf16 v[142:145], v[206:209], v[174:177], v[142:145]
	v_mfma_f32_16x16x32_bf16 v[130:133], v[214:217], v[174:177], v[130:133]
	v_mfma_f32_16x16x32_bf16 v[122:125], v[206:209], v[182:185], v[122:125]
	v_mfma_f32_16x16x32_bf16 v[114:117], v[214:217], v[182:185], v[114:117]
	v_mfma_f32_16x16x32_bf16 v[106:109], v[206:209], v[190:193], v[106:109]
	v_mfma_f32_16x16x32_bf16 v[90:93], v[214:217], v[190:193], v[90:93]
	v_mfma_f32_16x16x32_bf16 v[74:77], v[206:209], v[198:201], v[74:77]
	v_mfma_f32_16x16x32_bf16 v[66:69], v[214:217], v[198:201], v[66:69]
	v_mfma_f32_16x16x32_bf16 v[142:145], v[210:213], v[178:181], v[142:145]
	v_mfma_f32_16x16x32_bf16 v[130:133], v[218:221], v[178:181], v[130:133]
	v_mfma_f32_16x16x32_bf16 v[122:125], v[210:213], v[186:189], v[122:125]
	v_mfma_f32_16x16x32_bf16 v[114:117], v[218:221], v[186:189], v[114:117]
	v_mfma_f32_16x16x32_bf16 v[106:109], v[210:213], v[194:197], v[106:109]
	v_mfma_f32_16x16x32_bf16 v[90:93], v[218:221], v[194:197], v[90:93]
	v_mfma_f32_16x16x32_bf16 v[74:77], v[210:213], v[202:205], v[74:77]
	v_mfma_f32_16x16x32_bf16 v[66:69], v[218:221], v[202:205], v[66:69]
	s_mov_b32 m0, s35
	v_lshl_add_u64 v[160:161], v[236:237], 0, s[84:85]
	s_barrier
	ds_read_b128 v[174:177], v173 offset:49152
	ds_read_b128 v[178:181], v173 offset:50176
	ds_read_b128 v[182:185], v173 offset:51200
	ds_read_b128 v[186:189], v173 offset:52224
	ds_read_b128 v[190:193], v173 offset:53248
	ds_read_b128 v[194:197], v173 offset:54272
	ds_read_b128 v[198:201], v173 offset:55296
	ds_read_b128 v[202:205], v173 offset:56320
	global_load_lds_dwordx4 v[160:161], off
	v_lshl_add_u64 v[160:161], v[238:239], 0, s[84:85]
	s_mov_b32 m0, s38
	s_nop 0
	global_load_lds_dwordx4 v[160:161], off
	s_barrier
	s_waitcnt lgkmcnt(0)
	s_waitcnt lgkmcnt(0)
	v_mfma_f32_16x16x32_bf16 v[62:65], v[82:85], v[174:177], v[62:65]
	v_mfma_f32_16x16x32_bf16 v[54:57], v[98:101], v[174:177], v[54:57]
	v_mfma_f32_16x16x32_bf16 v[46:49], v[82:85], v[182:185], v[46:49]
	v_mfma_f32_16x16x32_bf16 v[38:41], v[98:101], v[182:185], v[38:41]
	v_mfma_f32_16x16x32_bf16 v[30:33], v[82:85], v[190:193], v[30:33]
	v_mfma_f32_16x16x32_bf16 v[22:25], v[98:101], v[190:193], v[22:25]
	v_mfma_f32_16x16x32_bf16 v[14:17], v[82:85], v[198:201], v[14:17]
	v_mfma_f32_16x16x32_bf16 v[6:9], v[98:101], v[198:201], v[6:9]
	v_mfma_f32_16x16x32_bf16 v[62:65], v[86:89], v[178:181], v[62:65]
	v_mfma_f32_16x16x32_bf16 v[54:57], v[102:105], v[178:181], v[54:57]
	v_mfma_f32_16x16x32_bf16 v[46:49], v[86:89], v[186:189], v[46:49]
	v_mfma_f32_16x16x32_bf16 v[38:41], v[102:105], v[186:189], v[38:41]
	v_mfma_f32_16x16x32_bf16 v[30:33], v[86:89], v[194:197], v[30:33]
	v_mfma_f32_16x16x32_bf16 v[22:25], v[102:105], v[194:197], v[22:25]
	v_mfma_f32_16x16x32_bf16 v[14:17], v[86:89], v[202:205], v[14:17]
	v_mfma_f32_16x16x32_bf16 v[6:9], v[102:105], v[202:205], v[6:9]
	s_barrier
	s_add_u32 s16, s16, 0x40080
	s_addc_u32 s17, s17, 0
	s_add_i32 s18, s18, s23
	v_lshl_add_u64 v[82:83], s[16:17], 0, v[150:151]
	s_mov_b32 m0, s18
	s_nop 0
	global_load_lds_dwordx4 v[82:83], off
	v_lshl_add_u64 v[82:83], s[16:17], 0, v[146:147]
	s_add_i32 m0, s18, 0x2000
	s_nop 0
	global_load_lds_dwordx4 v[82:83], off
	s_waitcnt vmcnt(6)
	s_barrier
	v_mfma_f32_16x16x32_bf16 v[58:61], v[206:209], v[174:177], v[58:61]
	v_mfma_f32_16x16x32_bf16 v[50:53], v[214:217], v[174:177], v[50:53]
	v_mfma_f32_16x16x32_bf16 v[42:45], v[206:209], v[182:185], v[42:45]
	v_mfma_f32_16x16x32_bf16 v[34:37], v[214:217], v[182:185], v[34:37]
	v_mfma_f32_16x16x32_bf16 v[26:29], v[206:209], v[190:193], v[26:29]
	v_mfma_f32_16x16x32_bf16 v[18:21], v[214:217], v[190:193], v[18:21]
	v_mfma_f32_16x16x32_bf16 v[10:13], v[206:209], v[198:201], v[10:13]
	v_mfma_f32_16x16x32_bf16 v[2:5], v[214:217], v[198:201], v[2:5]
	v_mfma_f32_16x16x32_bf16 v[58:61], v[210:213], v[178:181], v[58:61]
	v_mfma_f32_16x16x32_bf16 v[50:53], v[218:221], v[178:181], v[50:53]
	v_mfma_f32_16x16x32_bf16 v[42:45], v[210:213], v[186:189], v[42:45]
	v_mfma_f32_16x16x32_bf16 v[34:37], v[218:221], v[186:189], v[34:37]
	v_mfma_f32_16x16x32_bf16 v[26:29], v[210:213], v[194:197], v[26:29]
	v_mfma_f32_16x16x32_bf16 v[18:21], v[218:221], v[194:197], v[18:21]
	v_mfma_f32_16x16x32_bf16 v[10:13], v[210:213], v[202:205], v[10:13]
	v_mfma_f32_16x16x32_bf16 v[2:5], v[218:221], v[202:205], v[2:5]
	s_add_u32 s14, s14, 0x100
	s_addc_u32 s15, s15, 0
	s_add_u32 s45, s45, 0x100
	s_addc_u32 s46, s46, 0
	s_cmp_ge_i32 s47, s30
	s_mov_b32 s16, s47
	s_barrier
	s_cbranch_scc0 .LBB0_563
	s_branch .LBB0_558

.LBB0_592:
	s_add_i32 s51, s12, 2
	s_add_u32 s13, s10, 0x4000
	s_addc_u32 s14, s11, 0
	s_cmp_eq_u32 s41, s12
	s_cselect_b32 s16, s0, s13
	s_cselect_b32 s17, s1, s14
	s_cselect_b32 s12, s2, s49
	s_cselect_b32 s13, s3, s50
	s_add_u32 s14, s16, 0x8000
	s_addc_u32 s15, s17, 0
	s_add_i32 s52, 0, 0x10000
	v_add_u32_e32 v94, s52, v237
	ds_read_b128 v[66:69], v94
	ds_read_b128 v[70:73], v94 offset:1024
	ds_read_b128 v[90:93], v94 offset:2048
	ds_read_b128 v[94:97], v94 offset:3072
	v_lshl_add_u64 v[168:169], s[10:11], 0, v[176:177]
	s_add_i32 m0, s22, 0xc000
	ds_read_b128 v[146:149], v238
	ds_read_b128 v[150:153], v238 offset:1024
	ds_read_b128 v[154:157], v238 offset:2048
	ds_read_b128 v[180:183], v238 offset:3072
	ds_read_b128 v[184:187], v238 offset:4096
	ds_read_b128 v[188:191], v238 offset:5120
	ds_read_b128 v[192:195], v238 offset:6144
	ds_read_b128 v[196:199], v238 offset:7168
	global_load_lds_dwordx4 v[168:169], off
	v_lshl_add_u64 v[168:169], s[10:11], 0, v[178:179]
	s_add_i32 m0, s22, 0xe000
	s_nop 0
	global_load_lds_dwordx4 v[168:169], off
	s_waitcnt lgkmcnt(8)
	s_barrier
	s_waitcnt lgkmcnt(0)
	s_waitcnt lgkmcnt(0)
	v_mfma_f32_16x16x32_bf16 v[138:141], v[66:69], v[146:149], v[138:141]
	v_mfma_f32_16x16x32_bf16 v[142:145], v[90:93], v[146:149], v[142:145]
	v_mfma_f32_16x16x32_bf16 v[126:129], v[66:69], v[154:157], v[126:129]
	v_mfma_f32_16x16x32_bf16 v[122:125], v[90:93], v[154:157], v[122:125]
	v_mfma_f32_16x16x32_bf16 v[110:113], v[66:69], v[184:187], v[110:113]
	v_mfma_f32_16x16x32_bf16 v[106:109], v[90:93], v[184:187], v[106:109]
	v_mfma_f32_16x16x32_bf16 v[86:89], v[66:69], v[192:195], v[86:89]
	v_mfma_f32_16x16x32_bf16 v[82:85], v[90:93], v[192:195], v[82:85]
	v_mfma_f32_16x16x32_bf16 v[138:141], v[70:73], v[150:153], v[138:141]
	v_mfma_f32_16x16x32_bf16 v[142:145], v[94:97], v[150:153], v[142:145]
	v_mfma_f32_16x16x32_bf16 v[126:129], v[70:73], v[180:183], v[126:129]
	v_mfma_f32_16x16x32_bf16 v[122:125], v[94:97], v[180:183], v[122:125]
	v_mfma_f32_16x16x32_bf16 v[110:113], v[70:73], v[188:191], v[110:113]
	v_mfma_f32_16x16x32_bf16 v[106:109], v[94:97], v[188:191], v[106:109]
	v_mfma_f32_16x16x32_bf16 v[86:89], v[70:73], v[196:199], v[86:89]
	v_mfma_f32_16x16x32_bf16 v[82:85], v[94:97], v[196:199], v[82:85]
	s_barrier
	s_add_i32 s54, 0, 0x14000
	v_add_u32_e32 v168, s54, v237
	s_add_i32 s52, s52, s21
	ds_read_b128 v[200:203], v168
	ds_read_b128 v[204:207], v168 offset:1024
	ds_read_b128 v[208:211], v168 offset:2048
	ds_read_b128 v[212:215], v168 offset:3072
	v_lshl_add_u64 v[168:169], s[12:13], 0, v[160:161]
	s_mov_b32 m0, s52
	v_lshl_add_u64 v[216:217], s[12:13], 0, v[174:175]
	global_load_lds_dwordx4 v[168:169], off
	s_add_i32 m0, s52, 0x2000
	s_nop 0
	global_load_lds_dwordx4 v[216:217], off
	s_barrier
	s_waitcnt lgkmcnt(0)
	s_waitcnt lgkmcnt(0)
	v_mfma_f32_16x16x32_bf16 v[134:137], v[200:203], v[146:149], v[134:137]
	v_mfma_f32_16x16x32_bf16 v[130:133], v[208:211], v[146:149], v[130:133]
	v_mfma_f32_16x16x32_bf16 v[118:121], v[200:203], v[154:157], v[118:121]
	v_mfma_f32_16x16x32_bf16 v[114:117], v[208:211], v[154:157], v[114:117]
	v_mfma_f32_16x16x32_bf16 v[102:105], v[200:203], v[184:187], v[102:105]
	v_mfma_f32_16x16x32_bf16 v[98:101], v[208:211], v[184:187], v[98:101]
	v_mfma_f32_16x16x32_bf16 v[78:81], v[200:203], v[192:195], v[78:81]
	v_mfma_f32_16x16x32_bf16 v[74:77], v[208:211], v[192:195], v[74:77]
	v_mfma_f32_16x16x32_bf16 v[134:137], v[204:207], v[150:153], v[134:137]
	v_mfma_f32_16x16x32_bf16 v[130:133], v[212:215], v[150:153], v[130:133]
	v_mfma_f32_16x16x32_bf16 v[118:121], v[204:207], v[180:183], v[118:121]
	v_mfma_f32_16x16x32_bf16 v[114:117], v[212:215], v[180:183], v[114:117]
	v_mfma_f32_16x16x32_bf16 v[102:105], v[204:207], v[188:191], v[102:105]
	v_mfma_f32_16x16x32_bf16 v[98:101], v[212:215], v[188:191], v[98:101]
	v_mfma_f32_16x16x32_bf16 v[78:81], v[204:207], v[196:199], v[78:81]
	v_mfma_f32_16x16x32_bf16 v[74:77], v[212:215], v[196:199], v[74:77]
	s_mov_b32 m0, s22
	v_lshl_add_u64 v[218:219], s[16:17], 0, v[158:159]
	s_barrier
	ds_read_b128 v[146:149], v238 offset:16384
	ds_read_b128 v[150:153], v238 offset:17408
	ds_read_b128 v[154:157], v238 offset:18432
	ds_read_b128 v[180:183], v238 offset:19456
	ds_read_b128 v[184:187], v238 offset:20480
	ds_read_b128 v[188:191], v238 offset:21504
	ds_read_b128 v[192:195], v238 offset:22528
	ds_read_b128 v[196:199], v238 offset:23552
	global_load_lds_dwordx4 v[218:219], off
	v_lshl_add_u64 v[218:219], s[16:17], 0, v[172:173]
	s_mov_b32 m0, s23
	s_nop 0
	global_load_lds_dwordx4 v[218:219], off
	s_barrier
	s_waitcnt lgkmcnt(0)
	s_waitcnt lgkmcnt(0)
	v_mfma_f32_16x16x32_bf16 v[62:65], v[66:69], v[146:149], v[62:65]
	v_mfma_f32_16x16x32_bf16 v[58:61], v[90:93], v[146:149], v[58:61]
	v_mfma_f32_16x16x32_bf16 v[46:49], v[66:69], v[154:157], v[46:49]
	v_mfma_f32_16x16x32_bf16 v[42:45], v[90:93], v[154:157], v[42:45]
	v_mfma_f32_16x16x32_bf16 v[30:33], v[66:69], v[184:187], v[30:33]
	v_mfma_f32_16x16x32_bf16 v[26:29], v[90:93], v[184:187], v[26:29]
	v_mfma_f32_16x16x32_bf16 v[14:17], v[66:69], v[192:195], v[14:17]
	v_mfma_f32_16x16x32_bf16 v[10:13], v[90:93], v[192:195], v[10:13]
	v_mfma_f32_16x16x32_bf16 v[62:65], v[70:73], v[150:153], v[62:65]
	v_mfma_f32_16x16x32_bf16 v[58:61], v[94:97], v[150:153], v[58:61]
	v_mfma_f32_16x16x32_bf16 v[46:49], v[70:73], v[180:183], v[46:49]
	v_mfma_f32_16x16x32_bf16 v[42:45], v[94:97], v[180:183], v[42:45]
	v_mfma_f32_16x16x32_bf16 v[30:33], v[70:73], v[188:191], v[30:33]
	v_mfma_f32_16x16x32_bf16 v[26:29], v[94:97], v[188:191], v[26:29]
	v_mfma_f32_16x16x32_bf16 v[14:17], v[70:73], v[196:199], v[14:17]
	v_mfma_f32_16x16x32_bf16 v[10:13], v[94:97], v[196:199], v[10:13]
	s_barrier
	s_add_u32 s52, s12, 0xb0000
	s_addc_u32 s53, s13, 0
	s_add_i32 s54, s54, s21
	v_lshl_add_u64 v[66:67], s[52:53], 0, v[160:161]
	s_mov_b32 m0, s54
	s_nop 0
	global_load_lds_dwordx4 v[66:67], off
	v_lshl_add_u64 v[66:67], s[52:53], 0, v[174:175]
	s_add_i32 m0, s54, 0x2000
	s_nop 0
	global_load_lds_dwordx4 v[66:67], off
	s_waitcnt vmcnt(6)
	s_barrier
	v_mfma_f32_16x16x32_bf16 v[54:57], v[200:203], v[146:149], v[54:57]
	v_mfma_f32_16x16x32_bf16 v[50:53], v[208:211], v[146:149], v[50:53]
	v_mfma_f32_16x16x32_bf16 v[38:41], v[200:203], v[154:157], v[38:41]
	v_mfma_f32_16x16x32_bf16 v[34:37], v[208:211], v[154:157], v[34:37]
	v_mfma_f32_16x16x32_bf16 v[22:25], v[200:203], v[184:187], v[22:25]
	v_mfma_f32_16x16x32_bf16 v[18:21], v[208:211], v[184:187], v[18:21]
	v_mfma_f32_16x16x32_bf16 v[6:9], v[200:203], v[192:195], v[6:9]
	v_mfma_f32_16x16x32_bf16 v[2:5], v[208:211], v[192:195], v[2:5]
	v_mfma_f32_16x16x32_bf16 v[54:57], v[204:207], v[150:153], v[54:57]
	v_mfma_f32_16x16x32_bf16 v[50:53], v[212:215], v[150:153], v[50:53]
	v_mfma_f32_16x16x32_bf16 v[38:41], v[204:207], v[180:183], v[38:41]
	v_mfma_f32_16x16x32_bf16 v[34:37], v[212:215], v[180:183], v[34:37]
	v_mfma_f32_16x16x32_bf16 v[22:25], v[204:207], v[188:191], v[22:25]
	v_mfma_f32_16x16x32_bf16 v[18:21], v[212:215], v[188:191], v[18:21]
	v_mfma_f32_16x16x32_bf16 v[6:9], v[204:207], v[196:199], v[6:9]
	v_mfma_f32_16x16x32_bf16 v[2:5], v[212:215], v[196:199], v[2:5]
	s_add_i32 s52, 0, 0x18000
	v_add_u32_e32 v94, s52, v237
	s_barrier
	ds_read_b128 v[66:69], v94
	ds_read_b128 v[70:73], v94 offset:1024
	ds_read_b128 v[90:93], v94 offset:2048
	ds_read_b128 v[94:97], v94 offset:3072
	s_add_u32 s16, s16, 0x4000
	s_addc_u32 s17, s17, 0
	s_mov_b32 m0, s24
	v_lshl_add_u64 v[200:201], s[16:17], 0, v[158:159]
	ds_read_b128 v[146:149], v238 offset:32768
	ds_read_b128 v[150:153], v238 offset:33792
	ds_read_b128 v[154:157], v238 offset:34816
	ds_read_b128 v[180:183], v238 offset:35840
	ds_read_b128 v[184:187], v238 offset:36864
	ds_read_b128 v[188:191], v238 offset:37888
	ds_read_b128 v[192:195], v238 offset:38912
	ds_read_b128 v[196:199], v238 offset:39936
	global_load_lds_dwordx4 v[200:201], off
	v_lshl_add_u64 v[200:201], s[16:17], 0, v[172:173]
	s_mov_b32 m0, s25
	s_nop 0
	global_load_lds_dwordx4 v[200:201], off
	s_waitcnt lgkmcnt(8)
	s_barrier
	s_waitcnt lgkmcnt(0)
	s_waitcnt lgkmcnt(0)
	v_mfma_f32_16x16x32_bf16 v[138:141], v[66:69], v[146:149], v[138:141]
	v_mfma_f32_16x16x32_bf16 v[142:145], v[90:93], v[146:149], v[142:145]
	v_mfma_f32_16x16x32_bf16 v[126:129], v[66:69], v[154:157], v[126:129]
	v_mfma_f32_16x16x32_bf16 v[122:125], v[90:93], v[154:157], v[122:125]
	v_mfma_f32_16x16x32_bf16 v[110:113], v[66:69], v[184:187], v[110:113]
	v_mfma_f32_16x16x32_bf16 v[106:109], v[90:93], v[184:187], v[106:109]
	v_mfma_f32_16x16x32_bf16 v[86:89], v[66:69], v[192:195], v[86:89]
	v_mfma_f32_16x16x32_bf16 v[82:85], v[90:93], v[192:195], v[82:85]
	v_mfma_f32_16x16x32_bf16 v[138:141], v[70:73], v[150:153], v[138:141]
	v_mfma_f32_16x16x32_bf16 v[142:145], v[94:97], v[150:153], v[142:145]
	v_mfma_f32_16x16x32_bf16 v[126:129], v[70:73], v[180:183], v[126:129]
	v_mfma_f32_16x16x32_bf16 v[122:125], v[94:97], v[180:183], v[122:125]
	v_mfma_f32_16x16x32_bf16 v[110:113], v[70:73], v[188:191], v[110:113]
	v_mfma_f32_16x16x32_bf16 v[106:109], v[94:97], v[188:191], v[106:109]
	v_mfma_f32_16x16x32_bf16 v[86:89], v[70:73], v[196:199], v[86:89]
	v_mfma_f32_16x16x32_bf16 v[82:85], v[94:97], v[196:199], v[82:85]
	s_barrier
	s_add_i32 s16, 0, 0x1c000
	s_add_i32 s17, s52, s21
	v_add_u32_e32 v212, s16, v237
	v_lshl_add_u64 v[168:169], v[168:169], 0, s[84:85]
	s_mov_b32 m0, s17
	ds_read_b128 v[200:203], v212
	ds_read_b128 v[204:207], v212 offset:1024
	ds_read_b128 v[208:211], v212 offset:2048
	ds_read_b128 v[212:215], v212 offset:3072
	global_load_lds_dwordx4 v[168:169], off
	v_lshl_add_u64 v[168:169], v[216:217], 0, s[84:85]
	s_add_i32 m0, s17, 0x2000
	s_nop 0
	global_load_lds_dwordx4 v[168:169], off
	s_barrier
	s_waitcnt lgkmcnt(0)
	s_waitcnt lgkmcnt(0)
	v_mfma_f32_16x16x32_bf16 v[134:137], v[200:203], v[146:149], v[134:137]
	v_mfma_f32_16x16x32_bf16 v[130:133], v[208:211], v[146:149], v[130:133]
	v_mfma_f32_16x16x32_bf16 v[118:121], v[200:203], v[154:157], v[118:121]
	v_mfma_f32_16x16x32_bf16 v[114:117], v[208:211], v[154:157], v[114:117]
	v_mfma_f32_16x16x32_bf16 v[102:105], v[200:203], v[184:187], v[102:105]
	v_mfma_f32_16x16x32_bf16 v[98:101], v[208:211], v[184:187], v[98:101]
	v_mfma_f32_16x16x32_bf16 v[78:81], v[200:203], v[192:195], v[78:81]
	v_mfma_f32_16x16x32_bf16 v[74:77], v[208:211], v[192:195], v[74:77]
	v_mfma_f32_16x16x32_bf16 v[134:137], v[204:207], v[150:153], v[134:137]
	v_mfma_f32_16x16x32_bf16 v[130:133], v[212:215], v[150:153], v[130:133]
	v_mfma_f32_16x16x32_bf16 v[118:121], v[204:207], v[180:183], v[118:121]
	v_mfma_f32_16x16x32_bf16 v[114:117], v[212:215], v[180:183], v[114:117]
	v_mfma_f32_16x16x32_bf16 v[102:105], v[204:207], v[188:191], v[102:105]
	v_mfma_f32_16x16x32_bf16 v[98:101], v[212:215], v[188:191], v[98:101]
	v_mfma_f32_16x16x32_bf16 v[78:81], v[204:207], v[196:199], v[78:81]
	v_mfma_f32_16x16x32_bf16 v[74:77], v[212:215], v[196:199], v[74:77]
	s_mov_b32 m0, s39
	v_lshl_add_u64 v[168:169], s[14:15], 0, v[158:159]
	s_barrier
	ds_read_b128 v[146:149], v238 offset:49152
	ds_read_b128 v[150:153], v238 offset:50176
	ds_read_b128 v[154:157], v238 offset:51200
	ds_read_b128 v[180:183], v238 offset:52224
	ds_read_b128 v[184:187], v238 offset:53248
	ds_read_b128 v[188:191], v238 offset:54272
	ds_read_b128 v[192:195], v238 offset:55296
	ds_read_b128 v[196:199], v238 offset:56320
	global_load_lds_dwordx4 v[168:169], off
	v_lshl_add_u64 v[168:169], s[14:15], 0, v[172:173]
	s_mov_b32 m0, s40
	s_nop 0
	global_load_lds_dwordx4 v[168:169], off
	s_barrier
	s_waitcnt lgkmcnt(0)
	s_waitcnt lgkmcnt(0)
	v_mfma_f32_16x16x32_bf16 v[62:65], v[66:69], v[146:149], v[62:65]
	v_mfma_f32_16x16x32_bf16 v[58:61], v[90:93], v[146:149], v[58:61]
	v_mfma_f32_16x16x32_bf16 v[46:49], v[66:69], v[154:157], v[46:49]
	v_mfma_f32_16x16x32_bf16 v[42:45], v[90:93], v[154:157], v[42:45]
	v_mfma_f32_16x16x32_bf16 v[30:33], v[66:69], v[184:187], v[30:33]
	v_mfma_f32_16x16x32_bf16 v[26:29], v[90:93], v[184:187], v[26:29]
	v_mfma_f32_16x16x32_bf16 v[14:17], v[66:69], v[192:195], v[14:17]
	v_mfma_f32_16x16x32_bf16 v[10:13], v[90:93], v[192:195], v[10:13]
	v_mfma_f32_16x16x32_bf16 v[62:65], v[70:73], v[150:153], v[62:65]
	v_mfma_f32_16x16x32_bf16 v[58:61], v[94:97], v[150:153], v[58:61]
	v_mfma_f32_16x16x32_bf16 v[46:49], v[70:73], v[180:183], v[46:49]
	v_mfma_f32_16x16x32_bf16 v[42:45], v[94:97], v[180:183], v[42:45]
	v_mfma_f32_16x16x32_bf16 v[30:33], v[70:73], v[188:191], v[30:33]
	v_mfma_f32_16x16x32_bf16 v[26:29], v[94:97], v[188:191], v[26:29]
	v_mfma_f32_16x16x32_bf16 v[14:17], v[70:73], v[196:199], v[14:17]
	v_mfma_f32_16x16x32_bf16 v[10:13], v[94:97], v[196:199], v[10:13]
	s_barrier
	s_add_u32 s12, s12, 0xb0080
	s_addc_u32 s13, s13, 0
	s_add_i32 s14, s16, s21
	v_lshl_add_u64 v[66:67], s[12:13], 0, v[160:161]
	s_mov_b32 m0, s14
	s_nop 0
	global_load_lds_dwordx4 v[66:67], off
	v_lshl_add_u64 v[66:67], s[12:13], 0, v[174:175]
	s_add_i32 m0, s14, 0x2000
	s_nop 0
	global_load_lds_dwordx4 v[66:67], off
	s_waitcnt vmcnt(6)
	s_barrier
	v_mfma_f32_16x16x32_bf16 v[54:57], v[200:203], v[146:149], v[54:57]
	v_mfma_f32_16x16x32_bf16 v[50:53], v[208:211], v[146:149], v[50:53]
	v_mfma_f32_16x16x32_bf16 v[38:41], v[200:203], v[154:157], v[38:41]
	v_mfma_f32_16x16x32_bf16 v[34:37], v[208:211], v[154:157], v[34:37]
	v_mfma_f32_16x16x32_bf16 v[22:25], v[200:203], v[184:187], v[22:25]
	v_mfma_f32_16x16x32_bf16 v[18:21], v[208:211], v[184:187], v[18:21]
	v_mfma_f32_16x16x32_bf16 v[6:9], v[200:203], v[192:195], v[6:9]
	v_mfma_f32_16x16x32_bf16 v[2:5], v[208:211], v[192:195], v[2:5]
	v_mfma_f32_16x16x32_bf16 v[54:57], v[204:207], v[150:153], v[54:57]
	v_mfma_f32_16x16x32_bf16 v[50:53], v[212:215], v[150:153], v[50:53]
	v_mfma_f32_16x16x32_bf16 v[38:41], v[204:207], v[180:183], v[38:41]
	v_mfma_f32_16x16x32_bf16 v[34:37], v[212:215], v[180:183], v[34:37]
	v_mfma_f32_16x16x32_bf16 v[22:25], v[204:207], v[188:191], v[22:25]
	v_mfma_f32_16x16x32_bf16 v[18:21], v[212:215], v[188:191], v[18:21]
	v_mfma_f32_16x16x32_bf16 v[6:9], v[204:207], v[196:199], v[6:9]
	v_mfma_f32_16x16x32_bf16 v[2:5], v[212:215], v[196:199], v[2:5]
	s_add_u32 s49, s49, 0x100
	s_addc_u32 s50, s50, 0
	s_add_u32 s10, s10, 0x10000
	s_addc_u32 s11, s11, 0
	s_cmp_ge_i32 s51, s34
	s_mov_b32 s12, s51
	s_barrier
	s_cbranch_scc0 .LBB0_592

.LBB0_624:
	s_add_i32 s47, s16, 2
	s_add_u32 s17, s14, 0xfffc0080
	s_addc_u32 s18, s15, -1
	s_add_i32 s48, 0, 0x10000
	v_add_u32_e32 v102, s48, v171
	ds_read_b128 v[82:85], v102
	ds_read_b128 v[86:89], v102 offset:1024
	ds_read_b128 v[98:101], v102 offset:2048
	ds_read_b128 v[102:105], v102 offset:3072
	s_cmp_eq_u32 s39, s16
	s_cselect_b32 s16, s44, s45
	s_cselect_b32 s19, s5, s18
	s_cselect_b32 s18, s7, s17
	s_cselect_b32 s17, s43, s46
	v_lshl_add_u64 v[160:161], s[14:15], 0, v[154:155]
	s_add_i32 m0, s13, 0xc000
	ds_read_b128 v[174:177], v173
	ds_read_b128 v[178:181], v173 offset:1024
	ds_read_b128 v[182:185], v173 offset:2048
	ds_read_b128 v[186:189], v173 offset:3072
	ds_read_b128 v[190:193], v173 offset:4096
	ds_read_b128 v[194:197], v173 offset:5120
	ds_read_b128 v[198:201], v173 offset:6144
	ds_read_b128 v[202:205], v173 offset:7168
	global_load_lds_dwordx4 v[160:161], off
	v_lshl_add_u64 v[160:161], s[14:15], 0, v[156:157]
	s_add_i32 m0, s13, 0xe000
	s_nop 0
	global_load_lds_dwordx4 v[160:161], off
	s_waitcnt lgkmcnt(8)
	s_barrier
	s_waitcnt lgkmcnt(0)
	s_waitcnt lgkmcnt(0)
	v_mfma_f32_16x16x32_bf16 v[138:141], v[82:85], v[174:177], v[138:141]
	v_mfma_f32_16x16x32_bf16 v[134:137], v[98:101], v[174:177], v[134:137]
	v_mfma_f32_16x16x32_bf16 v[126:129], v[82:85], v[182:185], v[126:129]
	v_mfma_f32_16x16x32_bf16 v[118:121], v[98:101], v[182:185], v[118:121]
	v_mfma_f32_16x16x32_bf16 v[110:113], v[82:85], v[190:193], v[110:113]
	v_mfma_f32_16x16x32_bf16 v[94:97], v[98:101], v[190:193], v[94:97]
	v_mfma_f32_16x16x32_bf16 v[78:81], v[82:85], v[198:201], v[78:81]
	v_mfma_f32_16x16x32_bf16 v[70:73], v[98:101], v[198:201], v[70:73]
	v_mfma_f32_16x16x32_bf16 v[138:141], v[86:89], v[178:181], v[138:141]
	v_mfma_f32_16x16x32_bf16 v[134:137], v[102:105], v[178:181], v[134:137]
	v_mfma_f32_16x16x32_bf16 v[126:129], v[86:89], v[186:189], v[126:129]
	v_mfma_f32_16x16x32_bf16 v[118:121], v[102:105], v[186:189], v[118:121]
	v_mfma_f32_16x16x32_bf16 v[110:113], v[86:89], v[194:197], v[110:113]
	v_mfma_f32_16x16x32_bf16 v[94:97], v[102:105], v[194:197], v[94:97]
	v_mfma_f32_16x16x32_bf16 v[78:81], v[86:89], v[202:205], v[78:81]
	v_mfma_f32_16x16x32_bf16 v[70:73], v[102:105], v[202:205], v[70:73]
	s_barrier
	s_add_i32 s50, 0, 0x14000
	s_add_i32 s48, s48, s23
	v_add_u32_e32 v158, s50, v171
	v_lshl_add_u64 v[160:161], s[16:17], 0, v[150:151]
	s_mov_b32 m0, s48
	ds_read_b128 v[206:209], v158
	ds_read_b128 v[210:213], v158 offset:1024
	ds_read_b128 v[214:217], v158 offset:2048
	ds_read_b128 v[218:221], v158 offset:3072
	global_load_lds_dwordx4 v[160:161], off
	v_lshl_add_u64 v[236:237], s[16:17], 0, v[146:147]
	s_add_i32 m0, s48, 0x2000
	s_nop 0
	global_load_lds_dwordx4 v[236:237], off
	s_barrier
	s_waitcnt lgkmcnt(0)
	s_waitcnt lgkmcnt(0)
	v_mfma_f32_16x16x32_bf16 v[142:145], v[206:209], v[174:177], v[142:145]
	v_mfma_f32_16x16x32_bf16 v[130:133], v[214:217], v[174:177], v[130:133]
	v_mfma_f32_16x16x32_bf16 v[122:125], v[206:209], v[182:185], v[122:125]
	v_mfma_f32_16x16x32_bf16 v[114:117], v[214:217], v[182:185], v[114:117]
	v_mfma_f32_16x16x32_bf16 v[106:109], v[206:209], v[190:193], v[106:109]
	v_mfma_f32_16x16x32_bf16 v[90:93], v[214:217], v[190:193], v[90:93]
	v_mfma_f32_16x16x32_bf16 v[74:77], v[206:209], v[198:201], v[74:77]
	v_mfma_f32_16x16x32_bf16 v[66:69], v[214:217], v[198:201], v[66:69]
	v_mfma_f32_16x16x32_bf16 v[142:145], v[210:213], v[178:181], v[142:145]
	v_mfma_f32_16x16x32_bf16 v[130:133], v[218:221], v[178:181], v[130:133]
	v_mfma_f32_16x16x32_bf16 v[122:125], v[210:213], v[186:189], v[122:125]
	v_mfma_f32_16x16x32_bf16 v[114:117], v[218:221], v[186:189], v[114:117]
	v_mfma_f32_16x16x32_bf16 v[106:109], v[210:213], v[194:197], v[106:109]
	v_mfma_f32_16x16x32_bf16 v[90:93], v[218:221], v[194:197], v[90:93]
	v_mfma_f32_16x16x32_bf16 v[74:77], v[210:213], v[202:205], v[74:77]
	v_mfma_f32_16x16x32_bf16 v[66:69], v[218:221], v[202:205], v[66:69]
	s_mov_b32 m0, s13
	v_lshl_add_u64 v[238:239], s[18:19], 0, v[152:153]
	s_barrier
	ds_read_b128 v[174:177], v173 offset:16384
	ds_read_b128 v[178:181], v173 offset:17408
	ds_read_b128 v[182:185], v173 offset:18432
	ds_read_b128 v[186:189], v173 offset:19456
	ds_read_b128 v[190:193], v173 offset:20480
	ds_read_b128 v[194:197], v173 offset:21504
	ds_read_b128 v[198:201], v173 offset:22528
	ds_read_b128 v[202:205], v173 offset:23552
	global_load_lds_dwordx4 v[238:239], off
	v_lshl_add_u64 v[240:241], s[18:19], 0, v[148:149]
	s_mov_b32 m0, s25
	s_nop 0
	global_load_lds_dwordx4 v[240:241], off
	s_barrier
	s_waitcnt lgkmcnt(0)
	s_waitcnt lgkmcnt(0)
	v_mfma_f32_16x16x32_bf16 v[62:65], v[82:85], v[174:177], v[62:65]
	v_mfma_f32_16x16x32_bf16 v[54:57], v[98:101], v[174:177], v[54:57]
	v_mfma_f32_16x16x32_bf16 v[46:49], v[82:85], v[182:185], v[46:49]
	v_mfma_f32_16x16x32_bf16 v[38:41], v[98:101], v[182:185], v[38:41]
	v_mfma_f32_16x16x32_bf16 v[30:33], v[82:85], v[190:193], v[30:33]
	v_mfma_f32_16x16x32_bf16 v[22:25], v[98:101], v[190:193], v[22:25]
	v_mfma_f32_16x16x32_bf16 v[14:17], v[82:85], v[198:201], v[14:17]
	v_mfma_f32_16x16x32_bf16 v[6:9], v[98:101], v[198:201], v[6:9]
	v_mfma_f32_16x16x32_bf16 v[62:65], v[86:89], v[178:181], v[62:65]
	v_mfma_f32_16x16x32_bf16 v[54:57], v[102:105], v[178:181], v[54:57]
	v_mfma_f32_16x16x32_bf16 v[46:49], v[86:89], v[186:189], v[46:49]
	v_mfma_f32_16x16x32_bf16 v[38:41], v[102:105], v[186:189], v[38:41]
	v_mfma_f32_16x16x32_bf16 v[30:33], v[86:89], v[194:197], v[30:33]
	v_mfma_f32_16x16x32_bf16 v[22:25], v[102:105], v[194:197], v[22:25]
	v_mfma_f32_16x16x32_bf16 v[14:17], v[86:89], v[202:205], v[14:17]
	v_mfma_f32_16x16x32_bf16 v[6:9], v[102:105], v[202:205], v[6:9]
	s_barrier
	s_add_u32 s48, s16, 0x40000
	s_addc_u32 s49, s17, 0
	s_add_i32 s50, s50, s23
	v_lshl_add_u64 v[82:83], s[48:49], 0, v[150:151]
	s_mov_b32 m0, s50
	s_nop 0
	global_load_lds_dwordx4 v[82:83], off
	v_lshl_add_u64 v[82:83], s[48:49], 0, v[146:147]
	s_add_i32 m0, s50, 0x2000
	s_nop 0
	global_load_lds_dwordx4 v[82:83], off
	s_waitcnt vmcnt(6)
	s_barrier
	v_mfma_f32_16x16x32_bf16 v[58:61], v[206:209], v[174:177], v[58:61]
	v_mfma_f32_16x16x32_bf16 v[50:53], v[214:217], v[174:177], v[50:53]
	v_mfma_f32_16x16x32_bf16 v[42:45], v[206:209], v[182:185], v[42:45]
	v_mfma_f32_16x16x32_bf16 v[34:37], v[214:217], v[182:185], v[34:37]
	v_mfma_f32_16x16x32_bf16 v[26:29], v[206:209], v[190:193], v[26:29]
	v_mfma_f32_16x16x32_bf16 v[18:21], v[214:217], v[190:193], v[18:21]
	v_mfma_f32_16x16x32_bf16 v[10:13], v[206:209], v[198:201], v[10:13]
	v_mfma_f32_16x16x32_bf16 v[2:5], v[214:217], v[198:201], v[2:5]
	v_mfma_f32_16x16x32_bf16 v[58:61], v[210:213], v[178:181], v[58:61]
	v_mfma_f32_16x16x32_bf16 v[50:53], v[218:221], v[178:181], v[50:53]
	v_mfma_f32_16x16x32_bf16 v[42:45], v[210:213], v[186:189], v[42:45]
	v_mfma_f32_16x16x32_bf16 v[34:37], v[218:221], v[186:189], v[34:37]
	v_mfma_f32_16x16x32_bf16 v[26:29], v[210:213], v[194:197], v[26:29]
	v_mfma_f32_16x16x32_bf16 v[18:21], v[218:221], v[194:197], v[18:21]
	v_mfma_f32_16x16x32_bf16 v[10:13], v[210:213], v[202:205], v[10:13]
	v_mfma_f32_16x16x32_bf16 v[2:5], v[218:221], v[202:205], v[2:5]
	s_add_i32 s48, 0, 0x18000
	v_add_u32_e32 v102, s48, v171
	s_barrier
	ds_read_b128 v[82:85], v102
	ds_read_b128 v[86:89], v102 offset:1024
	ds_read_b128 v[98:101], v102 offset:2048
	ds_read_b128 v[102:105], v102 offset:3072
	s_add_u32 s18, s18, 0x40000
	s_addc_u32 s19, s19, 0
	s_mov_b32 m0, s26
	v_lshl_add_u64 v[206:207], s[18:19], 0, v[152:153]
	ds_read_b128 v[174:177], v173 offset:32768
	ds_read_b128 v[178:181], v173 offset:33792
	ds_read_b128 v[182:185], v173 offset:34816
	ds_read_b128 v[186:189], v173 offset:35840
	ds_read_b128 v[190:193], v173 offset:36864
	ds_read_b128 v[194:197], v173 offset:37888
	ds_read_b128 v[198:201], v173 offset:38912
	ds_read_b128 v[202:205], v173 offset:39936
	global_load_lds_dwordx4 v[206:207], off
	v_lshl_add_u64 v[206:207], s[18:19], 0, v[148:149]
	s_mov_b32 m0, s27
	s_nop 0
	global_load_lds_dwordx4 v[206:207], off
	s_waitcnt lgkmcnt(8)
	s_barrier
	s_waitcnt lgkmcnt(0)
	s_waitcnt lgkmcnt(0)
	v_mfma_f32_16x16x32_bf16 v[138:141], v[82:85], v[174:177], v[138:141]
	v_mfma_f32_16x16x32_bf16 v[134:137], v[98:101], v[174:177], v[134:137]
	v_mfma_f32_16x16x32_bf16 v[126:129], v[82:85], v[182:185], v[126:129]
	v_mfma_f32_16x16x32_bf16 v[118:121], v[98:101], v[182:185], v[118:121]
	v_mfma_f32_16x16x32_bf16 v[110:113], v[82:85], v[190:193], v[110:113]
	v_mfma_f32_16x16x32_bf16 v[94:97], v[98:101], v[190:193], v[94:97]
	v_mfma_f32_16x16x32_bf16 v[78:81], v[82:85], v[198:201], v[78:81]
	v_mfma_f32_16x16x32_bf16 v[70:73], v[98:101], v[198:201], v[70:73]
	v_mfma_f32_16x16x32_bf16 v[138:141], v[86:89], v[178:181], v[138:141]
	v_mfma_f32_16x16x32_bf16 v[134:137], v[102:105], v[178:181], v[134:137]
	v_mfma_f32_16x16x32_bf16 v[126:129], v[86:89], v[186:189], v[126:129]
	v_mfma_f32_16x16x32_bf16 v[118:121], v[102:105], v[186:189], v[118:121]
	v_mfma_f32_16x16x32_bf16 v[110:113], v[86:89], v[194:197], v[110:113]
	v_mfma_f32_16x16x32_bf16 v[94:97], v[102:105], v[194:197], v[94:97]
	v_mfma_f32_16x16x32_bf16 v[78:81], v[86:89], v[202:205], v[78:81]
	v_mfma_f32_16x16x32_bf16 v[70:73], v[102:105], v[202:205], v[70:73]
	s_barrier
	s_add_i32 s18, 0, 0x1c000
	s_add_i32 s19, s48, s23
	v_add_u32_e32 v158, s18, v171
	v_lshl_add_u64 v[160:161], v[160:161], 0, s[84:85]
	s_mov_b32 m0, s19
	ds_read_b128 v[206:209], v158
	ds_read_b128 v[210:213], v158 offset:1024
	ds_read_b128 v[214:217], v158 offset:2048
	ds_read_b128 v[218:221], v158 offset:3072
	global_load_lds_dwordx4 v[160:161], off
	v_lshl_add_u64 v[160:161], v[236:237], 0, s[84:85]
	s_add_i32 m0, s19, 0x2000
	s_nop 0
	global_load_lds_dwordx4 v[160:161], off
	s_barrier
	s_waitcnt lgkmcnt(0)
	s_waitcnt lgkmcnt(0)
	v_mfma_f32_16x16x32_bf16 v[142:145], v[206:209], v[174:177], v[142:145]
	v_mfma_f32_16x16x32_bf16 v[130:133], v[214:217], v[174:177], v[130:133]
	v_mfma_f32_16x16x32_bf16 v[122:125], v[206:209], v[182:185], v[122:125]
	v_mfma_f32_16x16x32_bf16 v[114:117], v[214:217], v[182:185], v[114:117]
	v_mfma_f32_16x16x32_bf16 v[106:109], v[206:209], v[190:193], v[106:109]
	v_mfma_f32_16x16x32_bf16 v[90:93], v[214:217], v[190:193], v[90:93]
	v_mfma_f32_16x16x32_bf16 v[74:77], v[206:209], v[198:201], v[74:77]
	v_mfma_f32_16x16x32_bf16 v[66:69], v[214:217], v[198:201], v[66:69]
	v_mfma_f32_16x16x32_bf16 v[142:145], v[210:213], v[178:181], v[142:145]
	v_mfma_f32_16x16x32_bf16 v[130:133], v[218:221], v[178:181], v[130:133]
	v_mfma_f32_16x16x32_bf16 v[122:125], v[210:213], v[186:189], v[122:125]
	v_mfma_f32_16x16x32_bf16 v[114:117], v[218:221], v[186:189], v[114:117]
	v_mfma_f32_16x16x32_bf16 v[106:109], v[210:213], v[194:197], v[106:109]
	v_mfma_f32_16x16x32_bf16 v[90:93], v[218:221], v[194:197], v[90:93]
	v_mfma_f32_16x16x32_bf16 v[74:77], v[210:213], v[202:205], v[74:77]
	v_mfma_f32_16x16x32_bf16 v[66:69], v[218:221], v[202:205], v[66:69]
	s_mov_b32 m0, s35
	v_lshl_add_u64 v[160:161], v[238:239], 0, s[84:85]
	s_barrier
	ds_read_b128 v[174:177], v173 offset:49152
	ds_read_b128 v[178:181], v173 offset:50176
	ds_read_b128 v[182:185], v173 offset:51200
	ds_read_b128 v[186:189], v173 offset:52224
	ds_read_b128 v[190:193], v173 offset:53248
	ds_read_b128 v[194:197], v173 offset:54272
	ds_read_b128 v[198:201], v173 offset:55296
	ds_read_b128 v[202:205], v173 offset:56320
	global_load_lds_dwordx4 v[160:161], off
	v_lshl_add_u64 v[160:161], v[240:241], 0, s[84:85]
	s_mov_b32 m0, s38
	s_nop 0
	global_load_lds_dwordx4 v[160:161], off
	s_barrier
	s_waitcnt lgkmcnt(0)
	s_waitcnt lgkmcnt(0)
	v_mfma_f32_16x16x32_bf16 v[62:65], v[82:85], v[174:177], v[62:65]
	v_mfma_f32_16x16x32_bf16 v[54:57], v[98:101], v[174:177], v[54:57]
	v_mfma_f32_16x16x32_bf16 v[46:49], v[82:85], v[182:185], v[46:49]
	v_mfma_f32_16x16x32_bf16 v[38:41], v[98:101], v[182:185], v[38:41]
	v_mfma_f32_16x16x32_bf16 v[30:33], v[82:85], v[190:193], v[30:33]
	v_mfma_f32_16x16x32_bf16 v[22:25], v[98:101], v[190:193], v[22:25]
	v_mfma_f32_16x16x32_bf16 v[14:17], v[82:85], v[198:201], v[14:17]
	v_mfma_f32_16x16x32_bf16 v[6:9], v[98:101], v[198:201], v[6:9]
	v_mfma_f32_16x16x32_bf16 v[62:65], v[86:89], v[178:181], v[62:65]
	v_mfma_f32_16x16x32_bf16 v[54:57], v[102:105], v[178:181], v[54:57]
	v_mfma_f32_16x16x32_bf16 v[46:49], v[86:89], v[186:189], v[46:49]
	v_mfma_f32_16x16x32_bf16 v[38:41], v[102:105], v[186:189], v[38:41]
	v_mfma_f32_16x16x32_bf16 v[30:33], v[86:89], v[194:197], v[30:33]
	v_mfma_f32_16x16x32_bf16 v[22:25], v[102:105], v[194:197], v[22:25]
	v_mfma_f32_16x16x32_bf16 v[14:17], v[86:89], v[202:205], v[14:17]
	v_mfma_f32_16x16x32_bf16 v[6:9], v[102:105], v[202:205], v[6:9]
	s_barrier
	s_add_u32 s16, s16, 0x40080
	s_addc_u32 s17, s17, 0
	s_add_i32 s18, s18, s23
	v_lshl_add_u64 v[82:83], s[16:17], 0, v[150:151]
	s_mov_b32 m0, s18
	s_nop 0
	global_load_lds_dwordx4 v[82:83], off
	v_lshl_add_u64 v[82:83], s[16:17], 0, v[146:147]
	s_add_i32 m0, s18, 0x2000
	s_nop 0
	global_load_lds_dwordx4 v[82:83], off
	s_waitcnt vmcnt(6)
	s_barrier
	v_mfma_f32_16x16x32_bf16 v[58:61], v[206:209], v[174:177], v[58:61]
	v_mfma_f32_16x16x32_bf16 v[50:53], v[214:217], v[174:177], v[50:53]
	v_mfma_f32_16x16x32_bf16 v[42:45], v[206:209], v[182:185], v[42:45]
	v_mfma_f32_16x16x32_bf16 v[34:37], v[214:217], v[182:185], v[34:37]
	v_mfma_f32_16x16x32_bf16 v[26:29], v[206:209], v[190:193], v[26:29]
	v_mfma_f32_16x16x32_bf16 v[18:21], v[214:217], v[190:193], v[18:21]
	v_mfma_f32_16x16x32_bf16 v[10:13], v[206:209], v[198:201], v[10:13]
	v_mfma_f32_16x16x32_bf16 v[2:5], v[214:217], v[198:201], v[2:5]
	v_mfma_f32_16x16x32_bf16 v[58:61], v[210:213], v[178:181], v[58:61]
	v_mfma_f32_16x16x32_bf16 v[50:53], v[218:221], v[178:181], v[50:53]
	v_mfma_f32_16x16x32_bf16 v[42:45], v[210:213], v[186:189], v[42:45]
	v_mfma_f32_16x16x32_bf16 v[34:37], v[218:221], v[186:189], v[34:37]
	v_mfma_f32_16x16x32_bf16 v[26:29], v[210:213], v[194:197], v[26:29]
	v_mfma_f32_16x16x32_bf16 v[18:21], v[218:221], v[194:197], v[18:21]
	v_mfma_f32_16x16x32_bf16 v[10:13], v[210:213], v[202:205], v[10:13]
	v_mfma_f32_16x16x32_bf16 v[2:5], v[218:221], v[202:205], v[2:5]
	s_add_u32 s14, s14, 0x100
	s_addc_u32 s15, s15, 0
	s_add_u32 s45, s45, 0x100
	s_addc_u32 s46, s46, 0
	s_cmp_ge_i32 s47, s30
	s_mov_b32 s16, s47
	s_barrier
	s_cbranch_scc0 .LBB0_624
	s_branch .LBB0_619

.LBB0_649:
	s_add_i32 s51, s18, 2
	s_add_u32 s19, s0, 0xfffc0080
	s_addc_u32 s20, s1, -1
	s_add_i32 s52, 0, 0x10000
	v_add_u32_e32 v122, s52, v206
	ds_read_b128 v[90:93], v122
	ds_read_b128 v[102:105], v122 offset:1024
	ds_read_b128 v[110:113], v122 offset:2048
	ds_read_b128 v[122:125], v122 offset:3072
	s_cmp_eq_u32 s43, s18
	s_cselect_b32 s18, s48, s49
	s_cselect_b32 s21, s7, s20
	s_cselect_b32 s20, s9, s19
	s_cselect_b32 s19, s47, s50
	v_lshl_add_u64 v[200:201], s[0:1], 0, v[172:173]
	s_add_i32 m0, s15, 0xc000
	ds_read_b128 v[146:149], v207
	ds_read_b128 v[150:153], v207 offset:1024
	ds_read_b128 v[176:179], v207 offset:2048
	ds_read_b128 v[180:183], v207 offset:3072
	ds_read_b128 v[184:187], v207 offset:4096
	ds_read_b128 v[188:191], v207 offset:5120
	ds_read_b128 v[192:195], v207 offset:6144
	ds_read_b128 v[196:199], v207 offset:7168
	global_load_lds_dwordx4 v[200:201], off
	v_lshl_add_u64 v[200:201], s[0:1], 0, v[174:175]
	s_add_i32 m0, s15, 0xe000
	s_nop 0
	global_load_lds_dwordx4 v[200:201], off
	s_waitcnt lgkmcnt(8)
	s_barrier
	s_waitcnt lgkmcnt(0)
	s_waitcnt lgkmcnt(0)
	v_mfma_f32_16x16x32_bf16 v[142:145], v[90:93], v[146:149], v[142:145]
	v_mfma_f32_16x16x32_bf16 v[138:141], v[110:113], v[146:149], v[138:141]
	v_mfma_f32_16x16x32_bf16 v[126:129], v[90:93], v[176:179], v[126:129]
	v_mfma_f32_16x16x32_bf16 v[118:121], v[110:113], v[176:179], v[118:121]
	v_mfma_f32_16x16x32_bf16 v[98:101], v[90:93], v[184:187], v[98:101]
	v_mfma_f32_16x16x32_bf16 v[94:97], v[110:113], v[184:187], v[94:97]
	v_mfma_f32_16x16x32_bf16 v[78:81], v[90:93], v[192:195], v[78:81]
	v_mfma_f32_16x16x32_bf16 v[74:77], v[110:113], v[192:195], v[74:77]
	v_mfma_f32_16x16x32_bf16 v[142:145], v[102:105], v[150:153], v[142:145]
	v_mfma_f32_16x16x32_bf16 v[138:141], v[122:125], v[150:153], v[138:141]
	v_mfma_f32_16x16x32_bf16 v[126:129], v[102:105], v[180:183], v[126:129]
	v_mfma_f32_16x16x32_bf16 v[118:121], v[122:125], v[180:183], v[118:121]
	v_mfma_f32_16x16x32_bf16 v[98:101], v[102:105], v[188:191], v[98:101]
	v_mfma_f32_16x16x32_bf16 v[94:97], v[122:125], v[188:191], v[94:97]
	v_mfma_f32_16x16x32_bf16 v[78:81], v[102:105], v[196:199], v[78:81]
	v_mfma_f32_16x16x32_bf16 v[74:77], v[122:125], v[196:199], v[74:77]
	s_barrier
	s_add_i32 s54, 0, 0x14000
	s_add_i32 s52, s52, s27
	v_add_u32_e32 v168, s54, v206
	v_lshl_add_u64 v[204:205], s[18:19], 0, v[156:157]
	s_mov_b32 m0, s52
	ds_read_b128 v[200:203], v168
	ds_read_b128 v[208:211], v168 offset:1024
	ds_read_b128 v[212:215], v168 offset:2048
	ds_read_b128 v[216:219], v168 offset:3072
	global_load_lds_dwordx4 v[204:205], off
	v_lshl_add_u64 v[220:221], s[18:19], 0, v[160:161]
	s_add_i32 m0, s52, 0x2000
	s_nop 0
	global_load_lds_dwordx4 v[220:221], off
	s_barrier
	s_waitcnt lgkmcnt(0)
	s_waitcnt lgkmcnt(0)
	v_mfma_f32_16x16x32_bf16 v[134:137], v[200:203], v[146:149], v[134:137]
	v_mfma_f32_16x16x32_bf16 v[130:133], v[212:215], v[146:149], v[130:133]
	v_mfma_f32_16x16x32_bf16 v[114:117], v[200:203], v[176:179], v[114:117]
	v_mfma_f32_16x16x32_bf16 v[106:109], v[212:215], v[176:179], v[106:109]
	v_mfma_f32_16x16x32_bf16 v[86:89], v[200:203], v[184:187], v[86:89]
	v_mfma_f32_16x16x32_bf16 v[82:85], v[212:215], v[184:187], v[82:85]
	v_mfma_f32_16x16x32_bf16 v[70:73], v[200:203], v[192:195], v[70:73]
	v_mfma_f32_16x16x32_bf16 v[66:69], v[212:215], v[192:195], v[66:69]
	v_mfma_f32_16x16x32_bf16 v[134:137], v[208:211], v[150:153], v[134:137]
	v_mfma_f32_16x16x32_bf16 v[130:133], v[216:219], v[150:153], v[130:133]
	v_mfma_f32_16x16x32_bf16 v[114:117], v[208:211], v[180:183], v[114:117]
	v_mfma_f32_16x16x32_bf16 v[106:109], v[216:219], v[180:183], v[106:109]
	v_mfma_f32_16x16x32_bf16 v[86:89], v[208:211], v[188:191], v[86:89]
	v_mfma_f32_16x16x32_bf16 v[82:85], v[216:219], v[188:191], v[82:85]
	v_mfma_f32_16x16x32_bf16 v[70:73], v[208:211], v[196:199], v[70:73]
	v_mfma_f32_16x16x32_bf16 v[66:69], v[216:219], v[196:199], v[66:69]
	s_mov_b32 m0, s15
	v_lshl_add_u64 v[236:237], s[20:21], 0, v[154:155]
	s_barrier
	ds_read_b128 v[146:149], v207 offset:16384
	ds_read_b128 v[150:153], v207 offset:17408
	ds_read_b128 v[176:179], v207 offset:18432
	ds_read_b128 v[180:183], v207 offset:19456
	ds_read_b128 v[184:187], v207 offset:20480
	ds_read_b128 v[188:191], v207 offset:21504
	ds_read_b128 v[192:195], v207 offset:22528
	ds_read_b128 v[196:199], v207 offset:23552
	global_load_lds_dwordx4 v[236:237], off
	v_lshl_add_u64 v[238:239], s[20:21], 0, v[158:159]
	s_mov_b32 m0, s17
	s_nop 0
	global_load_lds_dwordx4 v[238:239], off
	s_barrier
	s_waitcnt lgkmcnt(0)
	s_waitcnt lgkmcnt(0)
	v_mfma_f32_16x16x32_bf16 v[62:65], v[90:93], v[146:149], v[62:65]
	v_mfma_f32_16x16x32_bf16 v[58:61], v[110:113], v[146:149], v[58:61]
	v_mfma_f32_16x16x32_bf16 v[46:49], v[90:93], v[176:179], v[46:49]
	v_mfma_f32_16x16x32_bf16 v[42:45], v[110:113], v[176:179], v[42:45]
	v_mfma_f32_16x16x32_bf16 v[30:33], v[90:93], v[184:187], v[30:33]
	v_mfma_f32_16x16x32_bf16 v[26:29], v[110:113], v[184:187], v[26:29]
	v_mfma_f32_16x16x32_bf16 v[14:17], v[90:93], v[192:195], v[14:17]
	v_mfma_f32_16x16x32_bf16 v[10:13], v[110:113], v[192:195], v[10:13]
	v_mfma_f32_16x16x32_bf16 v[62:65], v[102:105], v[150:153], v[62:65]
	v_mfma_f32_16x16x32_bf16 v[58:61], v[122:125], v[150:153], v[58:61]
	v_mfma_f32_16x16x32_bf16 v[46:49], v[102:105], v[180:183], v[46:49]
	v_mfma_f32_16x16x32_bf16 v[42:45], v[122:125], v[180:183], v[42:45]
	v_mfma_f32_16x16x32_bf16 v[30:33], v[102:105], v[188:191], v[30:33]
	v_mfma_f32_16x16x32_bf16 v[26:29], v[122:125], v[188:191], v[26:29]
	v_mfma_f32_16x16x32_bf16 v[14:17], v[102:105], v[196:199], v[14:17]
	v_mfma_f32_16x16x32_bf16 v[10:13], v[122:125], v[196:199], v[10:13]
	s_barrier
	s_add_u32 s52, s18, 0x40000
	s_addc_u32 s53, s19, 0
	s_add_i32 s54, s54, s27
	v_lshl_add_u64 v[90:91], s[52:53], 0, v[156:157]
	s_mov_b32 m0, s54
	s_nop 0
	global_load_lds_dwordx4 v[90:91], off
	v_lshl_add_u64 v[90:91], s[52:53], 0, v[160:161]
	s_add_i32 m0, s54, 0x2000
	s_nop 0
	global_load_lds_dwordx4 v[90:91], off
	s_waitcnt vmcnt(6)
	s_barrier
	v_mfma_f32_16x16x32_bf16 v[54:57], v[200:203], v[146:149], v[54:57]
	v_mfma_f32_16x16x32_bf16 v[50:53], v[212:215], v[146:149], v[50:53]
	v_mfma_f32_16x16x32_bf16 v[38:41], v[200:203], v[176:179], v[38:41]
	v_mfma_f32_16x16x32_bf16 v[34:37], v[212:215], v[176:179], v[34:37]
	v_mfma_f32_16x16x32_bf16 v[22:25], v[200:203], v[184:187], v[22:25]
	v_mfma_f32_16x16x32_bf16 v[18:21], v[212:215], v[184:187], v[18:21]
	v_mfma_f32_16x16x32_bf16 v[6:9], v[200:203], v[192:195], v[6:9]
	v_mfma_f32_16x16x32_bf16 v[2:5], v[212:215], v[192:195], v[2:5]
	v_mfma_f32_16x16x32_bf16 v[54:57], v[208:211], v[150:153], v[54:57]
	v_mfma_f32_16x16x32_bf16 v[50:53], v[216:219], v[150:153], v[50:53]
	v_mfma_f32_16x16x32_bf16 v[38:41], v[208:211], v[180:183], v[38:41]
	v_mfma_f32_16x16x32_bf16 v[34:37], v[216:219], v[180:183], v[34:37]
	v_mfma_f32_16x16x32_bf16 v[22:25], v[208:211], v[188:191], v[22:25]
	v_mfma_f32_16x16x32_bf16 v[18:21], v[216:219], v[188:191], v[18:21]
	v_mfma_f32_16x16x32_bf16 v[6:9], v[208:211], v[196:199], v[6:9]
	v_mfma_f32_16x16x32_bf16 v[2:5], v[216:219], v[196:199], v[2:5]
	s_add_i32 s52, 0, 0x18000
	v_add_u32_e32 v122, s52, v206
	s_barrier
	ds_read_b128 v[90:93], v122
	ds_read_b128 v[102:105], v122 offset:1024
	ds_read_b128 v[110:113], v122 offset:2048
	ds_read_b128 v[122:125], v122 offset:3072
	s_add_u32 s20, s20, 0x40000
	s_addc_u32 s21, s21, 0
	s_mov_b32 m0, s28
	v_lshl_add_u64 v[200:201], s[20:21], 0, v[154:155]
	ds_read_b128 v[146:149], v207 offset:32768
	ds_read_b128 v[150:153], v207 offset:33792
	ds_read_b128 v[176:179], v207 offset:34816
	ds_read_b128 v[180:183], v207 offset:35840
	ds_read_b128 v[184:187], v207 offset:36864
	ds_read_b128 v[188:191], v207 offset:37888
	ds_read_b128 v[192:195], v207 offset:38912
	ds_read_b128 v[196:199], v207 offset:39936
	global_load_lds_dwordx4 v[200:201], off
	v_lshl_add_u64 v[200:201], s[20:21], 0, v[158:159]
	s_mov_b32 m0, s29
	s_nop 0
	global_load_lds_dwordx4 v[200:201], off
	s_waitcnt lgkmcnt(8)
	s_barrier
	s_waitcnt lgkmcnt(0)
	s_waitcnt lgkmcnt(0)
	v_mfma_f32_16x16x32_bf16 v[142:145], v[90:93], v[146:149], v[142:145]
	v_mfma_f32_16x16x32_bf16 v[138:141], v[110:113], v[146:149], v[138:141]
	v_mfma_f32_16x16x32_bf16 v[126:129], v[90:93], v[176:179], v[126:129]
	v_mfma_f32_16x16x32_bf16 v[118:121], v[110:113], v[176:179], v[118:121]
	v_mfma_f32_16x16x32_bf16 v[98:101], v[90:93], v[184:187], v[98:101]
	v_mfma_f32_16x16x32_bf16 v[94:97], v[110:113], v[184:187], v[94:97]
	v_mfma_f32_16x16x32_bf16 v[78:81], v[90:93], v[192:195], v[78:81]
	v_mfma_f32_16x16x32_bf16 v[74:77], v[110:113], v[192:195], v[74:77]
	v_mfma_f32_16x16x32_bf16 v[142:145], v[102:105], v[150:153], v[142:145]
	v_mfma_f32_16x16x32_bf16 v[138:141], v[122:125], v[150:153], v[138:141]
	v_mfma_f32_16x16x32_bf16 v[126:129], v[102:105], v[180:183], v[126:129]
	v_mfma_f32_16x16x32_bf16 v[118:121], v[122:125], v[180:183], v[118:121]
	v_mfma_f32_16x16x32_bf16 v[98:101], v[102:105], v[188:191], v[98:101]
	v_mfma_f32_16x16x32_bf16 v[94:97], v[122:125], v[188:191], v[94:97]
	v_mfma_f32_16x16x32_bf16 v[78:81], v[102:105], v[196:199], v[78:81]
	v_mfma_f32_16x16x32_bf16 v[74:77], v[122:125], v[196:199], v[74:77]
	s_barrier
	s_add_i32 s20, 0, 0x1c000
	s_add_i32 s21, s52, s27
	v_add_u32_e32 v168, s20, v206
	v_lshl_add_u64 v[204:205], v[204:205], 0, s[84:85]
	s_mov_b32 m0, s21
	ds_read_b128 v[200:203], v168
	ds_read_b128 v[208:211], v168 offset:1024
	ds_read_b128 v[212:215], v168 offset:2048
	ds_read_b128 v[216:219], v168 offset:3072
	global_load_lds_dwordx4 v[204:205], off
	v_lshl_add_u64 v[204:205], v[220:221], 0, s[84:85]
	s_add_i32 m0, s21, 0x2000
	s_nop 0
	global_load_lds_dwordx4 v[204:205], off
	s_barrier
	s_waitcnt lgkmcnt(0)
	s_waitcnt lgkmcnt(0)
	v_mfma_f32_16x16x32_bf16 v[134:137], v[200:203], v[146:149], v[134:137]
	v_mfma_f32_16x16x32_bf16 v[130:133], v[212:215], v[146:149], v[130:133]
	v_mfma_f32_16x16x32_bf16 v[114:117], v[200:203], v[176:179], v[114:117]
	v_mfma_f32_16x16x32_bf16 v[106:109], v[212:215], v[176:179], v[106:109]
	v_mfma_f32_16x16x32_bf16 v[86:89], v[200:203], v[184:187], v[86:89]
	v_mfma_f32_16x16x32_bf16 v[82:85], v[212:215], v[184:187], v[82:85]
	v_mfma_f32_16x16x32_bf16 v[70:73], v[200:203], v[192:195], v[70:73]
	v_mfma_f32_16x16x32_bf16 v[66:69], v[212:215], v[192:195], v[66:69]
	v_mfma_f32_16x16x32_bf16 v[134:137], v[208:211], v[150:153], v[134:137]
	v_mfma_f32_16x16x32_bf16 v[130:133], v[216:219], v[150:153], v[130:133]
	v_mfma_f32_16x16x32_bf16 v[114:117], v[208:211], v[180:183], v[114:117]
	v_mfma_f32_16x16x32_bf16 v[106:109], v[216:219], v[180:183], v[106:109]
	v_mfma_f32_16x16x32_bf16 v[86:89], v[208:211], v[188:191], v[86:89]
	v_mfma_f32_16x16x32_bf16 v[82:85], v[216:219], v[188:191], v[82:85]
	v_mfma_f32_16x16x32_bf16 v[70:73], v[208:211], v[196:199], v[70:73]
	v_mfma_f32_16x16x32_bf16 v[66:69], v[216:219], v[196:199], v[66:69]
	s_mov_b32 m0, s41
	v_lshl_add_u64 v[204:205], v[236:237], 0, s[84:85]
	s_barrier
	ds_read_b128 v[146:149], v207 offset:49152
	ds_read_b128 v[150:153], v207 offset:50176
	ds_read_b128 v[176:179], v207 offset:51200
	ds_read_b128 v[180:183], v207 offset:52224
	ds_read_b128 v[184:187], v207 offset:53248
	ds_read_b128 v[188:191], v207 offset:54272
	ds_read_b128 v[192:195], v207 offset:55296
	ds_read_b128 v[196:199], v207 offset:56320
	global_load_lds_dwordx4 v[204:205], off
	v_lshl_add_u64 v[204:205], v[238:239], 0, s[84:85]
	s_mov_b32 m0, s42
	s_nop 0
	global_load_lds_dwordx4 v[204:205], off
	s_barrier
	s_waitcnt lgkmcnt(0)
	s_waitcnt lgkmcnt(0)
	v_mfma_f32_16x16x32_bf16 v[62:65], v[90:93], v[146:149], v[62:65]
	v_mfma_f32_16x16x32_bf16 v[58:61], v[110:113], v[146:149], v[58:61]
	v_mfma_f32_16x16x32_bf16 v[46:49], v[90:93], v[176:179], v[46:49]
	v_mfma_f32_16x16x32_bf16 v[42:45], v[110:113], v[176:179], v[42:45]
	v_mfma_f32_16x16x32_bf16 v[30:33], v[90:93], v[184:187], v[30:33]
	v_mfma_f32_16x16x32_bf16 v[26:29], v[110:113], v[184:187], v[26:29]
	v_mfma_f32_16x16x32_bf16 v[14:17], v[90:93], v[192:195], v[14:17]
	v_mfma_f32_16x16x32_bf16 v[10:13], v[110:113], v[192:195], v[10:13]
	v_mfma_f32_16x16x32_bf16 v[62:65], v[102:105], v[150:153], v[62:65]
	v_mfma_f32_16x16x32_bf16 v[58:61], v[122:125], v[150:153], v[58:61]
	v_mfma_f32_16x16x32_bf16 v[46:49], v[102:105], v[180:183], v[46:49]
	v_mfma_f32_16x16x32_bf16 v[42:45], v[122:125], v[180:183], v[42:45]
	v_mfma_f32_16x16x32_bf16 v[30:33], v[102:105], v[188:191], v[30:33]
	v_mfma_f32_16x16x32_bf16 v[26:29], v[122:125], v[188:191], v[26:29]
	v_mfma_f32_16x16x32_bf16 v[14:17], v[102:105], v[196:199], v[14:17]
	v_mfma_f32_16x16x32_bf16 v[10:13], v[122:125], v[196:199], v[10:13]
	s_barrier
	s_add_u32 s18, s18, 0x40080
	s_addc_u32 s19, s19, 0
	s_add_i32 s20, s20, s27
	v_lshl_add_u64 v[90:91], s[18:19], 0, v[156:157]
	s_mov_b32 m0, s20
	s_nop 0
	global_load_lds_dwordx4 v[90:91], off
	v_lshl_add_u64 v[90:91], s[18:19], 0, v[160:161]
	s_add_i32 m0, s20, 0x2000
	s_nop 0
	global_load_lds_dwordx4 v[90:91], off
	s_waitcnt vmcnt(6)
	s_barrier
	v_mfma_f32_16x16x32_bf16 v[54:57], v[200:203], v[146:149], v[54:57]
	v_mfma_f32_16x16x32_bf16 v[50:53], v[212:215], v[146:149], v[50:53]
	v_mfma_f32_16x16x32_bf16 v[38:41], v[200:203], v[176:179], v[38:41]
	v_mfma_f32_16x16x32_bf16 v[34:37], v[212:215], v[176:179], v[34:37]
	v_mfma_f32_16x16x32_bf16 v[22:25], v[200:203], v[184:187], v[22:25]
	v_mfma_f32_16x16x32_bf16 v[18:21], v[212:215], v[184:187], v[18:21]
	v_mfma_f32_16x16x32_bf16 v[6:9], v[200:203], v[192:195], v[6:9]
	v_mfma_f32_16x16x32_bf16 v[2:5], v[212:215], v[192:195], v[2:5]
	v_mfma_f32_16x16x32_bf16 v[54:57], v[208:211], v[150:153], v[54:57]
	v_mfma_f32_16x16x32_bf16 v[50:53], v[216:219], v[150:153], v[50:53]
	v_mfma_f32_16x16x32_bf16 v[38:41], v[208:211], v[180:183], v[38:41]
	v_mfma_f32_16x16x32_bf16 v[34:37], v[216:219], v[180:183], v[34:37]
	v_mfma_f32_16x16x32_bf16 v[22:25], v[208:211], v[188:191], v[22:25]
	v_mfma_f32_16x16x32_bf16 v[18:21], v[216:219], v[188:191], v[18:21]
	v_mfma_f32_16x16x32_bf16 v[6:9], v[208:211], v[196:199], v[6:9]
	v_mfma_f32_16x16x32_bf16 v[2:5], v[216:219], v[196:199], v[2:5]
	s_add_u32 s49, s49, 0x100
	s_addc_u32 s50, s50, 0
	s_add_u32 s0, s0, 0x100
	s_addc_u32 s1, s1, 0
	s_cmp_ge_i32 s51, s38
	s_mov_b32 s18, s51
	s_barrier
	s_cbranch_scc0 .LBB0_649

.LBB0_799:
	s_add_i32 s57, s26, 2
	s_add_u32 s27, s24, 0xfffc0080
	s_addc_u32 s28, s25, -1
	s_add_i32 s58, 0, 0x10000
	v_add_u32_e32 v46, s58, v205
	ds_read_b128 v[22:25], v46
	ds_read_b128 v[34:37], v46 offset:1024
	ds_read_b128 v[42:45], v46 offset:2048
	ds_read_b128 v[46:49], v46 offset:3072
	s_cmp_eq_u32 s49, s26
	s_cselect_b32 s26, s39, s55
	s_cselect_b32 s29, s13, s28
	s_cselect_b32 s28, s15, s27
	s_cselect_b32 s27, s21, s56
	v_lshl_add_u64 v[200:201], s[24:25], 0, v[176:177]
	s_add_i32 m0, s41, 0xc000
	ds_read_b128 v[146:149], v208
	ds_read_b128 v[150:153], v208 offset:1024
	ds_read_b128 v[154:157], v208 offset:2048
	ds_read_b128 v[180:183], v208 offset:3072
	ds_read_b128 v[184:187], v208 offset:4096
	ds_read_b128 v[188:191], v208 offset:5120
	ds_read_b128 v[192:195], v208 offset:6144
	ds_read_b128 v[196:199], v208 offset:7168
	global_load_lds_dwordx4 v[200:201], off
	v_lshl_add_u64 v[200:201], s[24:25], 0, v[178:179]
	s_add_i32 m0, s41, 0xe000
	s_nop 0
	global_load_lds_dwordx4 v[200:201], off
	s_waitcnt lgkmcnt(8)
	s_barrier
	s_waitcnt lgkmcnt(0)
	s_waitcnt lgkmcnt(0)
	v_mfma_f32_16x16x32_bf16 v[142:145], v[22:25], v[146:149], v[142:145]
	v_mfma_f32_16x16x32_bf16 v[134:137], v[42:45], v[146:149], v[134:137]
	v_mfma_f32_16x16x32_bf16 v[126:129], v[22:25], v[154:157], v[126:129]
	v_mfma_f32_16x16x32_bf16 v[118:121], v[42:45], v[154:157], v[118:121]
	v_mfma_f32_16x16x32_bf16 v[110:113], v[22:25], v[184:187], v[110:113]
	v_mfma_f32_16x16x32_bf16 v[102:105], v[42:45], v[184:187], v[102:105]
	v_mfma_f32_16x16x32_bf16 v[94:97], v[22:25], v[192:195], v[94:97]
	v_mfma_f32_16x16x32_bf16 v[86:89], v[42:45], v[192:195], v[86:89]
	v_mfma_f32_16x16x32_bf16 v[142:145], v[34:37], v[150:153], v[142:145]
	v_mfma_f32_16x16x32_bf16 v[134:137], v[46:49], v[150:153], v[134:137]
	v_mfma_f32_16x16x32_bf16 v[126:129], v[34:37], v[180:183], v[126:129]
	v_mfma_f32_16x16x32_bf16 v[118:121], v[46:49], v[180:183], v[118:121]
	v_mfma_f32_16x16x32_bf16 v[110:113], v[34:37], v[188:191], v[110:113]
	v_mfma_f32_16x16x32_bf16 v[102:105], v[46:49], v[188:191], v[102:105]
	v_mfma_f32_16x16x32_bf16 v[94:97], v[34:37], v[196:199], v[94:97]
	v_mfma_f32_16x16x32_bf16 v[86:89], v[46:49], v[196:199], v[86:89]
	s_barrier
	s_add_i32 s60, 0, 0x14000
	s_add_i32 s58, s58, s35
	v_add_u32_e32 v168, s60, v205
	v_lshl_add_u64 v[206:207], s[26:27], 0, v[172:173]
	s_mov_b32 m0, s58
	ds_read_b128 v[200:203], v168
	ds_read_b128 v[210:213], v168 offset:1024
	ds_read_b128 v[214:217], v168 offset:2048
	ds_read_b128 v[218:221], v168 offset:3072
	global_load_lds_dwordx4 v[206:207], off
	v_lshl_add_u64 v[236:237], s[26:27], 0, v[158:159]
	s_add_i32 m0, s58, 0x2000
	s_nop 0
	global_load_lds_dwordx4 v[236:237], off
	s_barrier
	s_waitcnt lgkmcnt(0)
	s_waitcnt lgkmcnt(0)
	v_mfma_f32_16x16x32_bf16 v[138:141], v[200:203], v[146:149], v[138:141]
	v_mfma_f32_16x16x32_bf16 v[130:133], v[214:217], v[146:149], v[130:133]
	v_mfma_f32_16x16x32_bf16 v[122:125], v[200:203], v[154:157], v[122:125]
	v_mfma_f32_16x16x32_bf16 v[114:117], v[214:217], v[154:157], v[114:117]
	v_mfma_f32_16x16x32_bf16 v[106:109], v[200:203], v[184:187], v[106:109]
	v_mfma_f32_16x16x32_bf16 v[98:101], v[214:217], v[184:187], v[98:101]
	v_mfma_f32_16x16x32_bf16 v[90:93], v[200:203], v[192:195], v[90:93]
	v_mfma_f32_16x16x32_bf16 v[82:85], v[214:217], v[192:195], v[82:85]
	v_mfma_f32_16x16x32_bf16 v[138:141], v[210:213], v[150:153], v[138:141]
	v_mfma_f32_16x16x32_bf16 v[130:133], v[218:221], v[150:153], v[130:133]
	v_mfma_f32_16x16x32_bf16 v[122:125], v[210:213], v[180:183], v[122:125]
	v_mfma_f32_16x16x32_bf16 v[114:117], v[218:221], v[180:183], v[114:117]
	v_mfma_f32_16x16x32_bf16 v[106:109], v[210:213], v[188:191], v[106:109]
	v_mfma_f32_16x16x32_bf16 v[98:101], v[218:221], v[188:191], v[98:101]
	v_mfma_f32_16x16x32_bf16 v[90:93], v[210:213], v[196:199], v[90:93]
	v_mfma_f32_16x16x32_bf16 v[82:85], v[218:221], v[196:199], v[82:85]
	s_mov_b32 m0, s41
	v_lshl_add_u64 v[238:239], s[28:29], 0, v[174:175]
	s_barrier
	ds_read_b128 v[146:149], v208 offset:16384
	ds_read_b128 v[150:153], v208 offset:17408
	ds_read_b128 v[154:157], v208 offset:18432
	ds_read_b128 v[180:183], v208 offset:19456
	ds_read_b128 v[184:187], v208 offset:20480
	ds_read_b128 v[188:191], v208 offset:21504
	ds_read_b128 v[192:195], v208 offset:22528
	ds_read_b128 v[196:199], v208 offset:23552
	global_load_lds_dwordx4 v[238:239], off
	v_lshl_add_u64 v[240:241], s[28:29], 0, v[160:161]
	s_mov_b32 m0, s42
	s_nop 0
	global_load_lds_dwordx4 v[240:241], off
	s_barrier
	s_waitcnt lgkmcnt(0)
	s_waitcnt lgkmcnt(0)
	v_mfma_f32_16x16x32_bf16 v[78:81], v[22:25], v[146:149], v[78:81]
	v_mfma_f32_16x16x32_bf16 v[70:73], v[42:45], v[146:149], v[70:73]
	v_mfma_f32_16x16x32_bf16 v[62:65], v[22:25], v[154:157], v[62:65]
	v_mfma_f32_16x16x32_bf16 v[54:57], v[42:45], v[154:157], v[54:57]
	v_mfma_f32_16x16x32_bf16 v[38:41], v[22:25], v[184:187], v[38:41]
	v_mfma_f32_16x16x32_bf16 v[26:29], v[42:45], v[184:187], v[26:29]
	v_mfma_f32_16x16x32_bf16 v[14:17], v[22:25], v[192:195], v[14:17]
	v_mfma_f32_16x16x32_bf16 v[6:9], v[42:45], v[192:195], v[6:9]
	v_mfma_f32_16x16x32_bf16 v[78:81], v[34:37], v[150:153], v[78:81]
	v_mfma_f32_16x16x32_bf16 v[70:73], v[46:49], v[150:153], v[70:73]
	v_mfma_f32_16x16x32_bf16 v[62:65], v[34:37], v[180:183], v[62:65]
	v_mfma_f32_16x16x32_bf16 v[54:57], v[46:49], v[180:183], v[54:57]
	v_mfma_f32_16x16x32_bf16 v[38:41], v[34:37], v[188:191], v[38:41]
	v_mfma_f32_16x16x32_bf16 v[26:29], v[46:49], v[188:191], v[26:29]
	v_mfma_f32_16x16x32_bf16 v[14:17], v[34:37], v[196:199], v[14:17]
	v_mfma_f32_16x16x32_bf16 v[6:9], v[46:49], v[196:199], v[6:9]
	s_barrier
	s_add_u32 s58, s26, 0x40000
	s_addc_u32 s59, s27, 0
	s_add_i32 s60, s60, s35
	v_lshl_add_u64 v[22:23], s[58:59], 0, v[172:173]
	s_mov_b32 m0, s60
	s_nop 0
	global_load_lds_dwordx4 v[22:23], off
	v_lshl_add_u64 v[22:23], s[58:59], 0, v[158:159]
	s_add_i32 m0, s60, 0x2000
	s_nop 0
	global_load_lds_dwordx4 v[22:23], off
	s_waitcnt vmcnt(6)
	s_barrier
	v_mfma_f32_16x16x32_bf16 v[30:33], v[200:203], v[184:187], v[30:33]
	v_mfma_f32_16x16x32_bf16 v[18:21], v[214:217], v[184:187], v[18:21]
	v_mfma_f32_16x16x32_bf16 v[10:13], v[200:203], v[192:195], v[10:13]
	v_mfma_f32_16x16x32_bf16 v[2:5], v[214:217], v[192:195], v[2:5]
	v_mfma_f32_16x16x32_bf16 v[22:25], v[200:203], v[146:149], v[74:77]
	v_mfma_f32_16x16x32_bf16 v[34:37], v[214:217], v[146:149], v[66:69]
	v_mfma_f32_16x16x32_bf16 v[42:45], v[200:203], v[154:157], v[58:61]
	v_mfma_f32_16x16x32_bf16 v[46:49], v[214:217], v[154:157], v[50:53]
	v_mfma_f32_16x16x32_bf16 v[30:33], v[210:213], v[188:191], v[30:33]
	v_mfma_f32_16x16x32_bf16 v[18:21], v[218:221], v[188:191], v[18:21]
	v_mfma_f32_16x16x32_bf16 v[10:13], v[210:213], v[196:199], v[10:13]
	v_mfma_f32_16x16x32_bf16 v[2:5], v[218:221], v[196:199], v[2:5]
	v_mfma_f32_16x16x32_bf16 v[22:25], v[210:213], v[150:153], v[22:25]
	v_mfma_f32_16x16x32_bf16 v[34:37], v[218:221], v[150:153], v[34:37]
	v_mfma_f32_16x16x32_bf16 v[42:45], v[210:213], v[180:183], v[42:45]
	v_mfma_f32_16x16x32_bf16 v[46:49], v[218:221], v[180:183], v[46:49]
	s_add_i32 s58, 0, 0x18000
	v_add_u32_e32 v74, s58, v205
	s_barrier
	ds_read_b128 v[50:53], v74
	ds_read_b128 v[58:61], v74 offset:1024
	ds_read_b128 v[66:69], v74 offset:2048
	ds_read_b128 v[74:77], v74 offset:3072
	s_add_u32 s28, s28, 0x40000
	s_addc_u32 s29, s29, 0
	s_mov_b32 m0, s43
	v_lshl_add_u64 v[200:201], s[28:29], 0, v[174:175]
	ds_read_b128 v[146:149], v208 offset:32768
	ds_read_b128 v[150:153], v208 offset:33792
	ds_read_b128 v[154:157], v208 offset:34816
	ds_read_b128 v[180:183], v208 offset:35840
	ds_read_b128 v[184:187], v208 offset:36864
	ds_read_b128 v[188:191], v208 offset:37888
	ds_read_b128 v[192:195], v208 offset:38912
	ds_read_b128 v[196:199], v208 offset:39936
	global_load_lds_dwordx4 v[200:201], off
	v_lshl_add_u64 v[200:201], s[28:29], 0, v[160:161]
	s_mov_b32 m0, s44
	s_nop 0
	global_load_lds_dwordx4 v[200:201], off
	s_waitcnt lgkmcnt(8)
	s_barrier
	s_waitcnt lgkmcnt(0)
	s_waitcnt lgkmcnt(0)
	v_mfma_f32_16x16x32_bf16 v[142:145], v[50:53], v[146:149], v[142:145]
	v_mfma_f32_16x16x32_bf16 v[134:137], v[66:69], v[146:149], v[134:137]
	v_mfma_f32_16x16x32_bf16 v[126:129], v[50:53], v[154:157], v[126:129]
	v_mfma_f32_16x16x32_bf16 v[118:121], v[66:69], v[154:157], v[118:121]
	v_mfma_f32_16x16x32_bf16 v[110:113], v[50:53], v[184:187], v[110:113]
	v_mfma_f32_16x16x32_bf16 v[102:105], v[66:69], v[184:187], v[102:105]
	v_mfma_f32_16x16x32_bf16 v[94:97], v[50:53], v[192:195], v[94:97]
	v_mfma_f32_16x16x32_bf16 v[86:89], v[66:69], v[192:195], v[86:89]
	v_mfma_f32_16x16x32_bf16 v[142:145], v[58:61], v[150:153], v[142:145]
	v_mfma_f32_16x16x32_bf16 v[134:137], v[74:77], v[150:153], v[134:137]
	v_mfma_f32_16x16x32_bf16 v[126:129], v[58:61], v[180:183], v[126:129]
	v_mfma_f32_16x16x32_bf16 v[118:121], v[74:77], v[180:183], v[118:121]
	v_mfma_f32_16x16x32_bf16 v[110:113], v[58:61], v[188:191], v[110:113]
	v_mfma_f32_16x16x32_bf16 v[102:105], v[74:77], v[188:191], v[102:105]
	v_mfma_f32_16x16x32_bf16 v[94:97], v[58:61], v[196:199], v[94:97]
	v_mfma_f32_16x16x32_bf16 v[86:89], v[74:77], v[196:199], v[86:89]
	s_barrier
	s_add_i32 s28, 0, 0x1c000
	s_add_i32 s29, s58, s35
	v_add_u32_e32 v168, s28, v205
	v_lshl_add_u64 v[206:207], v[206:207], 0, s[84:85]
	s_mov_b32 m0, s29
	ds_read_b128 v[200:203], v168
	ds_read_b128 v[210:213], v168 offset:1024
	ds_read_b128 v[214:217], v168 offset:2048
	ds_read_b128 v[218:221], v168 offset:3072
	global_load_lds_dwordx4 v[206:207], off
	v_lshl_add_u64 v[206:207], v[236:237], 0, s[84:85]
	s_add_i32 m0, s29, 0x2000
	s_nop 0
	global_load_lds_dwordx4 v[206:207], off
	s_barrier
	s_waitcnt lgkmcnt(0)
	s_waitcnt lgkmcnt(0)
	v_mfma_f32_16x16x32_bf16 v[138:141], v[200:203], v[146:149], v[138:141]
	v_mfma_f32_16x16x32_bf16 v[130:133], v[214:217], v[146:149], v[130:133]
	v_mfma_f32_16x16x32_bf16 v[122:125], v[200:203], v[154:157], v[122:125]
	v_mfma_f32_16x16x32_bf16 v[114:117], v[214:217], v[154:157], v[114:117]
	v_mfma_f32_16x16x32_bf16 v[106:109], v[200:203], v[184:187], v[106:109]
	v_mfma_f32_16x16x32_bf16 v[98:101], v[214:217], v[184:187], v[98:101]
	v_mfma_f32_16x16x32_bf16 v[90:93], v[200:203], v[192:195], v[90:93]
	v_mfma_f32_16x16x32_bf16 v[82:85], v[214:217], v[192:195], v[82:85]
	v_mfma_f32_16x16x32_bf16 v[138:141], v[210:213], v[150:153], v[138:141]
	v_mfma_f32_16x16x32_bf16 v[130:133], v[218:221], v[150:153], v[130:133]
	v_mfma_f32_16x16x32_bf16 v[122:125], v[210:213], v[180:183], v[122:125]
	v_mfma_f32_16x16x32_bf16 v[114:117], v[218:221], v[180:183], v[114:117]
	v_mfma_f32_16x16x32_bf16 v[106:109], v[210:213], v[188:191], v[106:109]
	v_mfma_f32_16x16x32_bf16 v[98:101], v[218:221], v[188:191], v[98:101]
	v_mfma_f32_16x16x32_bf16 v[90:93], v[210:213], v[196:199], v[90:93]
	v_mfma_f32_16x16x32_bf16 v[82:85], v[218:221], v[196:199], v[82:85]
	s_mov_b32 m0, s47
	v_lshl_add_u64 v[206:207], v[238:239], 0, s[84:85]
	s_barrier
	ds_read_b128 v[146:149], v208 offset:49152
	ds_read_b128 v[150:153], v208 offset:50176
	ds_read_b128 v[154:157], v208 offset:51200
	ds_read_b128 v[180:183], v208 offset:52224
	ds_read_b128 v[184:187], v208 offset:53248
	ds_read_b128 v[188:191], v208 offset:54272
	ds_read_b128 v[192:195], v208 offset:55296
	ds_read_b128 v[196:199], v208 offset:56320
	global_load_lds_dwordx4 v[206:207], off
	v_lshl_add_u64 v[206:207], v[240:241], 0, s[84:85]
	s_mov_b32 m0, s48
	s_nop 0
	global_load_lds_dwordx4 v[206:207], off
	s_barrier
	s_waitcnt lgkmcnt(0)
	s_waitcnt lgkmcnt(0)
	v_mfma_f32_16x16x32_bf16 v[78:81], v[50:53], v[146:149], v[78:81]
	v_mfma_f32_16x16x32_bf16 v[70:73], v[66:69], v[146:149], v[70:73]
	v_mfma_f32_16x16x32_bf16 v[62:65], v[50:53], v[154:157], v[62:65]
	v_mfma_f32_16x16x32_bf16 v[54:57], v[66:69], v[154:157], v[54:57]
	v_mfma_f32_16x16x32_bf16 v[38:41], v[50:53], v[184:187], v[38:41]
	v_mfma_f32_16x16x32_bf16 v[26:29], v[66:69], v[184:187], v[26:29]
	v_mfma_f32_16x16x32_bf16 v[14:17], v[50:53], v[192:195], v[14:17]
	v_mfma_f32_16x16x32_bf16 v[6:9], v[66:69], v[192:195], v[6:9]
	v_mfma_f32_16x16x32_bf16 v[78:81], v[58:61], v[150:153], v[78:81]
	v_mfma_f32_16x16x32_bf16 v[70:73], v[74:77], v[150:153], v[70:73]
	v_mfma_f32_16x16x32_bf16 v[62:65], v[58:61], v[180:183], v[62:65]
	v_mfma_f32_16x16x32_bf16 v[54:57], v[74:77], v[180:183], v[54:57]
	v_mfma_f32_16x16x32_bf16 v[38:41], v[58:61], v[188:191], v[38:41]
	v_mfma_f32_16x16x32_bf16 v[26:29], v[74:77], v[188:191], v[26:29]
	v_mfma_f32_16x16x32_bf16 v[14:17], v[58:61], v[196:199], v[14:17]
	v_mfma_f32_16x16x32_bf16 v[6:9], v[74:77], v[196:199], v[6:9]
	s_barrier
	s_add_u32 s26, s26, 0x40080
	s_addc_u32 s27, s27, 0
	s_add_i32 s28, s28, s35
	v_lshl_add_u64 v[50:51], s[26:27], 0, v[172:173]
	s_mov_b32 m0, s28
	s_nop 0
	global_load_lds_dwordx4 v[50:51], off
	v_lshl_add_u64 v[50:51], s[26:27], 0, v[158:159]
	s_add_i32 m0, s28, 0x2000
	s_nop 0
	global_load_lds_dwordx4 v[50:51], off
	s_waitcnt vmcnt(6)
	s_barrier
	v_mfma_f32_16x16x32_bf16 v[22:25], v[200:203], v[146:149], v[22:25]
	v_mfma_f32_16x16x32_bf16 v[74:77], v[210:213], v[150:153], v[22:25]
	v_mfma_f32_16x16x32_bf16 v[22:25], v[214:217], v[146:149], v[34:37]
	v_mfma_f32_16x16x32_bf16 v[66:69], v[218:221], v[150:153], v[22:25]
	v_mfma_f32_16x16x32_bf16 v[22:25], v[200:203], v[154:157], v[42:45]
	v_mfma_f32_16x16x32_bf16 v[58:61], v[210:213], v[180:183], v[22:25]
	v_mfma_f32_16x16x32_bf16 v[22:25], v[214:217], v[154:157], v[46:49]
	v_mfma_f32_16x16x32_bf16 v[50:53], v[218:221], v[180:183], v[22:25]
	v_mfma_f32_16x16x32_bf16 v[22:25], v[200:203], v[184:187], v[30:33]
	v_mfma_f32_16x16x32_bf16 v[18:21], v[214:217], v[184:187], v[18:21]
	v_mfma_f32_16x16x32_bf16 v[10:13], v[200:203], v[192:195], v[10:13]
	v_mfma_f32_16x16x32_bf16 v[2:5], v[214:217], v[192:195], v[2:5]
	v_mfma_f32_16x16x32_bf16 v[30:33], v[210:213], v[188:191], v[22:25]
	v_mfma_f32_16x16x32_bf16 v[18:21], v[218:221], v[188:191], v[18:21]
	v_mfma_f32_16x16x32_bf16 v[10:13], v[210:213], v[196:199], v[10:13]
	v_mfma_f32_16x16x32_bf16 v[2:5], v[218:221], v[196:199], v[2:5]
	s_add_u32 s24, s24, 0x100
	s_addc_u32 s25, s25, 0
	s_add_u32 s55, s55, 0x100
	s_addc_u32 s56, s56, 0
	s_cmp_ge_i32 s57, s45
	s_mov_b32 s26, s57
	s_barrier
	s_cbranch_scc0 .LBB0_799

.LBB0_844:
	s_add_i32 s53, s14, 2
	s_add_u32 s15, s12, 0x4000
	s_addc_u32 s16, s13, 0
	s_cmp_eq_u32 s43, s14
	s_cselect_b32 s18, s0, s15
	s_cselect_b32 s19, s1, s16
	s_cselect_b32 s14, s2, s51
	s_cselect_b32 s15, s3, s52
	s_add_u32 s16, s18, 0x8000
	s_addc_u32 s17, s19, 0
	s_add_i32 s54, 0, 0x10000
	v_add_u32_e32 v142, s54, v210
	ds_read_b128 v[126:129], v142
	ds_read_b128 v[130:133], v142 offset:1024
	ds_read_b128 v[138:141], v142 offset:2048
	ds_read_b128 v[142:145], v142 offset:3072
	v_lshl_add_u64 v[200:201], s[12:13], 0, v[180:181]
	s_add_i32 m0, s26, 0xc000
	ds_read_b128 v[146:149], v211
	ds_read_b128 v[150:153], v211 offset:1024
	ds_read_b128 v[154:157], v211 offset:2048
	ds_read_b128 v[158:161], v211 offset:3072
	ds_read_b128 v[184:187], v211 offset:4096
	ds_read_b128 v[188:191], v211 offset:5120
	ds_read_b128 v[192:195], v211 offset:6144
	ds_read_b128 v[196:199], v211 offset:7168
	global_load_lds_dwordx4 v[200:201], off
	v_lshl_add_u64 v[200:201], s[12:13], 0, v[182:183]
	s_add_i32 m0, s26, 0xe000
	s_nop 0
	global_load_lds_dwordx4 v[200:201], off
	s_waitcnt lgkmcnt(8)
	s_barrier
	s_waitcnt lgkmcnt(0)
	s_waitcnt lgkmcnt(0)
	v_mfma_f32_16x16x32_bf16 v[134:137], v[126:129], v[146:149], v[134:137]
	v_mfma_f32_16x16x32_bf16 v[122:125], v[138:141], v[146:149], v[122:125]
	v_mfma_f32_16x16x32_bf16 v[110:113], v[126:129], v[154:157], v[110:113]
	v_mfma_f32_16x16x32_bf16 v[106:109], v[138:141], v[154:157], v[106:109]
	v_mfma_f32_16x16x32_bf16 v[94:97], v[126:129], v[184:187], v[94:97]
	v_mfma_f32_16x16x32_bf16 v[90:93], v[138:141], v[184:187], v[90:93]
	v_mfma_f32_16x16x32_bf16 v[78:81], v[126:129], v[192:195], v[78:81]
	v_mfma_f32_16x16x32_bf16 v[74:77], v[138:141], v[192:195], v[74:77]
	v_mfma_f32_16x16x32_bf16 v[134:137], v[130:133], v[150:153], v[134:137]
	v_mfma_f32_16x16x32_bf16 v[122:125], v[142:145], v[150:153], v[122:125]
	v_mfma_f32_16x16x32_bf16 v[110:113], v[130:133], v[158:161], v[110:113]
	v_mfma_f32_16x16x32_bf16 v[106:109], v[142:145], v[158:161], v[106:109]
	v_mfma_f32_16x16x32_bf16 v[94:97], v[130:133], v[188:191], v[94:97]
	v_mfma_f32_16x16x32_bf16 v[90:93], v[142:145], v[188:191], v[90:93]
	v_mfma_f32_16x16x32_bf16 v[78:81], v[130:133], v[196:199], v[78:81]
	v_mfma_f32_16x16x32_bf16 v[74:77], v[142:145], v[196:199], v[74:77]
	s_barrier
	s_add_i32 s56, 0, 0x14000
	s_add_i32 s54, s54, s25
	v_add_u32_e32 v168, s56, v210
	v_lshl_add_u64 v[208:209], s[14:15], 0, v[174:175]
	s_mov_b32 m0, s54
	ds_read_b128 v[200:203], v168
	ds_read_b128 v[204:207], v168 offset:1024
	ds_read_b128 v[212:215], v168 offset:2048
	ds_read_b128 v[216:219], v168 offset:3072
	global_load_lds_dwordx4 v[208:209], off
	v_lshl_add_u64 v[220:221], s[14:15], 0, v[178:179]
	s_add_i32 m0, s54, 0x2000
	s_nop 0
	global_load_lds_dwordx4 v[220:221], off
	s_barrier
	s_waitcnt lgkmcnt(0)
	s_waitcnt lgkmcnt(0)
	v_mfma_f32_16x16x32_bf16 v[118:121], v[200:203], v[146:149], v[118:121]
	v_mfma_f32_16x16x32_bf16 v[114:117], v[212:215], v[146:149], v[114:117]
	v_mfma_f32_16x16x32_bf16 v[102:105], v[200:203], v[154:157], v[102:105]
	v_mfma_f32_16x16x32_bf16 v[98:101], v[212:215], v[154:157], v[98:101]
	v_mfma_f32_16x16x32_bf16 v[86:89], v[200:203], v[184:187], v[86:89]
	v_mfma_f32_16x16x32_bf16 v[82:85], v[212:215], v[184:187], v[82:85]
	v_mfma_f32_16x16x32_bf16 v[70:73], v[200:203], v[192:195], v[70:73]
	v_mfma_f32_16x16x32_bf16 v[66:69], v[212:215], v[192:195], v[66:69]
	v_mfma_f32_16x16x32_bf16 v[118:121], v[204:207], v[150:153], v[118:121]
	v_mfma_f32_16x16x32_bf16 v[114:117], v[216:219], v[150:153], v[114:117]
	v_mfma_f32_16x16x32_bf16 v[102:105], v[204:207], v[158:161], v[102:105]
	v_mfma_f32_16x16x32_bf16 v[98:101], v[216:219], v[158:161], v[98:101]
	v_mfma_f32_16x16x32_bf16 v[86:89], v[204:207], v[188:191], v[86:89]
	v_mfma_f32_16x16x32_bf16 v[82:85], v[216:219], v[188:191], v[82:85]
	v_mfma_f32_16x16x32_bf16 v[70:73], v[204:207], v[196:199], v[70:73]
	v_mfma_f32_16x16x32_bf16 v[66:69], v[216:219], v[196:199], v[66:69]
	s_mov_b32 m0, s26
	v_lshl_add_u64 v[236:237], s[18:19], 0, v[172:173]
	s_barrier
	ds_read_b128 v[146:149], v211 offset:16384
	ds_read_b128 v[150:153], v211 offset:17408
	ds_read_b128 v[154:157], v211 offset:18432
	ds_read_b128 v[158:161], v211 offset:19456
	ds_read_b128 v[184:187], v211 offset:20480
	ds_read_b128 v[188:191], v211 offset:21504
	ds_read_b128 v[192:195], v211 offset:22528
	ds_read_b128 v[196:199], v211 offset:23552
	global_load_lds_dwordx4 v[236:237], off
	v_lshl_add_u64 v[236:237], s[18:19], 0, v[176:177]
	s_mov_b32 m0, s27
	s_nop 0
	global_load_lds_dwordx4 v[236:237], off
	s_barrier
	s_waitcnt lgkmcnt(0)
	s_waitcnt lgkmcnt(0)
	v_mfma_f32_16x16x32_bf16 v[62:65], v[126:129], v[146:149], v[62:65]
	v_mfma_f32_16x16x32_bf16 v[58:61], v[138:141], v[146:149], v[58:61]
	v_mfma_f32_16x16x32_bf16 v[46:49], v[126:129], v[154:157], v[46:49]
	v_mfma_f32_16x16x32_bf16 v[42:45], v[138:141], v[154:157], v[42:45]
	v_mfma_f32_16x16x32_bf16 v[30:33], v[126:129], v[184:187], v[30:33]
	v_mfma_f32_16x16x32_bf16 v[26:29], v[138:141], v[184:187], v[26:29]
	v_mfma_f32_16x16x32_bf16 v[14:17], v[126:129], v[192:195], v[14:17]
	v_mfma_f32_16x16x32_bf16 v[10:13], v[138:141], v[192:195], v[10:13]
	v_mfma_f32_16x16x32_bf16 v[62:65], v[130:133], v[150:153], v[62:65]
	v_mfma_f32_16x16x32_bf16 v[58:61], v[142:145], v[150:153], v[58:61]
	v_mfma_f32_16x16x32_bf16 v[46:49], v[130:133], v[158:161], v[46:49]
	v_mfma_f32_16x16x32_bf16 v[42:45], v[142:145], v[158:161], v[42:45]
	v_mfma_f32_16x16x32_bf16 v[30:33], v[130:133], v[188:191], v[30:33]
	v_mfma_f32_16x16x32_bf16 v[26:29], v[142:145], v[188:191], v[26:29]
	v_mfma_f32_16x16x32_bf16 v[14:17], v[130:133], v[196:199], v[14:17]
	v_mfma_f32_16x16x32_bf16 v[10:13], v[142:145], v[196:199], v[10:13]
	s_barrier
	s_add_u32 s54, s14, 0xb0000
	s_addc_u32 s55, s15, 0
	s_add_i32 s56, s56, s25
	v_lshl_add_u64 v[126:127], s[54:55], 0, v[174:175]
	s_mov_b32 m0, s56
	s_nop 0
	global_load_lds_dwordx4 v[126:127], off
	v_lshl_add_u64 v[126:127], s[54:55], 0, v[178:179]
	s_add_i32 m0, s56, 0x2000
	s_nop 0
	global_load_lds_dwordx4 v[126:127], off
	s_waitcnt vmcnt(6)
	s_barrier
	v_mfma_f32_16x16x32_bf16 v[54:57], v[200:203], v[146:149], v[54:57]
	v_mfma_f32_16x16x32_bf16 v[50:53], v[212:215], v[146:149], v[50:53]
	v_mfma_f32_16x16x32_bf16 v[38:41], v[200:203], v[154:157], v[38:41]
	v_mfma_f32_16x16x32_bf16 v[34:37], v[212:215], v[154:157], v[34:37]
	v_mfma_f32_16x16x32_bf16 v[22:25], v[200:203], v[184:187], v[22:25]
	v_mfma_f32_16x16x32_bf16 v[18:21], v[212:215], v[184:187], v[18:21]
	v_mfma_f32_16x16x32_bf16 v[6:9], v[200:203], v[192:195], v[6:9]
	v_mfma_f32_16x16x32_bf16 v[2:5], v[212:215], v[192:195], v[2:5]
	v_mfma_f32_16x16x32_bf16 v[54:57], v[204:207], v[150:153], v[54:57]
	v_mfma_f32_16x16x32_bf16 v[50:53], v[216:219], v[150:153], v[50:53]
	v_mfma_f32_16x16x32_bf16 v[38:41], v[204:207], v[158:161], v[38:41]
	v_mfma_f32_16x16x32_bf16 v[34:37], v[216:219], v[158:161], v[34:37]
	v_mfma_f32_16x16x32_bf16 v[22:25], v[204:207], v[188:191], v[22:25]
	v_mfma_f32_16x16x32_bf16 v[18:21], v[216:219], v[188:191], v[18:21]
	v_mfma_f32_16x16x32_bf16 v[6:9], v[204:207], v[196:199], v[6:9]
	v_mfma_f32_16x16x32_bf16 v[2:5], v[216:219], v[196:199], v[2:5]
	s_add_i32 s54, 0, 0x18000
	v_add_u32_e32 v142, s54, v210
	s_barrier
	ds_read_b128 v[126:129], v142
	ds_read_b128 v[130:133], v142 offset:1024
	ds_read_b128 v[138:141], v142 offset:2048
	ds_read_b128 v[142:145], v142 offset:3072
	s_add_u32 s18, s18, 0x4000
	s_addc_u32 s19, s19, 0
	s_mov_b32 m0, s28
	v_lshl_add_u64 v[200:201], s[18:19], 0, v[172:173]
	ds_read_b128 v[146:149], v211 offset:32768
	ds_read_b128 v[150:153], v211 offset:33792
	ds_read_b128 v[154:157], v211 offset:34816
	ds_read_b128 v[158:161], v211 offset:35840
	ds_read_b128 v[184:187], v211 offset:36864
	ds_read_b128 v[188:191], v211 offset:37888
	ds_read_b128 v[192:195], v211 offset:38912
	ds_read_b128 v[196:199], v211 offset:39936
	global_load_lds_dwordx4 v[200:201], off
	v_lshl_add_u64 v[200:201], s[18:19], 0, v[176:177]
	s_mov_b32 m0, s29
	s_nop 0
	global_load_lds_dwordx4 v[200:201], off
	s_waitcnt lgkmcnt(8)
	s_barrier
	s_waitcnt lgkmcnt(0)
	s_waitcnt lgkmcnt(0)
	v_mfma_f32_16x16x32_bf16 v[134:137], v[126:129], v[146:149], v[134:137]
	v_mfma_f32_16x16x32_bf16 v[122:125], v[138:141], v[146:149], v[122:125]
	v_mfma_f32_16x16x32_bf16 v[110:113], v[126:129], v[154:157], v[110:113]
	v_mfma_f32_16x16x32_bf16 v[106:109], v[138:141], v[154:157], v[106:109]
	v_mfma_f32_16x16x32_bf16 v[94:97], v[126:129], v[184:187], v[94:97]
	v_mfma_f32_16x16x32_bf16 v[90:93], v[138:141], v[184:187], v[90:93]
	v_mfma_f32_16x16x32_bf16 v[78:81], v[126:129], v[192:195], v[78:81]
	v_mfma_f32_16x16x32_bf16 v[74:77], v[138:141], v[192:195], v[74:77]
	v_mfma_f32_16x16x32_bf16 v[134:137], v[130:133], v[150:153], v[134:137]
	v_mfma_f32_16x16x32_bf16 v[122:125], v[142:145], v[150:153], v[122:125]
	v_mfma_f32_16x16x32_bf16 v[110:113], v[130:133], v[158:161], v[110:113]
	v_mfma_f32_16x16x32_bf16 v[106:109], v[142:145], v[158:161], v[106:109]
	v_mfma_f32_16x16x32_bf16 v[94:97], v[130:133], v[188:191], v[94:97]
	v_mfma_f32_16x16x32_bf16 v[90:93], v[142:145], v[188:191], v[90:93]
	v_mfma_f32_16x16x32_bf16 v[78:81], v[130:133], v[196:199], v[78:81]
	v_mfma_f32_16x16x32_bf16 v[74:77], v[142:145], v[196:199], v[74:77]
	s_barrier
	s_add_i32 s18, 0, 0x1c000
	s_add_i32 s19, s54, s25
	v_add_u32_e32 v168, s18, v210
	v_lshl_add_u64 v[208:209], v[208:209], 0, s[84:85]
	s_mov_b32 m0, s19
	ds_read_b128 v[200:203], v168
	ds_read_b128 v[204:207], v168 offset:1024
	ds_read_b128 v[212:215], v168 offset:2048
	ds_read_b128 v[216:219], v168 offset:3072
	global_load_lds_dwordx4 v[208:209], off
	v_lshl_add_u64 v[208:209], v[220:221], 0, s[84:85]
	s_add_i32 m0, s19, 0x2000
	s_nop 0
	global_load_lds_dwordx4 v[208:209], off
	s_barrier
	s_waitcnt lgkmcnt(0)
	s_waitcnt lgkmcnt(0)
	v_mfma_f32_16x16x32_bf16 v[118:121], v[200:203], v[146:149], v[118:121]
	v_mfma_f32_16x16x32_bf16 v[114:117], v[212:215], v[146:149], v[114:117]
	v_mfma_f32_16x16x32_bf16 v[102:105], v[200:203], v[154:157], v[102:105]
	v_mfma_f32_16x16x32_bf16 v[98:101], v[212:215], v[154:157], v[98:101]
	v_mfma_f32_16x16x32_bf16 v[86:89], v[200:203], v[184:187], v[86:89]
	v_mfma_f32_16x16x32_bf16 v[82:85], v[212:215], v[184:187], v[82:85]
	v_mfma_f32_16x16x32_bf16 v[70:73], v[200:203], v[192:195], v[70:73]
	v_mfma_f32_16x16x32_bf16 v[66:69], v[212:215], v[192:195], v[66:69]
	v_mfma_f32_16x16x32_bf16 v[118:121], v[204:207], v[150:153], v[118:121]
	v_mfma_f32_16x16x32_bf16 v[114:117], v[216:219], v[150:153], v[114:117]
	v_mfma_f32_16x16x32_bf16 v[102:105], v[204:207], v[158:161], v[102:105]
	v_mfma_f32_16x16x32_bf16 v[98:101], v[216:219], v[158:161], v[98:101]
	v_mfma_f32_16x16x32_bf16 v[86:89], v[204:207], v[188:191], v[86:89]
	v_mfma_f32_16x16x32_bf16 v[82:85], v[216:219], v[188:191], v[82:85]
	v_mfma_f32_16x16x32_bf16 v[70:73], v[204:207], v[196:199], v[70:73]
	v_mfma_f32_16x16x32_bf16 v[66:69], v[216:219], v[196:199], v[66:69]
	s_mov_b32 m0, s41
	v_lshl_add_u64 v[208:209], s[16:17], 0, v[172:173]
	s_barrier
	ds_read_b128 v[146:149], v211 offset:49152
	ds_read_b128 v[150:153], v211 offset:50176
	ds_read_b128 v[154:157], v211 offset:51200
	ds_read_b128 v[158:161], v211 offset:52224
	ds_read_b128 v[184:187], v211 offset:53248
	ds_read_b128 v[188:191], v211 offset:54272
	ds_read_b128 v[192:195], v211 offset:55296
	ds_read_b128 v[196:199], v211 offset:56320
	global_load_lds_dwordx4 v[208:209], off
	v_lshl_add_u64 v[208:209], s[16:17], 0, v[176:177]
	s_mov_b32 m0, s42
	s_nop 0
	global_load_lds_dwordx4 v[208:209], off
	s_barrier
	s_waitcnt lgkmcnt(0)
	s_waitcnt lgkmcnt(0)
	v_mfma_f32_16x16x32_bf16 v[62:65], v[126:129], v[146:149], v[62:65]
	v_mfma_f32_16x16x32_bf16 v[58:61], v[138:141], v[146:149], v[58:61]
	v_mfma_f32_16x16x32_bf16 v[46:49], v[126:129], v[154:157], v[46:49]
	v_mfma_f32_16x16x32_bf16 v[42:45], v[138:141], v[154:157], v[42:45]
	v_mfma_f32_16x16x32_bf16 v[30:33], v[126:129], v[184:187], v[30:33]
	v_mfma_f32_16x16x32_bf16 v[26:29], v[138:141], v[184:187], v[26:29]
	v_mfma_f32_16x16x32_bf16 v[14:17], v[126:129], v[192:195], v[14:17]
	v_mfma_f32_16x16x32_bf16 v[10:13], v[138:141], v[192:195], v[10:13]
	v_mfma_f32_16x16x32_bf16 v[62:65], v[130:133], v[150:153], v[62:65]
	v_mfma_f32_16x16x32_bf16 v[58:61], v[142:145], v[150:153], v[58:61]
	v_mfma_f32_16x16x32_bf16 v[46:49], v[130:133], v[158:161], v[46:49]
	v_mfma_f32_16x16x32_bf16 v[42:45], v[142:145], v[158:161], v[42:45]
	v_mfma_f32_16x16x32_bf16 v[30:33], v[130:133], v[188:191], v[30:33]
	v_mfma_f32_16x16x32_bf16 v[26:29], v[142:145], v[188:191], v[26:29]
	v_mfma_f32_16x16x32_bf16 v[14:17], v[130:133], v[196:199], v[14:17]
	v_mfma_f32_16x16x32_bf16 v[10:13], v[142:145], v[196:199], v[10:13]
	s_barrier
	s_add_u32 s14, s14, 0xb0080
	s_addc_u32 s15, s15, 0
	s_add_i32 s16, s18, s25
	v_lshl_add_u64 v[126:127], s[14:15], 0, v[174:175]
	s_mov_b32 m0, s16
	s_nop 0
	global_load_lds_dwordx4 v[126:127], off
	v_lshl_add_u64 v[126:127], s[14:15], 0, v[178:179]
	s_add_i32 m0, s16, 0x2000
	s_nop 0
	global_load_lds_dwordx4 v[126:127], off
	s_waitcnt vmcnt(6)
	s_barrier
	v_mfma_f32_16x16x32_bf16 v[54:57], v[200:203], v[146:149], v[54:57]
	v_mfma_f32_16x16x32_bf16 v[50:53], v[212:215], v[146:149], v[50:53]
	v_mfma_f32_16x16x32_bf16 v[38:41], v[200:203], v[154:157], v[38:41]
	v_mfma_f32_16x16x32_bf16 v[34:37], v[212:215], v[154:157], v[34:37]
	v_mfma_f32_16x16x32_bf16 v[22:25], v[200:203], v[184:187], v[22:25]
	v_mfma_f32_16x16x32_bf16 v[18:21], v[212:215], v[184:187], v[18:21]
	v_mfma_f32_16x16x32_bf16 v[6:9], v[200:203], v[192:195], v[6:9]
	v_mfma_f32_16x16x32_bf16 v[2:5], v[212:215], v[192:195], v[2:5]
	v_mfma_f32_16x16x32_bf16 v[54:57], v[204:207], v[150:153], v[54:57]
	v_mfma_f32_16x16x32_bf16 v[50:53], v[216:219], v[150:153], v[50:53]
	v_mfma_f32_16x16x32_bf16 v[38:41], v[204:207], v[158:161], v[38:41]
	v_mfma_f32_16x16x32_bf16 v[34:37], v[216:219], v[158:161], v[34:37]
	v_mfma_f32_16x16x32_bf16 v[22:25], v[204:207], v[188:191], v[22:25]
	v_mfma_f32_16x16x32_bf16 v[18:21], v[216:219], v[188:191], v[18:21]
	v_mfma_f32_16x16x32_bf16 v[6:9], v[204:207], v[196:199], v[6:9]
	v_mfma_f32_16x16x32_bf16 v[2:5], v[216:219], v[196:199], v[2:5]
	s_add_u32 s51, s51, 0x100
	s_addc_u32 s52, s52, 0
	s_add_u32 s12, s12, 0x10000
	s_addc_u32 s13, s13, 0
	s_cmp_ge_i32 s53, s38
	s_mov_b32 s14, s53
	s_barrier
	s_cbranch_scc0 .LBB0_844

.LBB0_874:
	s_add_i32 s43, s14, 2
	s_add_u32 s15, s12, 0xfffc0080
	s_addc_u32 s16, s13, -1
	s_add_i32 s44, 0, 0x10000
	v_add_u32_e32 v102, s44, v171
	ds_read_b128 v[82:85], v102
	ds_read_b128 v[86:89], v102 offset:1024
	ds_read_b128 v[98:101], v102 offset:2048
	ds_read_b128 v[102:105], v102 offset:3072
	s_cmp_eq_u32 s31, s14
	s_cselect_b32 s14, s40, s41
	s_cselect_b32 s17, s3, s16
	s_cselect_b32 s16, s5, s15
	s_cselect_b32 s15, s39, s42
	v_lshl_add_u64 v[160:161], s[12:13], 0, v[154:155]
	s_add_i32 m0, s11, 0xc000
	ds_read_b128 v[174:177], v173
	ds_read_b128 v[178:181], v173 offset:1024
	ds_read_b128 v[182:185], v173 offset:2048
	ds_read_b128 v[186:189], v173 offset:3072
	ds_read_b128 v[190:193], v173 offset:4096
	ds_read_b128 v[194:197], v173 offset:5120
	ds_read_b128 v[198:201], v173 offset:6144
	ds_read_b128 v[202:205], v173 offset:7168
	global_load_lds_dwordx4 v[160:161], off
	v_lshl_add_u64 v[160:161], s[12:13], 0, v[156:157]
	s_add_i32 m0, s11, 0xe000
	s_nop 0
	global_load_lds_dwordx4 v[160:161], off
	s_waitcnt lgkmcnt(8)
	s_barrier
	s_waitcnt lgkmcnt(0)
	s_waitcnt lgkmcnt(0)
	v_mfma_f32_16x16x32_bf16 v[138:141], v[82:85], v[174:177], v[138:141]
	v_mfma_f32_16x16x32_bf16 v[134:137], v[98:101], v[174:177], v[134:137]
	v_mfma_f32_16x16x32_bf16 v[126:129], v[82:85], v[182:185], v[126:129]
	v_mfma_f32_16x16x32_bf16 v[118:121], v[98:101], v[182:185], v[118:121]
	v_mfma_f32_16x16x32_bf16 v[110:113], v[82:85], v[190:193], v[110:113]
	v_mfma_f32_16x16x32_bf16 v[94:97], v[98:101], v[190:193], v[94:97]
	v_mfma_f32_16x16x32_bf16 v[78:81], v[82:85], v[198:201], v[78:81]
	v_mfma_f32_16x16x32_bf16 v[70:73], v[98:101], v[198:201], v[70:73]
	v_mfma_f32_16x16x32_bf16 v[138:141], v[86:89], v[178:181], v[138:141]
	v_mfma_f32_16x16x32_bf16 v[134:137], v[102:105], v[178:181], v[134:137]
	v_mfma_f32_16x16x32_bf16 v[126:129], v[86:89], v[186:189], v[126:129]
	v_mfma_f32_16x16x32_bf16 v[118:121], v[102:105], v[186:189], v[118:121]
	v_mfma_f32_16x16x32_bf16 v[110:113], v[86:89], v[194:197], v[110:113]
	v_mfma_f32_16x16x32_bf16 v[94:97], v[102:105], v[194:197], v[94:97]
	v_mfma_f32_16x16x32_bf16 v[78:81], v[86:89], v[202:205], v[78:81]
	v_mfma_f32_16x16x32_bf16 v[70:73], v[102:105], v[202:205], v[70:73]
	s_barrier
	s_add_i32 s46, 0, 0x14000
	s_add_i32 s44, s44, s19
	v_add_u32_e32 v158, s46, v171
	v_lshl_add_u64 v[160:161], s[14:15], 0, v[150:151]
	s_mov_b32 m0, s44
	ds_read_b128 v[206:209], v158
	ds_read_b128 v[210:213], v158 offset:1024
	ds_read_b128 v[214:217], v158 offset:2048
	ds_read_b128 v[218:221], v158 offset:3072
	global_load_lds_dwordx4 v[160:161], off
	v_lshl_add_u64 v[236:237], s[14:15], 0, v[146:147]
	s_add_i32 m0, s44, 0x2000
	s_nop 0
	global_load_lds_dwordx4 v[236:237], off
	s_barrier
	s_waitcnt lgkmcnt(0)
	s_waitcnt lgkmcnt(0)
	v_mfma_f32_16x16x32_bf16 v[142:145], v[206:209], v[174:177], v[142:145]
	v_mfma_f32_16x16x32_bf16 v[130:133], v[214:217], v[174:177], v[130:133]
	v_mfma_f32_16x16x32_bf16 v[122:125], v[206:209], v[182:185], v[122:125]
	v_mfma_f32_16x16x32_bf16 v[114:117], v[214:217], v[182:185], v[114:117]
	v_mfma_f32_16x16x32_bf16 v[106:109], v[206:209], v[190:193], v[106:109]
	v_mfma_f32_16x16x32_bf16 v[90:93], v[214:217], v[190:193], v[90:93]
	v_mfma_f32_16x16x32_bf16 v[74:77], v[206:209], v[198:201], v[74:77]
	v_mfma_f32_16x16x32_bf16 v[66:69], v[214:217], v[198:201], v[66:69]
	v_mfma_f32_16x16x32_bf16 v[142:145], v[210:213], v[178:181], v[142:145]
	v_mfma_f32_16x16x32_bf16 v[130:133], v[218:221], v[178:181], v[130:133]
	v_mfma_f32_16x16x32_bf16 v[122:125], v[210:213], v[186:189], v[122:125]
	v_mfma_f32_16x16x32_bf16 v[114:117], v[218:221], v[186:189], v[114:117]
	v_mfma_f32_16x16x32_bf16 v[106:109], v[210:213], v[194:197], v[106:109]
	v_mfma_f32_16x16x32_bf16 v[90:93], v[218:221], v[194:197], v[90:93]
	v_mfma_f32_16x16x32_bf16 v[74:77], v[210:213], v[202:205], v[74:77]
	v_mfma_f32_16x16x32_bf16 v[66:69], v[218:221], v[202:205], v[66:69]
	s_mov_b32 m0, s11
	v_lshl_add_u64 v[238:239], s[16:17], 0, v[152:153]
	s_barrier
	ds_read_b128 v[174:177], v173 offset:16384
	ds_read_b128 v[178:181], v173 offset:17408
	ds_read_b128 v[182:185], v173 offset:18432
	ds_read_b128 v[186:189], v173 offset:19456
	ds_read_b128 v[190:193], v173 offset:20480
	ds_read_b128 v[194:197], v173 offset:21504
	ds_read_b128 v[198:201], v173 offset:22528
	ds_read_b128 v[202:205], v173 offset:23552
	global_load_lds_dwordx4 v[238:239], off
	v_lshl_add_u64 v[240:241], s[16:17], 0, v[148:149]
	s_mov_b32 m0, s21
	s_nop 0
	global_load_lds_dwordx4 v[240:241], off
	s_barrier
	s_waitcnt lgkmcnt(0)
	s_waitcnt lgkmcnt(0)
	v_mfma_f32_16x16x32_bf16 v[62:65], v[82:85], v[174:177], v[62:65]
	v_mfma_f32_16x16x32_bf16 v[54:57], v[98:101], v[174:177], v[54:57]
	v_mfma_f32_16x16x32_bf16 v[46:49], v[82:85], v[182:185], v[46:49]
	v_mfma_f32_16x16x32_bf16 v[38:41], v[98:101], v[182:185], v[38:41]
	v_mfma_f32_16x16x32_bf16 v[30:33], v[82:85], v[190:193], v[30:33]
	v_mfma_f32_16x16x32_bf16 v[22:25], v[98:101], v[190:193], v[22:25]
	v_mfma_f32_16x16x32_bf16 v[14:17], v[82:85], v[198:201], v[14:17]
	v_mfma_f32_16x16x32_bf16 v[6:9], v[98:101], v[198:201], v[6:9]
	v_mfma_f32_16x16x32_bf16 v[62:65], v[86:89], v[178:181], v[62:65]
	v_mfma_f32_16x16x32_bf16 v[54:57], v[102:105], v[178:181], v[54:57]
	v_mfma_f32_16x16x32_bf16 v[46:49], v[86:89], v[186:189], v[46:49]
	v_mfma_f32_16x16x32_bf16 v[38:41], v[102:105], v[186:189], v[38:41]
	v_mfma_f32_16x16x32_bf16 v[30:33], v[86:89], v[194:197], v[30:33]
	v_mfma_f32_16x16x32_bf16 v[22:25], v[102:105], v[194:197], v[22:25]
	v_mfma_f32_16x16x32_bf16 v[14:17], v[86:89], v[202:205], v[14:17]
	v_mfma_f32_16x16x32_bf16 v[6:9], v[102:105], v[202:205], v[6:9]
	s_barrier
	s_add_u32 s44, s14, 0x40000
	s_addc_u32 s45, s15, 0
	s_add_i32 s46, s46, s19
	v_lshl_add_u64 v[82:83], s[44:45], 0, v[150:151]
	s_mov_b32 m0, s46
	s_nop 0
	global_load_lds_dwordx4 v[82:83], off
	v_lshl_add_u64 v[82:83], s[44:45], 0, v[146:147]
	s_add_i32 m0, s46, 0x2000
	s_nop 0
	global_load_lds_dwordx4 v[82:83], off
	s_waitcnt vmcnt(6)
	s_barrier
	v_mfma_f32_16x16x32_bf16 v[58:61], v[206:209], v[174:177], v[58:61]
	v_mfma_f32_16x16x32_bf16 v[50:53], v[214:217], v[174:177], v[50:53]
	v_mfma_f32_16x16x32_bf16 v[42:45], v[206:209], v[182:185], v[42:45]
	v_mfma_f32_16x16x32_bf16 v[34:37], v[214:217], v[182:185], v[34:37]
	v_mfma_f32_16x16x32_bf16 v[26:29], v[206:209], v[190:193], v[26:29]
	v_mfma_f32_16x16x32_bf16 v[18:21], v[214:217], v[190:193], v[18:21]
	v_mfma_f32_16x16x32_bf16 v[10:13], v[206:209], v[198:201], v[10:13]
	v_mfma_f32_16x16x32_bf16 v[2:5], v[214:217], v[198:201], v[2:5]
	v_mfma_f32_16x16x32_bf16 v[58:61], v[210:213], v[178:181], v[58:61]
	v_mfma_f32_16x16x32_bf16 v[50:53], v[218:221], v[178:181], v[50:53]
	v_mfma_f32_16x16x32_bf16 v[42:45], v[210:213], v[186:189], v[42:45]
	v_mfma_f32_16x16x32_bf16 v[34:37], v[218:221], v[186:189], v[34:37]
	v_mfma_f32_16x16x32_bf16 v[26:29], v[210:213], v[194:197], v[26:29]
	v_mfma_f32_16x16x32_bf16 v[18:21], v[218:221], v[194:197], v[18:21]
	v_mfma_f32_16x16x32_bf16 v[10:13], v[210:213], v[202:205], v[10:13]
	v_mfma_f32_16x16x32_bf16 v[2:5], v[218:221], v[202:205], v[2:5]
	s_add_i32 s44, 0, 0x18000
	v_add_u32_e32 v102, s44, v171
	s_barrier
	ds_read_b128 v[82:85], v102
	ds_read_b128 v[86:89], v102 offset:1024
	ds_read_b128 v[98:101], v102 offset:2048
	ds_read_b128 v[102:105], v102 offset:3072
	s_add_u32 s16, s16, 0x40000
	s_addc_u32 s17, s17, 0
	s_mov_b32 m0, s24
	v_lshl_add_u64 v[206:207], s[16:17], 0, v[152:153]
	ds_read_b128 v[174:177], v173 offset:32768
	ds_read_b128 v[178:181], v173 offset:33792
	ds_read_b128 v[182:185], v173 offset:34816
	ds_read_b128 v[186:189], v173 offset:35840
	ds_read_b128 v[190:193], v173 offset:36864
	ds_read_b128 v[194:197], v173 offset:37888
	ds_read_b128 v[198:201], v173 offset:38912
	ds_read_b128 v[202:205], v173 offset:39936
	global_load_lds_dwordx4 v[206:207], off
	v_lshl_add_u64 v[206:207], s[16:17], 0, v[148:149]
	s_mov_b32 m0, s25
	s_nop 0
	global_load_lds_dwordx4 v[206:207], off
	s_waitcnt lgkmcnt(8)
	s_barrier
	s_waitcnt lgkmcnt(0)
	s_waitcnt lgkmcnt(0)
	v_mfma_f32_16x16x32_bf16 v[138:141], v[82:85], v[174:177], v[138:141]
	v_mfma_f32_16x16x32_bf16 v[134:137], v[98:101], v[174:177], v[134:137]
	v_mfma_f32_16x16x32_bf16 v[126:129], v[82:85], v[182:185], v[126:129]
	v_mfma_f32_16x16x32_bf16 v[118:121], v[98:101], v[182:185], v[118:121]
	v_mfma_f32_16x16x32_bf16 v[110:113], v[82:85], v[190:193], v[110:113]
	v_mfma_f32_16x16x32_bf16 v[94:97], v[98:101], v[190:193], v[94:97]
	v_mfma_f32_16x16x32_bf16 v[78:81], v[82:85], v[198:201], v[78:81]
	v_mfma_f32_16x16x32_bf16 v[70:73], v[98:101], v[198:201], v[70:73]
	v_mfma_f32_16x16x32_bf16 v[138:141], v[86:89], v[178:181], v[138:141]
	v_mfma_f32_16x16x32_bf16 v[134:137], v[102:105], v[178:181], v[134:137]
	v_mfma_f32_16x16x32_bf16 v[126:129], v[86:89], v[186:189], v[126:129]
	v_mfma_f32_16x16x32_bf16 v[118:121], v[102:105], v[186:189], v[118:121]
	v_mfma_f32_16x16x32_bf16 v[110:113], v[86:89], v[194:197], v[110:113]
	v_mfma_f32_16x16x32_bf16 v[94:97], v[102:105], v[194:197], v[94:97]
	v_mfma_f32_16x16x32_bf16 v[78:81], v[86:89], v[202:205], v[78:81]
	v_mfma_f32_16x16x32_bf16 v[70:73], v[102:105], v[202:205], v[70:73]
	s_barrier
	s_add_i32 s16, 0, 0x1c000
	s_add_i32 s17, s44, s19
	v_add_u32_e32 v158, s16, v171
	v_lshl_add_u64 v[160:161], v[160:161], 0, s[84:85]
	s_mov_b32 m0, s17
	ds_read_b128 v[206:209], v158
	ds_read_b128 v[210:213], v158 offset:1024
	ds_read_b128 v[214:217], v158 offset:2048
	ds_read_b128 v[218:221], v158 offset:3072
	global_load_lds_dwordx4 v[160:161], off
	v_lshl_add_u64 v[160:161], v[236:237], 0, s[84:85]
	s_add_i32 m0, s17, 0x2000
	s_nop 0
	global_load_lds_dwordx4 v[160:161], off
	s_barrier
	s_waitcnt lgkmcnt(0)
	s_waitcnt lgkmcnt(0)
	v_mfma_f32_16x16x32_bf16 v[142:145], v[206:209], v[174:177], v[142:145]
	v_mfma_f32_16x16x32_bf16 v[130:133], v[214:217], v[174:177], v[130:133]
	v_mfma_f32_16x16x32_bf16 v[122:125], v[206:209], v[182:185], v[122:125]
	v_mfma_f32_16x16x32_bf16 v[114:117], v[214:217], v[182:185], v[114:117]
	v_mfma_f32_16x16x32_bf16 v[106:109], v[206:209], v[190:193], v[106:109]
	v_mfma_f32_16x16x32_bf16 v[90:93], v[214:217], v[190:193], v[90:93]
	v_mfma_f32_16x16x32_bf16 v[74:77], v[206:209], v[198:201], v[74:77]
	v_mfma_f32_16x16x32_bf16 v[66:69], v[214:217], v[198:201], v[66:69]
	v_mfma_f32_16x16x32_bf16 v[142:145], v[210:213], v[178:181], v[142:145]
	v_mfma_f32_16x16x32_bf16 v[130:133], v[218:221], v[178:181], v[130:133]
	v_mfma_f32_16x16x32_bf16 v[122:125], v[210:213], v[186:189], v[122:125]
	v_mfma_f32_16x16x32_bf16 v[114:117], v[218:221], v[186:189], v[114:117]
	v_mfma_f32_16x16x32_bf16 v[106:109], v[210:213], v[194:197], v[106:109]
	v_mfma_f32_16x16x32_bf16 v[90:93], v[218:221], v[194:197], v[90:93]
	v_mfma_f32_16x16x32_bf16 v[74:77], v[210:213], v[202:205], v[74:77]
	v_mfma_f32_16x16x32_bf16 v[66:69], v[218:221], v[202:205], v[66:69]
	s_mov_b32 m0, s29
	v_lshl_add_u64 v[160:161], v[238:239], 0, s[84:85]
	s_barrier
	ds_read_b128 v[174:177], v173 offset:49152
	ds_read_b128 v[178:181], v173 offset:50176
	ds_read_b128 v[182:185], v173 offset:51200
	ds_read_b128 v[186:189], v173 offset:52224
	ds_read_b128 v[190:193], v173 offset:53248
	ds_read_b128 v[194:197], v173 offset:54272
	ds_read_b128 v[198:201], v173 offset:55296
	ds_read_b128 v[202:205], v173 offset:56320
	global_load_lds_dwordx4 v[160:161], off
	v_lshl_add_u64 v[160:161], v[240:241], 0, s[84:85]
	s_mov_b32 m0, s30
	s_nop 0
	global_load_lds_dwordx4 v[160:161], off
	s_barrier
	s_waitcnt lgkmcnt(0)
	s_waitcnt lgkmcnt(0)
	v_mfma_f32_16x16x32_bf16 v[62:65], v[82:85], v[174:177], v[62:65]
	v_mfma_f32_16x16x32_bf16 v[54:57], v[98:101], v[174:177], v[54:57]
	v_mfma_f32_16x16x32_bf16 v[46:49], v[82:85], v[182:185], v[46:49]
	v_mfma_f32_16x16x32_bf16 v[38:41], v[98:101], v[182:185], v[38:41]
	v_mfma_f32_16x16x32_bf16 v[30:33], v[82:85], v[190:193], v[30:33]
	v_mfma_f32_16x16x32_bf16 v[22:25], v[98:101], v[190:193], v[22:25]
	v_mfma_f32_16x16x32_bf16 v[14:17], v[82:85], v[198:201], v[14:17]
	v_mfma_f32_16x16x32_bf16 v[6:9], v[98:101], v[198:201], v[6:9]
	v_mfma_f32_16x16x32_bf16 v[62:65], v[86:89], v[178:181], v[62:65]
	v_mfma_f32_16x16x32_bf16 v[54:57], v[102:105], v[178:181], v[54:57]
	v_mfma_f32_16x16x32_bf16 v[46:49], v[86:89], v[186:189], v[46:49]
	v_mfma_f32_16x16x32_bf16 v[38:41], v[102:105], v[186:189], v[38:41]
	v_mfma_f32_16x16x32_bf16 v[30:33], v[86:89], v[194:197], v[30:33]
	v_mfma_f32_16x16x32_bf16 v[22:25], v[102:105], v[194:197], v[22:25]
	v_mfma_f32_16x16x32_bf16 v[14:17], v[86:89], v[202:205], v[14:17]
	v_mfma_f32_16x16x32_bf16 v[6:9], v[102:105], v[202:205], v[6:9]
	s_barrier
	s_add_u32 s14, s14, 0x40080
	s_addc_u32 s15, s15, 0
	s_add_i32 s16, s16, s19
	v_lshl_add_u64 v[82:83], s[14:15], 0, v[150:151]
	s_mov_b32 m0, s16
	s_nop 0
	global_load_lds_dwordx4 v[82:83], off
	v_lshl_add_u64 v[82:83], s[14:15], 0, v[146:147]
	s_add_i32 m0, s16, 0x2000
	s_nop 0
	global_load_lds_dwordx4 v[82:83], off
	s_waitcnt vmcnt(6)
	s_barrier
	v_mfma_f32_16x16x32_bf16 v[58:61], v[206:209], v[174:177], v[58:61]
	v_mfma_f32_16x16x32_bf16 v[50:53], v[214:217], v[174:177], v[50:53]
	v_mfma_f32_16x16x32_bf16 v[42:45], v[206:209], v[182:185], v[42:45]
	v_mfma_f32_16x16x32_bf16 v[34:37], v[214:217], v[182:185], v[34:37]
	v_mfma_f32_16x16x32_bf16 v[26:29], v[206:209], v[190:193], v[26:29]
	v_mfma_f32_16x16x32_bf16 v[18:21], v[214:217], v[190:193], v[18:21]
	v_mfma_f32_16x16x32_bf16 v[10:13], v[206:209], v[198:201], v[10:13]
	v_mfma_f32_16x16x32_bf16 v[2:5], v[214:217], v[198:201], v[2:5]
	v_mfma_f32_16x16x32_bf16 v[58:61], v[210:213], v[178:181], v[58:61]
	v_mfma_f32_16x16x32_bf16 v[50:53], v[218:221], v[178:181], v[50:53]
	v_mfma_f32_16x16x32_bf16 v[42:45], v[210:213], v[186:189], v[42:45]
	v_mfma_f32_16x16x32_bf16 v[34:37], v[218:221], v[186:189], v[34:37]
	v_mfma_f32_16x16x32_bf16 v[26:29], v[210:213], v[194:197], v[26:29]
	v_mfma_f32_16x16x32_bf16 v[18:21], v[218:221], v[194:197], v[18:21]
	v_mfma_f32_16x16x32_bf16 v[10:13], v[210:213], v[202:205], v[10:13]
	v_mfma_f32_16x16x32_bf16 v[2:5], v[218:221], v[202:205], v[2:5]
	s_add_u32 s12, s12, 0x100
	s_addc_u32 s13, s13, 0
	s_add_u32 s41, s41, 0x100
	s_addc_u32 s42, s42, 0
	s_cmp_ge_i32 s43, s26
	s_mov_b32 s14, s43
	s_barrier
	s_cbranch_scc0 .LBB0_874
	s_branch .LBB0_869
